# GEMM K-loops: removed the mid-phase s_setprio 0 / s_setprio 1 pairs between the two 16-MFMA groups (priority stays raised across the 32-MFMA run)
# speedup vs baseline: 1.0303x; 1.0303x over previous
; #define PG8_STAGE(bufoff, gbase, voff) do { _Pragma("unroll") for (int _i = 0; _i < 2; ++_i) \
;         __builtin_amdgcn_global_load_lds((const unsigned*)((const char*)(gbase) + (voff)[_i]), (LAS unsigned*)(lds + (bufoff) + ldsw + _i * 8192), 16, 0, 0); } while (0)
; #define PG8_LDA(dst, b, h) do { _Pragma("unroll") for (int m = 0; m < 4; ++m) _Pragma("unroll") for (int k = 0; k < 2; ++k) dst[m][k] = *(const LAS bf16x8*)(lds + PG8_SA(b, h) + aoff + m * 2048 + k * 1024); } while (0)
; #define PG8_LDB(dst, b, h) do { _Pragma("unroll") for (int n = 0; n < 2; ++n) _Pragma("unroll") for (int k = 0; k < 2; ++k) dst[n][k] = *(const LAS bf16x8*)(lds + PG8_SB(b, h) + boff + n * 2048 + k * 1024); } while (0)
; #define PG8_MMA(ai, bj, At, Bt) do { __builtin_amdgcn_s_setprio(1); _Pragma("unroll") for (int m = 0; m < 4; ++m) _Pragma("unroll") for (int n = 0; n < 2; ++n) _Pragma("unroll") for (int k = 0; k < 2; ++k) \
;         acc[ai][bj][m][n] = __builtin_amdgcn_mfma_f32_16x16x32_bf16(Bt[n][k], At[m][k], acc[ai][bj][m][n], 0, 0, 0); __builtin_amdgcn_s_setprio(0); } while (0)
; #define PG8_WAIT_V(n) asm volatile("s_waitcnt vmcnt(" #n ")" ::: "memory")
; #define PG8_WAIT_L(n) asm volatile("s_waitcnt lgkmcnt(" #n ")" ::: "memory")
; #define PG8_BAR __builtin_amdgcn_s_barrier()
; #define PG8_SCHED __builtin_amdgcn_sched_barrier(0)
; template <class Epi, bool ALIGN_EPI, bool ASLOT = false>
; __device__ __forceinline__ void gemm_phase(LAS unsigned char* lds, const Gemm g, const Sched& S, const Epi& E) {
;     ...
;         for (int t = 0; t < nt; t += 2) {
;             const bool last = (t == nt - 2);
;             const char* a1 = cA + (size_t)(t + 1) * kstep;
;             const char* a2 = last ? nA : cA + (size_t)(t + 2) * kstep; const char* b2 = last ? nB : cB + (size_t)(t + 2) * kstep;
;             const char* a3 = a2 + kstep; const char* b3 = b2 + kstep;
;             PG8_LDB(B0, 0, 0); PG8_LDB(B1, 0, 1); PG8_SCHED; PG8_LDA(At, 0, 0); PG8_STAGE(PG8_SA(1, 1), a1 + hstep, voffA);
;             PG8_WAIT_V(8); PG8_WAIT_L(0); PG8_BAR; PG8_MMA(0, 0, At, B0); PG8_MMA(0, 1, At, B1); PG8_BAR; PG8_SCHED;
;             PG8_LDA(At, 0, 1); PG8_STAGE(PG8_SB(0, 0), b2, voffB); PG8_STAGE(PG8_SB(0, 1), b2 + hstep, voffB); PG8_STAGE(PG8_SA(0, 0), a2, voffA);
;             PG8_WAIT_V(8); PG8_WAIT_L(0); PG8_BAR; PG8_MMA(1, 0, At, B0); PG8_MMA(1, 1, At, B1); PG8_BAR; PG8_SCHED;
.LBB0_122:
	s_add_u32 s18, s14, 0xfffc0080
	s_addc_u32 s19, s15, -1
	s_add_i32 s28, 0, 0x10000
	s_cmp_eq_u32 s48, 12
	s_cselect_b32 s21, s7, s19
	s_cselect_b32 s20, s24, s18
	v_add_u32_e32 v156, s28, v158
	s_cselect_b32 s19, s9, s47
	s_cselect_b32 s18, s25, s46
	s_add_i32 s33, 0, 0x14000
	ds_read_b128 v[162:165], v156
	ds_read_b128 v[166:169], v156 offset:1024
	ds_read_b128 v[170:173], v156 offset:2048
	ds_read_b128 v[174:177], v156 offset:3072
	v_add_u32_e32 v156, s33, v158
	ds_read_b128 v[178:181], v156
	ds_read_b128 v[182:185], v156 offset:1024
	ds_read_b128 v[186:189], v156 offset:2048
	ds_read_b128 v[190:193], v156 offset:3072
	v_lshl_add_u64 v[156:157], s[14:15], 0, v[152:153]
	s_add_i32 m0, s40, 0xc000
	ds_read_b128 v[194:197], v160
	ds_read_b128 v[198:201], v160 offset:1024
	ds_read_b128 v[202:205], v160 offset:2048
	ds_read_b128 v[206:209], v160 offset:3072
	ds_read_b128 v[210:213], v160 offset:4096
	ds_read_b128 v[236:239], v160 offset:5120
	ds_read_b128 v[240:243], v160 offset:6144
	ds_read_b128 v[244:247], v160 offset:7168
	global_load_lds_dwordx4 v[156:157], off
	v_lshl_add_u64 v[156:157], s[14:15], 0, v[154:155]
	s_add_i32 m0, s40, 0xe000
	s_nop 0
	global_load_lds_dwordx4 v[156:157], off
	s_waitcnt vmcnt(8)
	s_waitcnt lgkmcnt(0)
	s_barrier
	s_setprio 1
	s_waitcnt lgkmcnt(0)
	v_mfma_f32_16x16x32_bf16 v[126:129], v[162:165], v[194:197], v[126:129]
	v_mfma_f32_16x16x32_bf16 v[122:125], v[170:173], v[194:197], v[122:125]
	v_mfma_f32_16x16x32_bf16 v[110:113], v[162:165], v[202:205], v[110:113]
	v_mfma_f32_16x16x32_bf16 v[106:109], v[170:173], v[202:205], v[106:109]
	v_mfma_f32_16x16x32_bf16 v[94:97], v[162:165], v[210:213], v[94:97]
	v_mfma_f32_16x16x32_bf16 v[90:93], v[170:173], v[210:213], v[90:93]
	v_mfma_f32_16x16x32_bf16 v[78:81], v[162:165], v[240:243], v[78:81]
	v_mfma_f32_16x16x32_bf16 v[74:77], v[170:173], v[240:243], v[74:77]
	v_mfma_f32_16x16x32_bf16 v[126:129], v[166:169], v[198:201], v[126:129]
	v_mfma_f32_16x16x32_bf16 v[122:125], v[174:177], v[198:201], v[122:125]
	v_mfma_f32_16x16x32_bf16 v[110:113], v[166:169], v[206:209], v[110:113]
	v_mfma_f32_16x16x32_bf16 v[106:109], v[174:177], v[206:209], v[106:109]
	v_mfma_f32_16x16x32_bf16 v[94:97], v[166:169], v[236:239], v[94:97]
	v_mfma_f32_16x16x32_bf16 v[90:93], v[174:177], v[236:239], v[90:93]
	v_mfma_f32_16x16x32_bf16 v[78:81], v[166:169], v[244:247], v[78:81]
	v_mfma_f32_16x16x32_bf16 v[74:77], v[174:177], v[244:247], v[74:77]
	v_mfma_f32_16x16x32_bf16 v[118:121], v[178:181], v[194:197], v[118:121]
	v_mfma_f32_16x16x32_bf16 v[114:117], v[186:189], v[194:197], v[114:117]
	v_mfma_f32_16x16x32_bf16 v[102:105], v[178:181], v[202:205], v[102:105]
	v_mfma_f32_16x16x32_bf16 v[98:101], v[186:189], v[202:205], v[98:101]
	v_mfma_f32_16x16x32_bf16 v[86:89], v[178:181], v[210:213], v[86:89]
	v_mfma_f32_16x16x32_bf16 v[82:85], v[186:189], v[210:213], v[82:85]
	v_mfma_f32_16x16x32_bf16 v[70:73], v[178:181], v[240:243], v[70:73]
	v_mfma_f32_16x16x32_bf16 v[66:69], v[186:189], v[240:243], v[66:69]
	v_mfma_f32_16x16x32_bf16 v[118:121], v[182:185], v[198:201], v[118:121]
	v_mfma_f32_16x16x32_bf16 v[114:117], v[190:193], v[198:201], v[114:117]
	v_mfma_f32_16x16x32_bf16 v[102:105], v[182:185], v[206:209], v[102:105]
	v_mfma_f32_16x16x32_bf16 v[98:101], v[190:193], v[206:209], v[98:101]
	v_mfma_f32_16x16x32_bf16 v[86:89], v[182:185], v[236:239], v[86:89]
	v_mfma_f32_16x16x32_bf16 v[82:85], v[190:193], v[236:239], v[82:85]
	v_mfma_f32_16x16x32_bf16 v[70:73], v[182:185], v[244:247], v[70:73]
	v_mfma_f32_16x16x32_bf16 v[66:69], v[190:193], v[244:247], v[66:69]
	s_setprio 0
	s_barrier
	s_add_i32 s22, s28, s39
	v_lshl_add_u64 v[156:157], s[18:19], 0, v[0:1]
	s_mov_b32 m0, s22
	ds_read_b128 v[194:197], v160 offset:16384
	ds_read_b128 v[198:201], v160 offset:17408
	ds_read_b128 v[202:205], v160 offset:18432
	ds_read_b128 v[206:209], v160 offset:19456
	ds_read_b128 v[210:213], v160 offset:20480
	ds_read_b128 v[236:239], v160 offset:21504
	ds_read_b128 v[240:243], v160 offset:22528
	ds_read_b128 v[244:247], v160 offset:23552
	global_load_lds_dwordx4 v[156:157], off
	s_add_i32 m0, s22, 0x2000
	s_add_u32 s22, s18, 0x40000
	v_lshl_add_u64 v[214:215], s[18:19], 0, v[134:135]
	s_addc_u32 s23, s19, 0
	s_add_i32 s26, s33, s39
	global_load_lds_dwordx4 v[214:215], off
	v_lshl_add_u64 v[220:221], s[22:23], 0, v[0:1]
	s_mov_b32 m0, s26
	v_lshl_add_u64 v[222:223], s[20:21], 0, v[132:133]
	global_load_lds_dwordx4 v[220:221], off
	v_lshl_add_u64 v[220:221], s[22:23], 0, v[134:135]
	s_add_i32 m0, s26, 0x2000
	s_nop 0
	global_load_lds_dwordx4 v[220:221], off
	v_lshl_add_u64 v[220:221], s[20:21], 0, v[130:131]
	s_mov_b32 m0, s40
	s_nop 0
	global_load_lds_dwordx4 v[220:221], off
	s_mov_b32 m0, s41
	s_nop 0
	global_load_lds_dwordx4 v[222:223], off
	s_waitcnt vmcnt(8)
	s_waitcnt lgkmcnt(0)
	s_barrier
; #define PG8_STAGE(bufoff, gbase, voff) do { _Pragma("unroll") for (int _i = 0; _i < 2; ++_i) \
;         __builtin_amdgcn_global_load_lds((const unsigned*)((const char*)(gbase) + (voff)[_i]), (LAS unsigned*)(lds + (bufoff) + ldsw + _i * 8192), 16, 0, 0); } while (0)
; #define PG8_LDA(dst, b, h) do { _Pragma("unroll") for (int m = 0; m < 4; ++m) _Pragma("unroll") for (int k = 0; k < 2; ++k) dst[m][k] = *(const LAS bf16x8*)(lds + PG8_SA(b, h) + aoff + m * 2048 + k * 1024); } while (0)
; #define PG8_LDB(dst, b, h) do { _Pragma("unroll") for (int n = 0; n < 2; ++n) _Pragma("unroll") for (int k = 0; k < 2; ++k) dst[n][k] = *(const LAS bf16x8*)(lds + PG8_SB(b, h) + boff + n * 2048 + k * 1024); } while (0)
; #define PG8_MMA(ai, bj, At, Bt) do { __builtin_amdgcn_s_setprio(1); _Pragma("unroll") for (int m = 0; m < 4; ++m) _Pragma("unroll") for (int n = 0; n < 2; ++n) _Pragma("unroll") for (int k = 0; k < 2; ++k) \
;         acc[ai][bj][m][n] = __builtin_amdgcn_mfma_f32_16x16x32_bf16(Bt[n][k], At[m][k], acc[ai][bj][m][n], 0, 0, 0); __builtin_amdgcn_s_setprio(0); } while (0)
; #define PG8_WAIT_V(n) asm volatile("s_waitcnt vmcnt(" #n ")" ::: "memory")
; #define PG8_WAIT_L(n) asm volatile("s_waitcnt lgkmcnt(" #n ")" ::: "memory")
; #define PG8_BAR __builtin_amdgcn_s_barrier()
; #define PG8_SCHED __builtin_amdgcn_sched_barrier(0)
; template <class Epi, bool ALIGN_EPI, bool ASLOT = false>
; __device__ __forceinline__ void gemm_phase(LAS unsigned char* lds, const Gemm g, const Sched& S, const Epi& E) {
;     ...
;             PG8_WAIT_V(8); PG8_WAIT_L(0); PG8_BAR; PG8_MMA(1, 0, At, B0); PG8_MMA(1, 1, At, B1); PG8_BAR; PG8_SCHED;
;             PG8_LDB(B0, 1, 0); PG8_LDB(B1, 1, 1); PG8_SCHED; PG8_LDA(At, 1, 0); PG8_STAGE(PG8_SA(0, 1), a2 + hstep, voffA);
;             PG8_WAIT_V(8); PG8_WAIT_L(0); PG8_BAR; PG8_MMA(0, 0, At, B0); PG8_MMA(0, 1, At, B1); PG8_BAR; PG8_SCHED;
	s_setprio 1
	s_waitcnt lgkmcnt(0)
	v_mfma_f32_16x16x32_bf16 v[62:65], v[162:165], v[194:197], v[62:65]
	v_mfma_f32_16x16x32_bf16 v[58:61], v[170:173], v[194:197], v[58:61]
	v_mfma_f32_16x16x32_bf16 v[46:49], v[162:165], v[202:205], v[46:49]
	v_mfma_f32_16x16x32_bf16 v[42:45], v[170:173], v[202:205], v[42:45]
	v_mfma_f32_16x16x32_bf16 v[30:33], v[162:165], v[210:213], v[30:33]
	v_mfma_f32_16x16x32_bf16 v[26:29], v[170:173], v[210:213], v[26:29]
	v_mfma_f32_16x16x32_bf16 v[14:17], v[162:165], v[240:243], v[14:17]
	v_mfma_f32_16x16x32_bf16 v[10:13], v[170:173], v[240:243], v[10:13]
	v_mfma_f32_16x16x32_bf16 v[62:65], v[166:169], v[198:201], v[62:65]
	v_mfma_f32_16x16x32_bf16 v[58:61], v[174:177], v[198:201], v[58:61]
	v_mfma_f32_16x16x32_bf16 v[46:49], v[166:169], v[206:209], v[46:49]
	v_mfma_f32_16x16x32_bf16 v[42:45], v[174:177], v[206:209], v[42:45]
	v_mfma_f32_16x16x32_bf16 v[30:33], v[166:169], v[236:239], v[30:33]
	v_mfma_f32_16x16x32_bf16 v[26:29], v[174:177], v[236:239], v[26:29]
	v_mfma_f32_16x16x32_bf16 v[14:17], v[166:169], v[244:247], v[14:17]
	v_mfma_f32_16x16x32_bf16 v[10:13], v[174:177], v[244:247], v[10:13]
	v_mfma_f32_16x16x32_bf16 v[54:57], v[178:181], v[194:197], v[54:57]
	v_mfma_f32_16x16x32_bf16 v[50:53], v[186:189], v[194:197], v[50:53]
	v_mfma_f32_16x16x32_bf16 v[38:41], v[178:181], v[202:205], v[38:41]
	v_mfma_f32_16x16x32_bf16 v[34:37], v[186:189], v[202:205], v[34:37]
	v_mfma_f32_16x16x32_bf16 v[22:25], v[178:181], v[210:213], v[22:25]
	v_mfma_f32_16x16x32_bf16 v[18:21], v[186:189], v[210:213], v[18:21]
	v_mfma_f32_16x16x32_bf16 v[6:9], v[178:181], v[240:243], v[6:9]
	v_mfma_f32_16x16x32_bf16 v[2:5], v[186:189], v[240:243], v[2:5]
	v_mfma_f32_16x16x32_bf16 v[54:57], v[182:185], v[198:201], v[54:57]
	v_mfma_f32_16x16x32_bf16 v[50:53], v[190:193], v[198:201], v[50:53]
	v_mfma_f32_16x16x32_bf16 v[38:41], v[182:185], v[206:209], v[38:41]
	v_mfma_f32_16x16x32_bf16 v[34:37], v[190:193], v[206:209], v[34:37]
	v_mfma_f32_16x16x32_bf16 v[22:25], v[182:185], v[236:239], v[22:25]
	v_mfma_f32_16x16x32_bf16 v[18:21], v[190:193], v[236:239], v[18:21]
	v_mfma_f32_16x16x32_bf16 v[6:9], v[182:185], v[244:247], v[6:9]
	v_mfma_f32_16x16x32_bf16 v[2:5], v[190:193], v[244:247], v[2:5]
	s_setprio 0
	s_barrier
	s_add_i32 s29, 0, 0x18000
	v_add_u32_e32 v161, s29, v158
	s_add_i32 s26, 0, 0x1c000
	ds_read_b128 v[162:165], v161
	ds_read_b128 v[166:169], v161 offset:1024
	ds_read_b128 v[170:173], v161 offset:2048
	ds_read_b128 v[174:177], v161 offset:3072
	v_add_u32_e32 v161, s26, v158
	ds_read_b128 v[178:181], v161
	ds_read_b128 v[182:185], v161 offset:1024
	ds_read_b128 v[186:189], v161 offset:2048
	ds_read_b128 v[190:193], v161 offset:3072
	s_add_u32 s20, s20, 0x40000
	s_addc_u32 s21, s21, 0
	s_mov_b32 m0, s42
	v_lshl_add_u64 v[232:233], s[20:21], 0, v[130:131]
	ds_read_b128 v[194:197], v160 offset:32768
	ds_read_b128 v[198:201], v160 offset:33792
	ds_read_b128 v[202:205], v160 offset:34816
	ds_read_b128 v[206:209], v160 offset:35840
	ds_read_b128 v[210:213], v160 offset:36864
	ds_read_b128 v[236:239], v160 offset:37888
	ds_read_b128 v[240:243], v160 offset:38912
	ds_read_b128 v[244:247], v160 offset:39936
	global_load_lds_dwordx4 v[232:233], off
	v_lshl_add_u64 v[232:233], s[20:21], 0, v[132:133]
	s_mov_b32 m0, s43
	s_nop 0
	global_load_lds_dwordx4 v[232:233], off
	s_waitcnt vmcnt(8)
	s_waitcnt lgkmcnt(0)
	s_barrier
	s_setprio 1
	s_waitcnt lgkmcnt(0)
	v_mfma_f32_16x16x32_bf16 v[126:129], v[162:165], v[194:197], v[126:129]
	v_mfma_f32_16x16x32_bf16 v[122:125], v[170:173], v[194:197], v[122:125]
	v_mfma_f32_16x16x32_bf16 v[110:113], v[162:165], v[202:205], v[110:113]
	v_mfma_f32_16x16x32_bf16 v[106:109], v[170:173], v[202:205], v[106:109]
	v_mfma_f32_16x16x32_bf16 v[94:97], v[162:165], v[210:213], v[94:97]
	v_mfma_f32_16x16x32_bf16 v[90:93], v[170:173], v[210:213], v[90:93]
	v_mfma_f32_16x16x32_bf16 v[78:81], v[162:165], v[240:243], v[78:81]
	v_mfma_f32_16x16x32_bf16 v[74:77], v[170:173], v[240:243], v[74:77]
	v_mfma_f32_16x16x32_bf16 v[126:129], v[166:169], v[198:201], v[126:129]
	v_mfma_f32_16x16x32_bf16 v[122:125], v[174:177], v[198:201], v[122:125]
	v_mfma_f32_16x16x32_bf16 v[110:113], v[166:169], v[206:209], v[110:113]
	v_mfma_f32_16x16x32_bf16 v[106:109], v[174:177], v[206:209], v[106:109]
	v_mfma_f32_16x16x32_bf16 v[94:97], v[166:169], v[236:239], v[94:97]
	v_mfma_f32_16x16x32_bf16 v[90:93], v[174:177], v[236:239], v[90:93]
	v_mfma_f32_16x16x32_bf16 v[78:81], v[166:169], v[244:247], v[78:81]
	v_mfma_f32_16x16x32_bf16 v[74:77], v[174:177], v[244:247], v[74:77]
	v_mfma_f32_16x16x32_bf16 v[118:121], v[178:181], v[194:197], v[118:121]
	v_mfma_f32_16x16x32_bf16 v[114:117], v[186:189], v[194:197], v[114:117]
	v_mfma_f32_16x16x32_bf16 v[102:105], v[178:181], v[202:205], v[102:105]
	v_mfma_f32_16x16x32_bf16 v[98:101], v[186:189], v[202:205], v[98:101]
	v_mfma_f32_16x16x32_bf16 v[86:89], v[178:181], v[210:213], v[86:89]
	v_mfma_f32_16x16x32_bf16 v[82:85], v[186:189], v[210:213], v[82:85]
	v_mfma_f32_16x16x32_bf16 v[70:73], v[178:181], v[240:243], v[70:73]
	v_mfma_f32_16x16x32_bf16 v[66:69], v[186:189], v[240:243], v[66:69]
	v_mfma_f32_16x16x32_bf16 v[118:121], v[182:185], v[198:201], v[118:121]
	v_mfma_f32_16x16x32_bf16 v[114:117], v[190:193], v[198:201], v[114:117]
	v_mfma_f32_16x16x32_bf16 v[102:105], v[182:185], v[206:209], v[102:105]
	v_mfma_f32_16x16x32_bf16 v[98:101], v[190:193], v[206:209], v[98:101]
	v_mfma_f32_16x16x32_bf16 v[86:89], v[182:185], v[236:239], v[86:89]
	v_mfma_f32_16x16x32_bf16 v[82:85], v[190:193], v[236:239], v[82:85]
	v_mfma_f32_16x16x32_bf16 v[70:73], v[182:185], v[244:247], v[70:73]
	v_mfma_f32_16x16x32_bf16 v[66:69], v[190:193], v[244:247], v[66:69]
	s_setprio 0
	s_barrier
; #define PG8_STAGE(bufoff, gbase, voff) do { _Pragma("unroll") for (int _i = 0; _i < 2; ++_i) \
;         __builtin_amdgcn_global_load_lds((const unsigned*)((const char*)(gbase) + (voff)[_i]), (LAS unsigned*)(lds + (bufoff) + ldsw + _i * 8192), 16, 0, 0); } while (0)
; #define PG8_LDA(dst, b, h) do { _Pragma("unroll") for (int m = 0; m < 4; ++m) _Pragma("unroll") for (int k = 0; k < 2; ++k) dst[m][k] = *(const LAS bf16x8*)(lds + PG8_SA(b, h) + aoff + m * 2048 + k * 1024); } while (0)
; #define PG8_MMA(ai, bj, At, Bt) do { __builtin_amdgcn_s_setprio(1); _Pragma("unroll") for (int m = 0; m < 4; ++m) _Pragma("unroll") for (int n = 0; n < 2; ++n) _Pragma("unroll") for (int k = 0; k < 2; ++k) \
;         acc[ai][bj][m][n] = __builtin_amdgcn_mfma_f32_16x16x32_bf16(Bt[n][k], At[m][k], acc[ai][bj][m][n], 0, 0, 0); __builtin_amdgcn_s_setprio(0); } while (0)
; #define PG8_WAIT_V(n) asm volatile("s_waitcnt vmcnt(" #n ")" ::: "memory")
; #define PG8_WAIT_L(n) asm volatile("s_waitcnt lgkmcnt(" #n ")" ::: "memory")
; #define PG8_BAR __builtin_amdgcn_s_barrier()
; #define PG8_SCHED __builtin_amdgcn_sched_barrier(0)
; template <class Epi, bool ALIGN_EPI, bool ASLOT = false>
; __device__ __forceinline__ void gemm_phase(LAS unsigned char* lds, const Gemm g, const Sched& S, const Epi& E) {
;     ...
;             PG8_LDA(At, 1, 1); PG8_STAGE(PG8_SB(1, 0), b3, voffB); PG8_STAGE(PG8_SB(1, 1), b3 + hstep, voffB); PG8_STAGE(PG8_SA(1, 0), a3, voffA);
;             PG8_WAIT_V(8); PG8_WAIT_L(0); PG8_BAR; PG8_MMA(1, 0, At, B0); PG8_MMA(1, 1, At, B1); PG8_BAR; PG8_SCHED;
;         }
	s_add_i32 s20, s29, s39
	v_lshl_add_u64 v[156:157], v[156:157], 0, s[16:17]
	s_mov_b32 m0, s20
	ds_read_b128 v[194:197], v160 offset:49152
	ds_read_b128 v[198:201], v160 offset:50176
	ds_read_b128 v[202:205], v160 offset:51200
	ds_read_b128 v[206:209], v160 offset:52224
	ds_read_b128 v[210:213], v160 offset:53248
	ds_read_b128 v[236:239], v160 offset:54272
	ds_read_b128 v[240:243], v160 offset:55296
	ds_read_b128 v[244:247], v160 offset:56320
	global_load_lds_dwordx4 v[156:157], off
	s_add_i32 m0, s20, 0x2000
	s_add_u32 s18, s18, 0x40080
	v_lshl_add_u64 v[156:157], v[214:215], 0, s[16:17]
	s_addc_u32 s19, s19, 0
	s_add_i32 s20, s26, s39
	global_load_lds_dwordx4 v[156:157], off
	v_lshl_add_u64 v[156:157], s[18:19], 0, v[0:1]
	s_mov_b32 m0, s20
	s_nop 0
	global_load_lds_dwordx4 v[156:157], off
	v_lshl_add_u64 v[156:157], s[18:19], 0, v[134:135]
	s_add_i32 m0, s20, 0x2000
	s_nop 0
	global_load_lds_dwordx4 v[156:157], off
	v_lshl_add_u64 v[156:157], v[220:221], 0, s[16:17]
	s_mov_b32 m0, s44
	s_nop 0
	global_load_lds_dwordx4 v[156:157], off
	v_lshl_add_u64 v[156:157], v[222:223], 0, s[16:17]
	s_mov_b32 m0, s45
	s_nop 0
	global_load_lds_dwordx4 v[156:157], off
	s_waitcnt vmcnt(8)
	s_waitcnt lgkmcnt(0)
	s_barrier
	s_setprio 1
	s_waitcnt lgkmcnt(0)
	v_mfma_f32_16x16x32_bf16 v[62:65], v[162:165], v[194:197], v[62:65]
	v_mfma_f32_16x16x32_bf16 v[58:61], v[170:173], v[194:197], v[58:61]
	v_mfma_f32_16x16x32_bf16 v[46:49], v[162:165], v[202:205], v[46:49]
	v_mfma_f32_16x16x32_bf16 v[42:45], v[170:173], v[202:205], v[42:45]
	v_mfma_f32_16x16x32_bf16 v[30:33], v[162:165], v[210:213], v[30:33]
	v_mfma_f32_16x16x32_bf16 v[26:29], v[170:173], v[210:213], v[26:29]
	v_mfma_f32_16x16x32_bf16 v[14:17], v[162:165], v[240:243], v[14:17]
	v_mfma_f32_16x16x32_bf16 v[10:13], v[170:173], v[240:243], v[10:13]
	v_mfma_f32_16x16x32_bf16 v[62:65], v[166:169], v[198:201], v[62:65]
	v_mfma_f32_16x16x32_bf16 v[58:61], v[174:177], v[198:201], v[58:61]
	v_mfma_f32_16x16x32_bf16 v[46:49], v[166:169], v[206:209], v[46:49]
	v_mfma_f32_16x16x32_bf16 v[42:45], v[174:177], v[206:209], v[42:45]
	v_mfma_f32_16x16x32_bf16 v[30:33], v[166:169], v[236:239], v[30:33]
	v_mfma_f32_16x16x32_bf16 v[26:29], v[174:177], v[236:239], v[26:29]
	v_mfma_f32_16x16x32_bf16 v[14:17], v[166:169], v[244:247], v[14:17]
	v_mfma_f32_16x16x32_bf16 v[10:13], v[174:177], v[244:247], v[10:13]
	v_mfma_f32_16x16x32_bf16 v[54:57], v[178:181], v[194:197], v[54:57]
	v_mfma_f32_16x16x32_bf16 v[50:53], v[186:189], v[194:197], v[50:53]
	v_mfma_f32_16x16x32_bf16 v[38:41], v[178:181], v[202:205], v[38:41]
	v_mfma_f32_16x16x32_bf16 v[34:37], v[186:189], v[202:205], v[34:37]
	v_mfma_f32_16x16x32_bf16 v[22:25], v[178:181], v[210:213], v[22:25]
	v_mfma_f32_16x16x32_bf16 v[18:21], v[186:189], v[210:213], v[18:21]
	v_mfma_f32_16x16x32_bf16 v[6:9], v[178:181], v[240:243], v[6:9]
	v_mfma_f32_16x16x32_bf16 v[2:5], v[186:189], v[240:243], v[2:5]
	v_mfma_f32_16x16x32_bf16 v[54:57], v[182:185], v[198:201], v[54:57]
	v_mfma_f32_16x16x32_bf16 v[50:53], v[190:193], v[198:201], v[50:53]
	v_mfma_f32_16x16x32_bf16 v[38:41], v[182:185], v[206:209], v[38:41]
	v_mfma_f32_16x16x32_bf16 v[34:37], v[190:193], v[206:209], v[34:37]
	v_mfma_f32_16x16x32_bf16 v[22:25], v[182:185], v[236:239], v[22:25]
	v_mfma_f32_16x16x32_bf16 v[18:21], v[190:193], v[236:239], v[18:21]
	v_mfma_f32_16x16x32_bf16 v[6:9], v[182:185], v[244:247], v[6:9]
	v_mfma_f32_16x16x32_bf16 v[2:5], v[190:193], v[244:247], v[2:5]
	s_setprio 0
	s_barrier
	s_add_i32 s48, s48, 2
	s_add_u32 s14, s14, 0x100
	s_addc_u32 s15, s15, 0
	s_add_u32 s46, s46, 0x100
	s_addc_u32 s47, s47, 0
	s_cmp_gt_u32 s48, 13
	s_cbranch_scc0 .LBB0_122
	s_and_b64 vcc, exec, s[4:5]
	s_cbranch_vccz .LBB0_125
	s_barrier

; #define PG8_STAGE(bufoff, gbase, voff) do { _Pragma("unroll") for (int _i = 0; _i < 2; ++_i) \
;         __builtin_amdgcn_global_load_lds((const unsigned*)((const char*)(gbase) + (voff)[_i]), (LAS unsigned*)(lds + (bufoff) + ldsw + _i * 8192), 16, 0, 0); } while (0)
; #define PG8_LDA(dst, b, h) do { _Pragma("unroll") for (int m = 0; m < 4; ++m) _Pragma("unroll") for (int k = 0; k < 2; ++k) dst[m][k] = *(const LAS bf16x8*)(lds + PG8_SA(b, h) + aoff + m * 2048 + k * 1024); } while (0)
; #define PG8_LDB(dst, b, h) do { _Pragma("unroll") for (int n = 0; n < 2; ++n) _Pragma("unroll") for (int k = 0; k < 2; ++k) dst[n][k] = *(const LAS bf16x8*)(lds + PG8_SB(b, h) + boff + n * 2048 + k * 1024); } while (0)
; #define PG8_MMA(ai, bj, At, Bt) do { __builtin_amdgcn_s_setprio(1); _Pragma("unroll") for (int m = 0; m < 4; ++m) _Pragma("unroll") for (int n = 0; n < 2; ++n) _Pragma("unroll") for (int k = 0; k < 2; ++k) \
;         acc[ai][bj][m][n] = __builtin_amdgcn_mfma_f32_16x16x32_bf16(Bt[n][k], At[m][k], acc[ai][bj][m][n], 0, 0, 0); __builtin_amdgcn_s_setprio(0); } while (0)
; #define PG8_WAIT_V(n) asm volatile("s_waitcnt vmcnt(" #n ")" ::: "memory")
; #define PG8_WAIT_L(n) asm volatile("s_waitcnt lgkmcnt(" #n ")" ::: "memory")
; #define PG8_BAR __builtin_amdgcn_s_barrier()
; #define PG8_SCHED __builtin_amdgcn_sched_barrier(0)
; template <class Epi, bool ALIGN_EPI, bool ASLOT = false>
; __device__ __forceinline__ void gemm_phase(LAS unsigned char* lds, const Gemm g, const Sched& S, const Epi& E) {
;     ...
;         for (int t = 0; t < nt; t += 2) {
;             const bool last = (t == nt - 2);
;             const char* a1 = cA + (size_t)(t + 1) * kstep;
;             const char* a2 = last ? nA : cA + (size_t)(t + 2) * kstep; const char* b2 = last ? nB : cB + (size_t)(t + 2) * kstep;
;             const char* a3 = a2 + kstep; const char* b3 = b2 + kstep;
;             PG8_LDB(B0, 0, 0); PG8_LDB(B1, 0, 1); PG8_SCHED; PG8_LDA(At, 0, 0); PG8_STAGE(PG8_SA(1, 1), a1 + hstep, voffA);
;             PG8_WAIT_V(8); PG8_WAIT_L(0); PG8_BAR; PG8_MMA(0, 0, At, B0); PG8_MMA(0, 1, At, B1); PG8_BAR; PG8_SCHED;
;             PG8_LDA(At, 0, 1); PG8_STAGE(PG8_SB(0, 0), b2, voffB); PG8_STAGE(PG8_SB(0, 1), b2 + hstep, voffB); PG8_STAGE(PG8_SA(0, 0), a2, voffA);
;             PG8_WAIT_V(8); PG8_WAIT_L(0); PG8_BAR; PG8_MMA(1, 0, At, B0); PG8_MMA(1, 1, At, B1); PG8_BAR; PG8_SCHED;
.LBB0_140:
	v_add_u32_e32 v156, s28, v141
	v_add_u32_e32 v172, s33, v141
	ds_read_b128 v[144:147], v156
	ds_read_b128 v[148:151], v156 offset:1024
	ds_read_b128 v[152:155], v156 offset:2048
	ds_read_b128 v[156:159], v156 offset:3072
	ds_read_b128 v[160:163], v172
	ds_read_b128 v[164:167], v172 offset:1024
	ds_read_b128 v[168:171], v172 offset:2048
	ds_read_b128 v[172:175], v172 offset:3072
	s_add_u32 s18, s44, 0xfffc0080
	s_addc_u32 s19, s45, -1
	s_cmp_eq_u32 s50, 12
	s_cselect_b32 s21, s11, s19
	s_cselect_b32 s20, s13, s18
	s_cselect_b32 s19, s39, s49
	s_cselect_b32 s18, s38, s15
	v_lshl_add_u64 v[208:209], s[44:45], 0, v[136:137]
	s_add_i32 m0, s3, 0xc000
	ds_read_b128 v[176:179], v143
	ds_read_b128 v[180:183], v143 offset:1024
	ds_read_b128 v[184:187], v143 offset:2048
	ds_read_b128 v[188:191], v143 offset:3072
	ds_read_b128 v[192:195], v143 offset:4096
	ds_read_b128 v[196:199], v143 offset:5120
	ds_read_b128 v[200:203], v143 offset:6144
	ds_read_b128 v[204:207], v143 offset:7168
	global_load_lds_dwordx4 v[208:209], off
	v_lshl_add_u64 v[208:209], s[44:45], 0, v[138:139]
	s_add_i32 m0, s3, 0xe000
	s_nop 0
	global_load_lds_dwordx4 v[208:209], off
	s_waitcnt vmcnt(8)
	s_waitcnt lgkmcnt(0)
	s_barrier
	s_setprio 1
	s_waitcnt lgkmcnt(0)
	v_mfma_f32_16x16x32_bf16 v[126:129], v[144:147], v[176:179], v[126:129]
	v_mfma_f32_16x16x32_bf16 v[122:125], v[152:155], v[176:179], v[122:125]
	v_mfma_f32_16x16x32_bf16 v[118:121], v[144:147], v[184:187], v[118:121]
	v_mfma_f32_16x16x32_bf16 v[114:117], v[152:155], v[184:187], v[114:117]
	v_mfma_f32_16x16x32_bf16 v[102:105], v[144:147], v[192:195], v[102:105]
	v_mfma_f32_16x16x32_bf16 v[98:101], v[152:155], v[192:195], v[98:101]
	v_mfma_f32_16x16x32_bf16 v[86:89], v[144:147], v[200:203], v[86:89]
	v_mfma_f32_16x16x32_bf16 v[82:85], v[152:155], v[200:203], v[82:85]
	v_mfma_f32_16x16x32_bf16 v[126:129], v[148:151], v[180:183], v[126:129]
	v_mfma_f32_16x16x32_bf16 v[122:125], v[156:159], v[180:183], v[122:125]
	v_mfma_f32_16x16x32_bf16 v[118:121], v[148:151], v[188:191], v[118:121]
	v_mfma_f32_16x16x32_bf16 v[114:117], v[156:159], v[188:191], v[114:117]
	v_mfma_f32_16x16x32_bf16 v[102:105], v[148:151], v[196:199], v[102:105]
	v_mfma_f32_16x16x32_bf16 v[98:101], v[156:159], v[196:199], v[98:101]
	v_mfma_f32_16x16x32_bf16 v[86:89], v[148:151], v[204:207], v[86:89]
	v_mfma_f32_16x16x32_bf16 v[82:85], v[156:159], v[204:207], v[82:85]
	v_mfma_f32_16x16x32_bf16 v[110:113], v[160:163], v[176:179], v[110:113]
	v_mfma_f32_16x16x32_bf16 v[106:109], v[168:171], v[176:179], v[106:109]
	v_mfma_f32_16x16x32_bf16 v[94:97], v[160:163], v[184:187], v[94:97]
	v_mfma_f32_16x16x32_bf16 v[90:93], v[168:171], v[184:187], v[90:93]
	v_mfma_f32_16x16x32_bf16 v[78:81], v[160:163], v[192:195], v[78:81]
	v_mfma_f32_16x16x32_bf16 v[74:77], v[168:171], v[192:195], v[74:77]
	v_mfma_f32_16x16x32_bf16 v[70:73], v[160:163], v[200:203], v[70:73]
	v_mfma_f32_16x16x32_bf16 v[66:69], v[168:171], v[200:203], v[66:69]
	v_mfma_f32_16x16x32_bf16 v[110:113], v[164:167], v[180:183], v[110:113]
	v_mfma_f32_16x16x32_bf16 v[106:109], v[172:175], v[180:183], v[106:109]
	v_mfma_f32_16x16x32_bf16 v[94:97], v[164:167], v[188:191], v[94:97]
	v_mfma_f32_16x16x32_bf16 v[90:93], v[172:175], v[188:191], v[90:93]
	v_mfma_f32_16x16x32_bf16 v[78:81], v[164:167], v[196:199], v[78:81]
	v_mfma_f32_16x16x32_bf16 v[74:77], v[172:175], v[196:199], v[74:77]
	v_mfma_f32_16x16x32_bf16 v[70:73], v[164:167], v[204:207], v[70:73]
	v_mfma_f32_16x16x32_bf16 v[66:69], v[172:175], v[204:207], v[66:69]
	s_setprio 0
	s_barrier
	s_add_i32 s22, s28, s2
	v_lshl_add_u64 v[208:209], s[18:19], 0, v[0:1]
	s_mov_b32 m0, s22
	ds_read_b128 v[176:179], v143 offset:16384
	ds_read_b128 v[180:183], v143 offset:17408
	ds_read_b128 v[184:187], v143 offset:18432
	ds_read_b128 v[188:191], v143 offset:19456
	ds_read_b128 v[192:195], v143 offset:20480
	ds_read_b128 v[196:199], v143 offset:21504
	ds_read_b128 v[200:203], v143 offset:22528
	ds_read_b128 v[204:207], v143 offset:23552
	global_load_lds_dwordx4 v[208:209], off
	s_add_i32 m0, s22, 0x2000
	s_add_u32 s22, s18, 0x40000
	v_lshl_add_u64 v[210:211], s[18:19], 0, v[130:131]
	s_addc_u32 s23, s19, 0
	s_add_i32 s30, s33, s2
	global_load_lds_dwordx4 v[210:211], off
	v_lshl_add_u64 v[212:213], s[22:23], 0, v[0:1]
	s_mov_b32 m0, s30
	v_lshl_add_u64 v[214:215], s[20:21], 0, v[132:133]
	global_load_lds_dwordx4 v[212:213], off
	v_lshl_add_u64 v[212:213], s[22:23], 0, v[130:131]
	s_add_i32 m0, s30, 0x2000
	s_nop 0
	global_load_lds_dwordx4 v[212:213], off
	v_lshl_add_u64 v[212:213], s[20:21], 0, v[134:135]
	s_mov_b32 m0, s3
	s_nop 0
	global_load_lds_dwordx4 v[212:213], off
	s_mov_b32 m0, s24
	s_nop 0
	global_load_lds_dwordx4 v[214:215], off
	s_waitcnt vmcnt(8)
	s_waitcnt lgkmcnt(0)
	s_barrier
; #define PG8_STAGE(bufoff, gbase, voff) do { _Pragma("unroll") for (int _i = 0; _i < 2; ++_i) \
;         __builtin_amdgcn_global_load_lds((const unsigned*)((const char*)(gbase) + (voff)[_i]), (LAS unsigned*)(lds + (bufoff) + ldsw + _i * 8192), 16, 0, 0); } while (0)
; #define PG8_LDA(dst, b, h) do { _Pragma("unroll") for (int m = 0; m < 4; ++m) _Pragma("unroll") for (int k = 0; k < 2; ++k) dst[m][k] = *(const LAS bf16x8*)(lds + PG8_SA(b, h) + aoff + m * 2048 + k * 1024); } while (0)
; #define PG8_LDB(dst, b, h) do { _Pragma("unroll") for (int n = 0; n < 2; ++n) _Pragma("unroll") for (int k = 0; k < 2; ++k) dst[n][k] = *(const LAS bf16x8*)(lds + PG8_SB(b, h) + boff + n * 2048 + k * 1024); } while (0)
; #define PG8_MMA(ai, bj, At, Bt) do { __builtin_amdgcn_s_setprio(1); _Pragma("unroll") for (int m = 0; m < 4; ++m) _Pragma("unroll") for (int n = 0; n < 2; ++n) _Pragma("unroll") for (int k = 0; k < 2; ++k) \
;         acc[ai][bj][m][n] = __builtin_amdgcn_mfma_f32_16x16x32_bf16(Bt[n][k], At[m][k], acc[ai][bj][m][n], 0, 0, 0); __builtin_amdgcn_s_setprio(0); } while (0)
; #define PG8_WAIT_V(n) asm volatile("s_waitcnt vmcnt(" #n ")" ::: "memory")
; #define PG8_WAIT_L(n) asm volatile("s_waitcnt lgkmcnt(" #n ")" ::: "memory")
; #define PG8_BAR __builtin_amdgcn_s_barrier()
; #define PG8_SCHED __builtin_amdgcn_sched_barrier(0)
; template <class Epi, bool ALIGN_EPI, bool ASLOT = false>
; __device__ __forceinline__ void gemm_phase(LAS unsigned char* lds, const Gemm g, const Sched& S, const Epi& E) {
;     ...
;             PG8_WAIT_V(8); PG8_WAIT_L(0); PG8_BAR; PG8_MMA(1, 0, At, B0); PG8_MMA(1, 1, At, B1); PG8_BAR; PG8_SCHED;
;             PG8_LDB(B0, 1, 0); PG8_LDB(B1, 1, 1); PG8_SCHED; PG8_LDA(At, 1, 0); PG8_STAGE(PG8_SA(0, 1), a2 + hstep, voffA);
;             PG8_WAIT_V(8); PG8_WAIT_L(0); PG8_BAR; PG8_MMA(0, 0, At, B0); PG8_MMA(0, 1, At, B1); PG8_BAR; PG8_SCHED;
	s_setprio 1
	s_waitcnt lgkmcnt(0)
	v_mfma_f32_16x16x32_bf16 v[62:65], v[144:147], v[176:179], v[62:65]
	v_mfma_f32_16x16x32_bf16 v[58:61], v[152:155], v[176:179], v[58:61]
	v_mfma_f32_16x16x32_bf16 v[54:57], v[144:147], v[184:187], v[54:57]
	v_mfma_f32_16x16x32_bf16 v[50:53], v[152:155], v[184:187], v[50:53]
	v_mfma_f32_16x16x32_bf16 v[38:41], v[144:147], v[192:195], v[38:41]
	v_mfma_f32_16x16x32_bf16 v[34:37], v[152:155], v[192:195], v[34:37]
	v_mfma_f32_16x16x32_bf16 v[22:25], v[144:147], v[200:203], v[22:25]
	v_mfma_f32_16x16x32_bf16 v[18:21], v[152:155], v[200:203], v[18:21]
	v_mfma_f32_16x16x32_bf16 v[62:65], v[148:151], v[180:183], v[62:65]
	v_mfma_f32_16x16x32_bf16 v[58:61], v[156:159], v[180:183], v[58:61]
	v_mfma_f32_16x16x32_bf16 v[54:57], v[148:151], v[188:191], v[54:57]
	v_mfma_f32_16x16x32_bf16 v[50:53], v[156:159], v[188:191], v[50:53]
	v_mfma_f32_16x16x32_bf16 v[38:41], v[148:151], v[196:199], v[38:41]
	v_mfma_f32_16x16x32_bf16 v[34:37], v[156:159], v[196:199], v[34:37]
	v_mfma_f32_16x16x32_bf16 v[22:25], v[148:151], v[204:207], v[22:25]
	v_mfma_f32_16x16x32_bf16 v[18:21], v[156:159], v[204:207], v[18:21]
	v_mfma_f32_16x16x32_bf16 v[46:49], v[160:163], v[176:179], v[46:49]
	v_mfma_f32_16x16x32_bf16 v[42:45], v[168:171], v[176:179], v[42:45]
	v_mfma_f32_16x16x32_bf16 v[30:33], v[160:163], v[184:187], v[30:33]
	v_mfma_f32_16x16x32_bf16 v[26:29], v[168:171], v[184:187], v[26:29]
	v_mfma_f32_16x16x32_bf16 v[14:17], v[160:163], v[192:195], v[14:17]
	v_mfma_f32_16x16x32_bf16 v[10:13], v[168:171], v[192:195], v[10:13]
	v_mfma_f32_16x16x32_bf16 v[6:9], v[160:163], v[200:203], v[6:9]
	v_mfma_f32_16x16x32_bf16 v[2:5], v[168:171], v[200:203], v[2:5]
	v_mfma_f32_16x16x32_bf16 v[46:49], v[164:167], v[180:183], v[46:49]
	v_mfma_f32_16x16x32_bf16 v[42:45], v[172:175], v[180:183], v[42:45]
	v_mfma_f32_16x16x32_bf16 v[30:33], v[164:167], v[188:191], v[30:33]
	v_mfma_f32_16x16x32_bf16 v[26:29], v[172:175], v[188:191], v[26:29]
	v_mfma_f32_16x16x32_bf16 v[14:17], v[164:167], v[196:199], v[14:17]
	v_mfma_f32_16x16x32_bf16 v[10:13], v[172:175], v[196:199], v[10:13]
	v_mfma_f32_16x16x32_bf16 v[6:9], v[164:167], v[204:207], v[6:9]
	v_mfma_f32_16x16x32_bf16 v[2:5], v[172:175], v[204:207], v[2:5]
	s_setprio 0
	s_barrier
	v_add_u32_e32 v156, s29, v141
	v_add_u32_e32 v172, s26, v141
	ds_read_b128 v[144:147], v156
	ds_read_b128 v[148:151], v156 offset:1024
	ds_read_b128 v[152:155], v156 offset:2048
	ds_read_b128 v[156:159], v156 offset:3072
	ds_read_b128 v[160:163], v172
	ds_read_b128 v[164:167], v172 offset:1024
	ds_read_b128 v[168:171], v172 offset:2048
	ds_read_b128 v[172:175], v172 offset:3072
	s_add_u32 s20, s20, 0x40000
	s_addc_u32 s21, s21, 0
	s_mov_b32 m0, s25
	v_lshl_add_u64 v[220:221], s[20:21], 0, v[134:135]
	ds_read_b128 v[176:179], v143 offset:32768
	ds_read_b128 v[180:183], v143 offset:33792
	ds_read_b128 v[184:187], v143 offset:34816
	ds_read_b128 v[188:191], v143 offset:35840
	ds_read_b128 v[192:195], v143 offset:36864
	ds_read_b128 v[196:199], v143 offset:37888
	ds_read_b128 v[200:203], v143 offset:38912
	ds_read_b128 v[204:207], v143 offset:39936
	global_load_lds_dwordx4 v[220:221], off
	v_lshl_add_u64 v[220:221], s[20:21], 0, v[132:133]
	s_mov_b32 m0, s27
	s_nop 0
	global_load_lds_dwordx4 v[220:221], off
	s_waitcnt vmcnt(8)
	s_waitcnt lgkmcnt(0)
	s_barrier
	s_setprio 1
	s_waitcnt lgkmcnt(0)
	v_mfma_f32_16x16x32_bf16 v[126:129], v[144:147], v[176:179], v[126:129]
	v_mfma_f32_16x16x32_bf16 v[122:125], v[152:155], v[176:179], v[122:125]
	v_mfma_f32_16x16x32_bf16 v[118:121], v[144:147], v[184:187], v[118:121]
	v_mfma_f32_16x16x32_bf16 v[114:117], v[152:155], v[184:187], v[114:117]
	v_mfma_f32_16x16x32_bf16 v[102:105], v[144:147], v[192:195], v[102:105]
	v_mfma_f32_16x16x32_bf16 v[98:101], v[152:155], v[192:195], v[98:101]
	v_mfma_f32_16x16x32_bf16 v[86:89], v[144:147], v[200:203], v[86:89]
	v_mfma_f32_16x16x32_bf16 v[82:85], v[152:155], v[200:203], v[82:85]
	v_mfma_f32_16x16x32_bf16 v[126:129], v[148:151], v[180:183], v[126:129]
	v_mfma_f32_16x16x32_bf16 v[122:125], v[156:159], v[180:183], v[122:125]
	v_mfma_f32_16x16x32_bf16 v[118:121], v[148:151], v[188:191], v[118:121]
	v_mfma_f32_16x16x32_bf16 v[114:117], v[156:159], v[188:191], v[114:117]
	v_mfma_f32_16x16x32_bf16 v[102:105], v[148:151], v[196:199], v[102:105]
	v_mfma_f32_16x16x32_bf16 v[98:101], v[156:159], v[196:199], v[98:101]
	v_mfma_f32_16x16x32_bf16 v[86:89], v[148:151], v[204:207], v[86:89]
	v_mfma_f32_16x16x32_bf16 v[82:85], v[156:159], v[204:207], v[82:85]
	v_mfma_f32_16x16x32_bf16 v[110:113], v[160:163], v[176:179], v[110:113]
	v_mfma_f32_16x16x32_bf16 v[106:109], v[168:171], v[176:179], v[106:109]
	v_mfma_f32_16x16x32_bf16 v[94:97], v[160:163], v[184:187], v[94:97]
	v_mfma_f32_16x16x32_bf16 v[90:93], v[168:171], v[184:187], v[90:93]
	v_mfma_f32_16x16x32_bf16 v[78:81], v[160:163], v[192:195], v[78:81]
	v_mfma_f32_16x16x32_bf16 v[74:77], v[168:171], v[192:195], v[74:77]
	v_mfma_f32_16x16x32_bf16 v[70:73], v[160:163], v[200:203], v[70:73]
	v_mfma_f32_16x16x32_bf16 v[66:69], v[168:171], v[200:203], v[66:69]
	v_mfma_f32_16x16x32_bf16 v[110:113], v[164:167], v[180:183], v[110:113]
	v_mfma_f32_16x16x32_bf16 v[106:109], v[172:175], v[180:183], v[106:109]
	v_mfma_f32_16x16x32_bf16 v[94:97], v[164:167], v[188:191], v[94:97]
	v_mfma_f32_16x16x32_bf16 v[90:93], v[172:175], v[188:191], v[90:93]
	v_mfma_f32_16x16x32_bf16 v[78:81], v[164:167], v[196:199], v[78:81]
	v_mfma_f32_16x16x32_bf16 v[74:77], v[172:175], v[196:199], v[74:77]
	v_mfma_f32_16x16x32_bf16 v[70:73], v[164:167], v[204:207], v[70:73]
	v_mfma_f32_16x16x32_bf16 v[66:69], v[172:175], v[204:207], v[66:69]
	s_setprio 0
	s_barrier
; #define PG8_STAGE(bufoff, gbase, voff) do { _Pragma("unroll") for (int _i = 0; _i < 2; ++_i) \
;         __builtin_amdgcn_global_load_lds((const unsigned*)((const char*)(gbase) + (voff)[_i]), (LAS unsigned*)(lds + (bufoff) + ldsw + _i * 8192), 16, 0, 0); } while (0)
; #define PG8_LDA(dst, b, h) do { _Pragma("unroll") for (int m = 0; m < 4; ++m) _Pragma("unroll") for (int k = 0; k < 2; ++k) dst[m][k] = *(const LAS bf16x8*)(lds + PG8_SA(b, h) + aoff + m * 2048 + k * 1024); } while (0)
; #define PG8_MMA(ai, bj, At, Bt) do { __builtin_amdgcn_s_setprio(1); _Pragma("unroll") for (int m = 0; m < 4; ++m) _Pragma("unroll") for (int n = 0; n < 2; ++n) _Pragma("unroll") for (int k = 0; k < 2; ++k) \
;         acc[ai][bj][m][n] = __builtin_amdgcn_mfma_f32_16x16x32_bf16(Bt[n][k], At[m][k], acc[ai][bj][m][n], 0, 0, 0); __builtin_amdgcn_s_setprio(0); } while (0)
; #define PG8_WAIT_V(n) asm volatile("s_waitcnt vmcnt(" #n ")" ::: "memory")
; #define PG8_WAIT_L(n) asm volatile("s_waitcnt lgkmcnt(" #n ")" ::: "memory")
; #define PG8_BAR __builtin_amdgcn_s_barrier()
; #define PG8_SCHED __builtin_amdgcn_sched_barrier(0)
; template <class Epi, bool ALIGN_EPI, bool ASLOT = false>
; __device__ __forceinline__ void gemm_phase(LAS unsigned char* lds, const Gemm g, const Sched& S, const Epi& E) {
;     ...
;             PG8_LDA(At, 1, 1); PG8_STAGE(PG8_SB(1, 0), b3, voffB); PG8_STAGE(PG8_SB(1, 1), b3 + hstep, voffB); PG8_STAGE(PG8_SA(1, 0), a3, voffA);
;             PG8_WAIT_V(8); PG8_WAIT_L(0); PG8_BAR; PG8_MMA(1, 0, At, B0); PG8_MMA(1, 1, At, B1); PG8_BAR; PG8_SCHED;
;         }
	s_add_i32 s20, s29, s2
	v_lshl_add_u64 v[208:209], v[208:209], 0, s[16:17]
	s_mov_b32 m0, s20
	ds_read_b128 v[176:179], v143 offset:49152
	ds_read_b128 v[180:183], v143 offset:50176
	ds_read_b128 v[184:187], v143 offset:51200
	ds_read_b128 v[188:191], v143 offset:52224
	ds_read_b128 v[192:195], v143 offset:53248
	ds_read_b128 v[196:199], v143 offset:54272
	ds_read_b128 v[200:203], v143 offset:55296
	ds_read_b128 v[204:207], v143 offset:56320
	global_load_lds_dwordx4 v[208:209], off
	s_add_i32 m0, s20, 0x2000
	s_add_u32 s18, s18, 0x40080
	v_lshl_add_u64 v[208:209], v[210:211], 0, s[16:17]
	s_addc_u32 s19, s19, 0
	s_add_i32 s20, s26, s2
	global_load_lds_dwordx4 v[208:209], off
	v_lshl_add_u64 v[208:209], s[18:19], 0, v[0:1]
	s_mov_b32 m0, s20
	s_nop 0
	global_load_lds_dwordx4 v[208:209], off
	v_lshl_add_u64 v[208:209], s[18:19], 0, v[130:131]
	s_add_i32 m0, s20, 0x2000
	s_nop 0
	global_load_lds_dwordx4 v[208:209], off
	v_lshl_add_u64 v[208:209], v[212:213], 0, s[16:17]
	s_mov_b32 m0, s46
	s_nop 0
	global_load_lds_dwordx4 v[208:209], off
	v_lshl_add_u64 v[208:209], v[214:215], 0, s[16:17]
	s_mov_b32 m0, s47
	s_nop 0
	global_load_lds_dwordx4 v[208:209], off
	s_waitcnt vmcnt(8)
	s_waitcnt lgkmcnt(0)
	s_barrier
	s_setprio 1
	s_waitcnt lgkmcnt(0)
	v_mfma_f32_16x16x32_bf16 v[62:65], v[144:147], v[176:179], v[62:65]
	v_mfma_f32_16x16x32_bf16 v[58:61], v[152:155], v[176:179], v[58:61]
	v_mfma_f32_16x16x32_bf16 v[54:57], v[144:147], v[184:187], v[54:57]
	v_mfma_f32_16x16x32_bf16 v[50:53], v[152:155], v[184:187], v[50:53]
	v_mfma_f32_16x16x32_bf16 v[38:41], v[144:147], v[192:195], v[38:41]
	v_mfma_f32_16x16x32_bf16 v[34:37], v[152:155], v[192:195], v[34:37]
	v_mfma_f32_16x16x32_bf16 v[22:25], v[144:147], v[200:203], v[22:25]
	v_mfma_f32_16x16x32_bf16 v[18:21], v[152:155], v[200:203], v[18:21]
	v_mfma_f32_16x16x32_bf16 v[62:65], v[148:151], v[180:183], v[62:65]
	v_mfma_f32_16x16x32_bf16 v[58:61], v[156:159], v[180:183], v[58:61]
	v_mfma_f32_16x16x32_bf16 v[54:57], v[148:151], v[188:191], v[54:57]
	v_mfma_f32_16x16x32_bf16 v[50:53], v[156:159], v[188:191], v[50:53]
	v_mfma_f32_16x16x32_bf16 v[38:41], v[148:151], v[196:199], v[38:41]
	v_mfma_f32_16x16x32_bf16 v[34:37], v[156:159], v[196:199], v[34:37]
	v_mfma_f32_16x16x32_bf16 v[22:25], v[148:151], v[204:207], v[22:25]
	v_mfma_f32_16x16x32_bf16 v[18:21], v[156:159], v[204:207], v[18:21]
	v_mfma_f32_16x16x32_bf16 v[46:49], v[160:163], v[176:179], v[46:49]
	v_mfma_f32_16x16x32_bf16 v[42:45], v[168:171], v[176:179], v[42:45]
	v_mfma_f32_16x16x32_bf16 v[30:33], v[160:163], v[184:187], v[30:33]
	v_mfma_f32_16x16x32_bf16 v[26:29], v[168:171], v[184:187], v[26:29]
	v_mfma_f32_16x16x32_bf16 v[14:17], v[160:163], v[192:195], v[14:17]
	v_mfma_f32_16x16x32_bf16 v[10:13], v[168:171], v[192:195], v[10:13]
	v_mfma_f32_16x16x32_bf16 v[6:9], v[160:163], v[200:203], v[6:9]
	v_mfma_f32_16x16x32_bf16 v[2:5], v[168:171], v[200:203], v[2:5]
	v_mfma_f32_16x16x32_bf16 v[46:49], v[164:167], v[180:183], v[46:49]
	v_mfma_f32_16x16x32_bf16 v[42:45], v[172:175], v[180:183], v[42:45]
	v_mfma_f32_16x16x32_bf16 v[30:33], v[164:167], v[188:191], v[30:33]
	v_mfma_f32_16x16x32_bf16 v[26:29], v[172:175], v[188:191], v[26:29]
	v_mfma_f32_16x16x32_bf16 v[14:17], v[164:167], v[196:199], v[14:17]
	v_mfma_f32_16x16x32_bf16 v[10:13], v[172:175], v[196:199], v[10:13]
	v_mfma_f32_16x16x32_bf16 v[6:9], v[164:167], v[204:207], v[6:9]
	v_mfma_f32_16x16x32_bf16 v[2:5], v[172:175], v[204:207], v[2:5]
	s_setprio 0
	s_barrier
	s_add_i32 s50, s50, 2
	s_add_u32 s44, s44, 0x100
	s_addc_u32 s45, s45, 0
	s_add_u32 s15, s15, 0x100
	s_addc_u32 s49, s49, 0
	s_cmp_gt_u32 s50, 13
	s_cbranch_scc0 .LBB0_140
	s_and_b64 vcc, exec, s[8:9]
	s_cbranch_vccz .LBB0_143
	s_barrier

; #define PG8_STAGE(bufoff, gbase, voff) do { _Pragma("unroll") for (int _i = 0; _i < 2; ++_i) \
;         __builtin_amdgcn_global_load_lds((const unsigned*)((const char*)(gbase) + (voff)[_i]), (LAS unsigned*)(lds + (bufoff) + ldsw + _i * 8192), 16, 0, 0); } while (0)
; #define PG8_LDA(dst, b, h) do { _Pragma("unroll") for (int m = 0; m < 4; ++m) _Pragma("unroll") for (int k = 0; k < 2; ++k) dst[m][k] = *(const LAS bf16x8*)(lds + PG8_SA(b, h) + aoff + m * 2048 + k * 1024); } while (0)
; #define PG8_LDB(dst, b, h) do { _Pragma("unroll") for (int n = 0; n < 2; ++n) _Pragma("unroll") for (int k = 0; k < 2; ++k) dst[n][k] = *(const LAS bf16x8*)(lds + PG8_SB(b, h) + boff + n * 2048 + k * 1024); } while (0)
; #define PG8_MMA(ai, bj, At, Bt) do { __builtin_amdgcn_s_setprio(1); _Pragma("unroll") for (int m = 0; m < 4; ++m) _Pragma("unroll") for (int n = 0; n < 2; ++n) _Pragma("unroll") for (int k = 0; k < 2; ++k) \
;         acc[ai][bj][m][n] = __builtin_amdgcn_mfma_f32_16x16x32_bf16(Bt[n][k], At[m][k], acc[ai][bj][m][n], 0, 0, 0); __builtin_amdgcn_s_setprio(0); } while (0)
; #define PG8_WAIT_V(n) asm volatile("s_waitcnt vmcnt(" #n ")" ::: "memory")
; #define PG8_WAIT_L(n) asm volatile("s_waitcnt lgkmcnt(" #n ")" ::: "memory")
; #define PG8_BAR __builtin_amdgcn_s_barrier()
; #define PG8_SCHED __builtin_amdgcn_sched_barrier(0)
; template <class Epi, bool ALIGN_EPI, bool ASLOT = false>
; __device__ __forceinline__ void gemm_phase(LAS unsigned char* lds, const Gemm g, const Sched& S, const Epi& E) {
;     ...
;         for (int t = 0; t < nt; t += 2) {
;             const bool last = (t == nt - 2);
;             const char* a1 = cA + (size_t)(t + 1) * kstep;
;             const char* a2 = last ? nA : cA + (size_t)(t + 2) * kstep; const char* b2 = last ? nB : cB + (size_t)(t + 2) * kstep;
;             const char* a3 = a2 + kstep; const char* b3 = b2 + kstep;
;             PG8_LDB(B0, 0, 0); PG8_LDB(B1, 0, 1); PG8_SCHED; PG8_LDA(At, 0, 0); PG8_STAGE(PG8_SA(1, 1), a1 + hstep, voffA);
;             PG8_WAIT_V(8); PG8_WAIT_L(0); PG8_BAR; PG8_MMA(0, 0, At, B0); PG8_MMA(0, 1, At, B1); PG8_BAR; PG8_SCHED;
;             PG8_LDA(At, 0, 1); PG8_STAGE(PG8_SB(0, 0), b2, voffB); PG8_STAGE(PG8_SB(0, 1), b2 + hstep, voffB); PG8_STAGE(PG8_SA(0, 0), a2, voffA);
;             PG8_WAIT_V(8); PG8_WAIT_L(0); PG8_BAR; PG8_MMA(1, 0, At, B0); PG8_MMA(1, 1, At, B1); PG8_BAR; PG8_SCHED;
.LBB0_175:
	v_add_u32_e32 v156, s28, v142
	v_add_u32_e32 v172, s33, v142
	s_add_u32 s12, s31, s10
	ds_read_b128 v[144:147], v156
	ds_read_b128 v[148:151], v156 offset:1024
	ds_read_b128 v[152:155], v156 offset:2048
	ds_read_b128 v[156:159], v156 offset:3072
	ds_read_b128 v[160:163], v172
	ds_read_b128 v[164:167], v172 offset:1024
	ds_read_b128 v[168:171], v172 offset:2048
	ds_read_b128 v[172:175], v172 offset:3072
	s_addc_u32 s13, s35, s11
	s_add_u32 s12, s12, 0x8800100
	s_addc_u32 s13, s13, 0
	s_add_u32 s22, s34, s10
	s_addc_u32 s23, s36, s11
	s_cmpk_eq_i32 s10, 0x1500
	s_cselect_b32 s15, s39, s13
	s_cselect_b32 s14, s38, s12
	s_cselect_b32 s13, s9, s23
	s_cselect_b32 s12, s8, s22
	v_lshl_add_u64 v[208:209], v[136:137], 0, s[10:11]
	s_add_i32 m0, s18, 0xc000
	ds_read_b128 v[176:179], v143
	ds_read_b128 v[180:183], v143 offset:1024
	ds_read_b128 v[184:187], v143 offset:2048
	ds_read_b128 v[188:191], v143 offset:3072
	ds_read_b128 v[192:195], v143 offset:4096
	ds_read_b128 v[196:199], v143 offset:5120
	ds_read_b128 v[200:203], v143 offset:6144
	ds_read_b128 v[204:207], v143 offset:7168
	global_load_lds_dwordx4 v[208:209], off
	v_lshl_add_u64 v[208:209], v[138:139], 0, s[10:11]
	s_add_i32 m0, s18, 0xe000
	s_nop 0
	global_load_lds_dwordx4 v[208:209], off
	s_waitcnt vmcnt(8)
	s_waitcnt lgkmcnt(0)
	s_barrier
	s_setprio 1
	s_waitcnt lgkmcnt(0)
	v_mfma_f32_16x16x32_bf16 v[126:129], v[144:147], v[176:179], v[126:129]
	v_mfma_f32_16x16x32_bf16 v[122:125], v[152:155], v[176:179], v[122:125]
	v_mfma_f32_16x16x32_bf16 v[118:121], v[144:147], v[184:187], v[118:121]
	v_mfma_f32_16x16x32_bf16 v[114:117], v[152:155], v[184:187], v[114:117]
	v_mfma_f32_16x16x32_bf16 v[102:105], v[144:147], v[192:195], v[102:105]
	v_mfma_f32_16x16x32_bf16 v[98:101], v[152:155], v[192:195], v[98:101]
	v_mfma_f32_16x16x32_bf16 v[86:89], v[144:147], v[200:203], v[86:89]
	v_mfma_f32_16x16x32_bf16 v[82:85], v[152:155], v[200:203], v[82:85]
	v_mfma_f32_16x16x32_bf16 v[126:129], v[148:151], v[180:183], v[126:129]
	v_mfma_f32_16x16x32_bf16 v[122:125], v[156:159], v[180:183], v[122:125]
	v_mfma_f32_16x16x32_bf16 v[118:121], v[148:151], v[188:191], v[118:121]
	v_mfma_f32_16x16x32_bf16 v[114:117], v[156:159], v[188:191], v[114:117]
	v_mfma_f32_16x16x32_bf16 v[102:105], v[148:151], v[196:199], v[102:105]
	v_mfma_f32_16x16x32_bf16 v[98:101], v[156:159], v[196:199], v[98:101]
	v_mfma_f32_16x16x32_bf16 v[86:89], v[148:151], v[204:207], v[86:89]
	v_mfma_f32_16x16x32_bf16 v[82:85], v[156:159], v[204:207], v[82:85]
	v_mfma_f32_16x16x32_bf16 v[110:113], v[160:163], v[176:179], v[110:113]
	v_mfma_f32_16x16x32_bf16 v[106:109], v[168:171], v[176:179], v[106:109]
	v_mfma_f32_16x16x32_bf16 v[94:97], v[160:163], v[184:187], v[94:97]
	v_mfma_f32_16x16x32_bf16 v[90:93], v[168:171], v[184:187], v[90:93]
	v_mfma_f32_16x16x32_bf16 v[78:81], v[160:163], v[192:195], v[78:81]
	v_mfma_f32_16x16x32_bf16 v[74:77], v[168:171], v[192:195], v[74:77]
	v_mfma_f32_16x16x32_bf16 v[70:73], v[160:163], v[200:203], v[70:73]
	v_mfma_f32_16x16x32_bf16 v[66:69], v[168:171], v[200:203], v[66:69]
	v_mfma_f32_16x16x32_bf16 v[110:113], v[164:167], v[180:183], v[110:113]
	v_mfma_f32_16x16x32_bf16 v[106:109], v[172:175], v[180:183], v[106:109]
	v_mfma_f32_16x16x32_bf16 v[94:97], v[164:167], v[188:191], v[94:97]
	v_mfma_f32_16x16x32_bf16 v[90:93], v[172:175], v[188:191], v[90:93]
	v_mfma_f32_16x16x32_bf16 v[78:81], v[164:167], v[196:199], v[78:81]
	v_mfma_f32_16x16x32_bf16 v[74:77], v[172:175], v[196:199], v[74:77]
	v_mfma_f32_16x16x32_bf16 v[70:73], v[164:167], v[204:207], v[70:73]
	v_mfma_f32_16x16x32_bf16 v[66:69], v[172:175], v[204:207], v[66:69]
	s_setprio 0
	s_barrier
	s_add_i32 s22, s28, s3
	v_lshl_add_u64 v[208:209], s[12:13], 0, v[0:1]
	s_mov_b32 m0, s22
	ds_read_b128 v[176:179], v143 offset:16384
	ds_read_b128 v[180:183], v143 offset:17408
	ds_read_b128 v[184:187], v143 offset:18432
	ds_read_b128 v[188:191], v143 offset:19456
	ds_read_b128 v[192:195], v143 offset:20480
	ds_read_b128 v[196:199], v143 offset:21504
	ds_read_b128 v[200:203], v143 offset:22528
	ds_read_b128 v[204:207], v143 offset:23552
	global_load_lds_dwordx4 v[208:209], off
	s_add_i32 m0, s22, 0x2000
	s_add_u32 s22, s12, 0xb0000
	v_lshl_add_u64 v[210:211], s[12:13], 0, v[134:135]
	s_addc_u32 s23, s13, 0
	s_add_i32 s30, s33, s3
	global_load_lds_dwordx4 v[210:211], off
	v_lshl_add_u64 v[212:213], s[22:23], 0, v[0:1]
	s_mov_b32 m0, s30
	v_lshl_add_u64 v[214:215], s[14:15], 0, v[132:133]
	global_load_lds_dwordx4 v[212:213], off
	v_lshl_add_u64 v[212:213], s[22:23], 0, v[134:135]
	s_add_i32 m0, s30, 0x2000
	s_nop 0
	global_load_lds_dwordx4 v[212:213], off
	v_lshl_add_u64 v[212:213], s[14:15], 0, v[130:131]
	s_mov_b32 m0, s18
	s_nop 0
	global_load_lds_dwordx4 v[212:213], off
	s_mov_b32 m0, s19
	s_nop 0
	global_load_lds_dwordx4 v[214:215], off
	s_waitcnt vmcnt(8)
	s_waitcnt lgkmcnt(0)
	s_barrier
; #define PG8_STAGE(bufoff, gbase, voff) do { _Pragma("unroll") for (int _i = 0; _i < 2; ++_i) \
;         __builtin_amdgcn_global_load_lds((const unsigned*)((const char*)(gbase) + (voff)[_i]), (LAS unsigned*)(lds + (bufoff) + ldsw + _i * 8192), 16, 0, 0); } while (0)
; #define PG8_LDA(dst, b, h) do { _Pragma("unroll") for (int m = 0; m < 4; ++m) _Pragma("unroll") for (int k = 0; k < 2; ++k) dst[m][k] = *(const LAS bf16x8*)(lds + PG8_SA(b, h) + aoff + m * 2048 + k * 1024); } while (0)
; #define PG8_LDB(dst, b, h) do { _Pragma("unroll") for (int n = 0; n < 2; ++n) _Pragma("unroll") for (int k = 0; k < 2; ++k) dst[n][k] = *(const LAS bf16x8*)(lds + PG8_SB(b, h) + boff + n * 2048 + k * 1024); } while (0)
; #define PG8_MMA(ai, bj, At, Bt) do { __builtin_amdgcn_s_setprio(1); _Pragma("unroll") for (int m = 0; m < 4; ++m) _Pragma("unroll") for (int n = 0; n < 2; ++n) _Pragma("unroll") for (int k = 0; k < 2; ++k) \
;         acc[ai][bj][m][n] = __builtin_amdgcn_mfma_f32_16x16x32_bf16(Bt[n][k], At[m][k], acc[ai][bj][m][n], 0, 0, 0); __builtin_amdgcn_s_setprio(0); } while (0)
; #define PG8_WAIT_V(n) asm volatile("s_waitcnt vmcnt(" #n ")" ::: "memory")
; #define PG8_WAIT_L(n) asm volatile("s_waitcnt lgkmcnt(" #n ")" ::: "memory")
; #define PG8_BAR __builtin_amdgcn_s_barrier()
; #define PG8_SCHED __builtin_amdgcn_sched_barrier(0)
; template <class Epi, bool ALIGN_EPI, bool ASLOT = false>
; __device__ __forceinline__ void gemm_phase(LAS unsigned char* lds, const Gemm g, const Sched& S, const Epi& E) {
;     ...
;             PG8_WAIT_V(8); PG8_WAIT_L(0); PG8_BAR; PG8_MMA(1, 0, At, B0); PG8_MMA(1, 1, At, B1); PG8_BAR; PG8_SCHED;
;             PG8_LDB(B0, 1, 0); PG8_LDB(B1, 1, 1); PG8_SCHED; PG8_LDA(At, 1, 0); PG8_STAGE(PG8_SA(0, 1), a2 + hstep, voffA);
;             PG8_WAIT_V(8); PG8_WAIT_L(0); PG8_BAR; PG8_MMA(0, 0, At, B0); PG8_MMA(0, 1, At, B1); PG8_BAR; PG8_SCHED;
	s_setprio 1
	s_waitcnt lgkmcnt(0)
	v_mfma_f32_16x16x32_bf16 v[62:65], v[144:147], v[176:179], v[62:65]
	v_mfma_f32_16x16x32_bf16 v[58:61], v[152:155], v[176:179], v[58:61]
	v_mfma_f32_16x16x32_bf16 v[54:57], v[144:147], v[184:187], v[54:57]
	v_mfma_f32_16x16x32_bf16 v[50:53], v[152:155], v[184:187], v[50:53]
	v_mfma_f32_16x16x32_bf16 v[38:41], v[144:147], v[192:195], v[38:41]
	v_mfma_f32_16x16x32_bf16 v[34:37], v[152:155], v[192:195], v[34:37]
	v_mfma_f32_16x16x32_bf16 v[22:25], v[144:147], v[200:203], v[22:25]
	v_mfma_f32_16x16x32_bf16 v[18:21], v[152:155], v[200:203], v[18:21]
	v_mfma_f32_16x16x32_bf16 v[62:65], v[148:151], v[180:183], v[62:65]
	v_mfma_f32_16x16x32_bf16 v[58:61], v[156:159], v[180:183], v[58:61]
	v_mfma_f32_16x16x32_bf16 v[54:57], v[148:151], v[188:191], v[54:57]
	v_mfma_f32_16x16x32_bf16 v[50:53], v[156:159], v[188:191], v[50:53]
	v_mfma_f32_16x16x32_bf16 v[38:41], v[148:151], v[196:199], v[38:41]
	v_mfma_f32_16x16x32_bf16 v[34:37], v[156:159], v[196:199], v[34:37]
	v_mfma_f32_16x16x32_bf16 v[22:25], v[148:151], v[204:207], v[22:25]
	v_mfma_f32_16x16x32_bf16 v[18:21], v[156:159], v[204:207], v[18:21]
	v_mfma_f32_16x16x32_bf16 v[46:49], v[160:163], v[176:179], v[46:49]
	v_mfma_f32_16x16x32_bf16 v[42:45], v[168:171], v[176:179], v[42:45]
	v_mfma_f32_16x16x32_bf16 v[30:33], v[160:163], v[184:187], v[30:33]
	v_mfma_f32_16x16x32_bf16 v[26:29], v[168:171], v[184:187], v[26:29]
	v_mfma_f32_16x16x32_bf16 v[14:17], v[160:163], v[192:195], v[14:17]
	v_mfma_f32_16x16x32_bf16 v[10:13], v[168:171], v[192:195], v[10:13]
	v_mfma_f32_16x16x32_bf16 v[6:9], v[160:163], v[200:203], v[6:9]
	v_mfma_f32_16x16x32_bf16 v[2:5], v[168:171], v[200:203], v[2:5]
	v_mfma_f32_16x16x32_bf16 v[46:49], v[164:167], v[180:183], v[46:49]
	v_mfma_f32_16x16x32_bf16 v[42:45], v[172:175], v[180:183], v[42:45]
	v_mfma_f32_16x16x32_bf16 v[30:33], v[164:167], v[188:191], v[30:33]
	v_mfma_f32_16x16x32_bf16 v[26:29], v[172:175], v[188:191], v[26:29]
	v_mfma_f32_16x16x32_bf16 v[14:17], v[164:167], v[196:199], v[14:17]
	v_mfma_f32_16x16x32_bf16 v[10:13], v[172:175], v[196:199], v[10:13]
	v_mfma_f32_16x16x32_bf16 v[6:9], v[164:167], v[204:207], v[6:9]
	v_mfma_f32_16x16x32_bf16 v[2:5], v[172:175], v[204:207], v[2:5]
	s_setprio 0
	s_barrier
	v_add_u32_e32 v156, s29, v142
	v_add_u32_e32 v172, s26, v142
	ds_read_b128 v[144:147], v156
	ds_read_b128 v[148:151], v156 offset:1024
	ds_read_b128 v[152:155], v156 offset:2048
	ds_read_b128 v[156:159], v156 offset:3072
	ds_read_b128 v[160:163], v172
	ds_read_b128 v[164:167], v172 offset:1024
	ds_read_b128 v[168:171], v172 offset:2048
	ds_read_b128 v[172:175], v172 offset:3072
	s_add_u32 s14, s14, 0xb0000
	s_addc_u32 s15, s15, 0
	s_mov_b32 m0, s20
	v_lshl_add_u64 v[220:221], s[14:15], 0, v[130:131]
	ds_read_b128 v[176:179], v143 offset:32768
	ds_read_b128 v[180:183], v143 offset:33792
	ds_read_b128 v[184:187], v143 offset:34816
	ds_read_b128 v[188:191], v143 offset:35840
	ds_read_b128 v[192:195], v143 offset:36864
	ds_read_b128 v[196:199], v143 offset:37888
	ds_read_b128 v[200:203], v143 offset:38912
	ds_read_b128 v[204:207], v143 offset:39936
	global_load_lds_dwordx4 v[220:221], off
	v_lshl_add_u64 v[220:221], s[14:15], 0, v[132:133]
	s_mov_b32 m0, s21
	s_nop 0
	global_load_lds_dwordx4 v[220:221], off
	s_waitcnt vmcnt(8)
	s_waitcnt lgkmcnt(0)
	s_barrier
	s_setprio 1
	s_waitcnt lgkmcnt(0)
	v_mfma_f32_16x16x32_bf16 v[126:129], v[144:147], v[176:179], v[126:129]
	v_mfma_f32_16x16x32_bf16 v[122:125], v[152:155], v[176:179], v[122:125]
	v_mfma_f32_16x16x32_bf16 v[118:121], v[144:147], v[184:187], v[118:121]
	v_mfma_f32_16x16x32_bf16 v[114:117], v[152:155], v[184:187], v[114:117]
	v_mfma_f32_16x16x32_bf16 v[102:105], v[144:147], v[192:195], v[102:105]
	v_mfma_f32_16x16x32_bf16 v[98:101], v[152:155], v[192:195], v[98:101]
	v_mfma_f32_16x16x32_bf16 v[86:89], v[144:147], v[200:203], v[86:89]
	v_mfma_f32_16x16x32_bf16 v[82:85], v[152:155], v[200:203], v[82:85]
	v_mfma_f32_16x16x32_bf16 v[126:129], v[148:151], v[180:183], v[126:129]
	v_mfma_f32_16x16x32_bf16 v[122:125], v[156:159], v[180:183], v[122:125]
	v_mfma_f32_16x16x32_bf16 v[118:121], v[148:151], v[188:191], v[118:121]
	v_mfma_f32_16x16x32_bf16 v[114:117], v[156:159], v[188:191], v[114:117]
	v_mfma_f32_16x16x32_bf16 v[102:105], v[148:151], v[196:199], v[102:105]
	v_mfma_f32_16x16x32_bf16 v[98:101], v[156:159], v[196:199], v[98:101]
	v_mfma_f32_16x16x32_bf16 v[86:89], v[148:151], v[204:207], v[86:89]
	v_mfma_f32_16x16x32_bf16 v[82:85], v[156:159], v[204:207], v[82:85]
	v_mfma_f32_16x16x32_bf16 v[110:113], v[160:163], v[176:179], v[110:113]
	v_mfma_f32_16x16x32_bf16 v[106:109], v[168:171], v[176:179], v[106:109]
	v_mfma_f32_16x16x32_bf16 v[94:97], v[160:163], v[184:187], v[94:97]
	v_mfma_f32_16x16x32_bf16 v[90:93], v[168:171], v[184:187], v[90:93]
	v_mfma_f32_16x16x32_bf16 v[78:81], v[160:163], v[192:195], v[78:81]
	v_mfma_f32_16x16x32_bf16 v[74:77], v[168:171], v[192:195], v[74:77]
	v_mfma_f32_16x16x32_bf16 v[70:73], v[160:163], v[200:203], v[70:73]
	v_mfma_f32_16x16x32_bf16 v[66:69], v[168:171], v[200:203], v[66:69]
	v_mfma_f32_16x16x32_bf16 v[110:113], v[164:167], v[180:183], v[110:113]
	v_mfma_f32_16x16x32_bf16 v[106:109], v[172:175], v[180:183], v[106:109]
	v_mfma_f32_16x16x32_bf16 v[94:97], v[164:167], v[188:191], v[94:97]
	v_mfma_f32_16x16x32_bf16 v[90:93], v[172:175], v[188:191], v[90:93]
	v_mfma_f32_16x16x32_bf16 v[78:81], v[164:167], v[196:199], v[78:81]
	v_mfma_f32_16x16x32_bf16 v[74:77], v[172:175], v[196:199], v[74:77]
	v_mfma_f32_16x16x32_bf16 v[70:73], v[164:167], v[204:207], v[70:73]
	v_mfma_f32_16x16x32_bf16 v[66:69], v[172:175], v[204:207], v[66:69]
	s_setprio 0
	s_barrier
; #define PG8_STAGE(bufoff, gbase, voff) do { _Pragma("unroll") for (int _i = 0; _i < 2; ++_i) \
;         __builtin_amdgcn_global_load_lds((const unsigned*)((const char*)(gbase) + (voff)[_i]), (LAS unsigned*)(lds + (bufoff) + ldsw + _i * 8192), 16, 0, 0); } while (0)
; #define PG8_LDA(dst, b, h) do { _Pragma("unroll") for (int m = 0; m < 4; ++m) _Pragma("unroll") for (int k = 0; k < 2; ++k) dst[m][k] = *(const LAS bf16x8*)(lds + PG8_SA(b, h) + aoff + m * 2048 + k * 1024); } while (0)
; #define PG8_MMA(ai, bj, At, Bt) do { __builtin_amdgcn_s_setprio(1); _Pragma("unroll") for (int m = 0; m < 4; ++m) _Pragma("unroll") for (int n = 0; n < 2; ++n) _Pragma("unroll") for (int k = 0; k < 2; ++k) \
;         acc[ai][bj][m][n] = __builtin_amdgcn_mfma_f32_16x16x32_bf16(Bt[n][k], At[m][k], acc[ai][bj][m][n], 0, 0, 0); __builtin_amdgcn_s_setprio(0); } while (0)
; #define PG8_WAIT_V(n) asm volatile("s_waitcnt vmcnt(" #n ")" ::: "memory")
; #define PG8_WAIT_L(n) asm volatile("s_waitcnt lgkmcnt(" #n ")" ::: "memory")
; #define PG8_BAR __builtin_amdgcn_s_barrier()
; #define PG8_SCHED __builtin_amdgcn_sched_barrier(0)
; template <class Epi, bool ALIGN_EPI, bool ASLOT = false>
; __device__ __forceinline__ void gemm_phase(LAS unsigned char* lds, const Gemm g, const Sched& S, const Epi& E) {
;     ...
;             PG8_LDA(At, 1, 1); PG8_STAGE(PG8_SB(1, 0), b3, voffB); PG8_STAGE(PG8_SB(1, 1), b3 + hstep, voffB); PG8_STAGE(PG8_SA(1, 0), a3, voffA);
;             PG8_WAIT_V(8); PG8_WAIT_L(0); PG8_BAR; PG8_MMA(1, 0, At, B0); PG8_MMA(1, 1, At, B1); PG8_BAR; PG8_SCHED;
;         }
	s_add_i32 s14, s29, s3
	v_lshl_add_u64 v[208:209], v[208:209], 0, s[16:17]
	s_mov_b32 m0, s14
	ds_read_b128 v[176:179], v143 offset:49152
	ds_read_b128 v[180:183], v143 offset:50176
	ds_read_b128 v[184:187], v143 offset:51200
	ds_read_b128 v[188:191], v143 offset:52224
	ds_read_b128 v[192:195], v143 offset:53248
	ds_read_b128 v[196:199], v143 offset:54272
	ds_read_b128 v[200:203], v143 offset:55296
	ds_read_b128 v[204:207], v143 offset:56320
	global_load_lds_dwordx4 v[208:209], off
	s_add_i32 m0, s14, 0x2000
	s_add_u32 s12, s12, 0xb0080
	v_lshl_add_u64 v[208:209], v[210:211], 0, s[16:17]
	s_addc_u32 s13, s13, 0
	s_add_i32 s14, s26, s3
	global_load_lds_dwordx4 v[208:209], off
	v_lshl_add_u64 v[208:209], s[12:13], 0, v[0:1]
	s_mov_b32 m0, s14
	s_nop 0
	global_load_lds_dwordx4 v[208:209], off
	v_lshl_add_u64 v[208:209], s[12:13], 0, v[134:135]
	s_add_i32 m0, s14, 0x2000
	s_nop 0
	global_load_lds_dwordx4 v[208:209], off
	v_lshl_add_u64 v[208:209], v[212:213], 0, s[16:17]
	s_mov_b32 m0, s25
	s_nop 0
	global_load_lds_dwordx4 v[208:209], off
	v_lshl_add_u64 v[208:209], v[214:215], 0, s[16:17]
	s_mov_b32 m0, s27
	s_nop 0
	global_load_lds_dwordx4 v[208:209], off
	s_waitcnt vmcnt(8)
	s_waitcnt lgkmcnt(0)
	s_barrier
	s_setprio 1
	s_waitcnt lgkmcnt(0)
	v_mfma_f32_16x16x32_bf16 v[62:65], v[144:147], v[176:179], v[62:65]
	v_mfma_f32_16x16x32_bf16 v[58:61], v[152:155], v[176:179], v[58:61]
	v_mfma_f32_16x16x32_bf16 v[54:57], v[144:147], v[184:187], v[54:57]
	v_mfma_f32_16x16x32_bf16 v[50:53], v[152:155], v[184:187], v[50:53]
	v_mfma_f32_16x16x32_bf16 v[38:41], v[144:147], v[192:195], v[38:41]
	v_mfma_f32_16x16x32_bf16 v[34:37], v[152:155], v[192:195], v[34:37]
	v_mfma_f32_16x16x32_bf16 v[22:25], v[144:147], v[200:203], v[22:25]
	v_mfma_f32_16x16x32_bf16 v[18:21], v[152:155], v[200:203], v[18:21]
	v_mfma_f32_16x16x32_bf16 v[62:65], v[148:151], v[180:183], v[62:65]
	v_mfma_f32_16x16x32_bf16 v[58:61], v[156:159], v[180:183], v[58:61]
	v_mfma_f32_16x16x32_bf16 v[54:57], v[148:151], v[188:191], v[54:57]
	v_mfma_f32_16x16x32_bf16 v[50:53], v[156:159], v[188:191], v[50:53]
	v_mfma_f32_16x16x32_bf16 v[38:41], v[148:151], v[196:199], v[38:41]
	v_mfma_f32_16x16x32_bf16 v[34:37], v[156:159], v[196:199], v[34:37]
	v_mfma_f32_16x16x32_bf16 v[22:25], v[148:151], v[204:207], v[22:25]
	v_mfma_f32_16x16x32_bf16 v[18:21], v[156:159], v[204:207], v[18:21]
	v_mfma_f32_16x16x32_bf16 v[46:49], v[160:163], v[176:179], v[46:49]
	v_mfma_f32_16x16x32_bf16 v[42:45], v[168:171], v[176:179], v[42:45]
	v_mfma_f32_16x16x32_bf16 v[30:33], v[160:163], v[184:187], v[30:33]
	v_mfma_f32_16x16x32_bf16 v[26:29], v[168:171], v[184:187], v[26:29]
	v_mfma_f32_16x16x32_bf16 v[14:17], v[160:163], v[192:195], v[14:17]
	v_mfma_f32_16x16x32_bf16 v[10:13], v[168:171], v[192:195], v[10:13]
	v_mfma_f32_16x16x32_bf16 v[6:9], v[160:163], v[200:203], v[6:9]
	v_mfma_f32_16x16x32_bf16 v[2:5], v[168:171], v[200:203], v[2:5]
	v_mfma_f32_16x16x32_bf16 v[46:49], v[164:167], v[180:183], v[46:49]
	v_mfma_f32_16x16x32_bf16 v[42:45], v[172:175], v[180:183], v[42:45]
	v_mfma_f32_16x16x32_bf16 v[30:33], v[164:167], v[188:191], v[30:33]
	v_mfma_f32_16x16x32_bf16 v[26:29], v[172:175], v[188:191], v[26:29]
	v_mfma_f32_16x16x32_bf16 v[14:17], v[164:167], v[196:199], v[14:17]
	v_mfma_f32_16x16x32_bf16 v[10:13], v[172:175], v[196:199], v[10:13]
	v_mfma_f32_16x16x32_bf16 v[6:9], v[164:167], v[204:207], v[6:9]
	v_mfma_f32_16x16x32_bf16 v[2:5], v[172:175], v[204:207], v[2:5]
	s_setprio 0
	s_barrier
	s_add_i32 s37, s37, 2
	s_add_u32 s10, s10, 0x100
	s_addc_u32 s11, s11, 0
	s_cmp_gt_u32 s37, 41
	s_cbranch_scc0 .LBB0_175
	s_cmpk_lt_u32 s2, 0x100
	s_cbranch_scc0 .LBB0_178
	s_barrier

; #define PG8_STAGE(bufoff, gbase, voff) do { _Pragma("unroll") for (int _i = 0; _i < 2; ++_i) \
;         __builtin_amdgcn_global_load_lds((const unsigned*)((const char*)(gbase) + (voff)[_i]), (LAS unsigned*)(lds + (bufoff) + ldsw + _i * 8192), 16, 0, 0); } while (0)
; #define PG8_LDA(dst, b, h) do { _Pragma("unroll") for (int m = 0; m < 4; ++m) _Pragma("unroll") for (int k = 0; k < 2; ++k) dst[m][k] = *(const LAS bf16x8*)(lds + PG8_SA(b, h) + aoff + m * 2048 + k * 1024); } while (0)
; #define PG8_LDB(dst, b, h) do { _Pragma("unroll") for (int n = 0; n < 2; ++n) _Pragma("unroll") for (int k = 0; k < 2; ++k) dst[n][k] = *(const LAS bf16x8*)(lds + PG8_SB(b, h) + boff + n * 2048 + k * 1024); } while (0)
; #define PG8_MMA(ai, bj, At, Bt) do { __builtin_amdgcn_s_setprio(1); _Pragma("unroll") for (int m = 0; m < 4; ++m) _Pragma("unroll") for (int n = 0; n < 2; ++n) _Pragma("unroll") for (int k = 0; k < 2; ++k) \
;         acc[ai][bj][m][n] = __builtin_amdgcn_mfma_f32_16x16x32_bf16(Bt[n][k], At[m][k], acc[ai][bj][m][n], 0, 0, 0); __builtin_amdgcn_s_setprio(0); } while (0)
; #define PG8_WAIT_V(n) asm volatile("s_waitcnt vmcnt(" #n ")" ::: "memory")
; #define PG8_WAIT_L(n) asm volatile("s_waitcnt lgkmcnt(" #n ")" ::: "memory")
; #define PG8_BAR __builtin_amdgcn_s_barrier()
; #define PG8_SCHED __builtin_amdgcn_sched_barrier(0)
; template <class Epi, bool ALIGN_EPI, bool ASLOT = false>
; __device__ __forceinline__ void gemm_phase(LAS unsigned char* lds, const Gemm g, const Sched& S, const Epi& E) {
;     ...
;         for (int t = 0; t < nt; t += 2) {
;             const bool last = (t == nt - 2);
;             const char* a1 = cA + (size_t)(t + 1) * kstep;
;             const char* a2 = last ? nA : cA + (size_t)(t + 2) * kstep; const char* b2 = last ? nB : cB + (size_t)(t + 2) * kstep;
;             const char* a3 = a2 + kstep; const char* b3 = b2 + kstep;
;             PG8_LDB(B0, 0, 0); PG8_LDB(B1, 0, 1); PG8_SCHED; PG8_LDA(At, 0, 0); PG8_STAGE(PG8_SA(1, 1), a1 + hstep, voffA);
;             PG8_WAIT_V(8); PG8_WAIT_L(0); PG8_BAR; PG8_MMA(0, 0, At, B0); PG8_MMA(0, 1, At, B1); PG8_BAR; PG8_SCHED;
;             PG8_LDA(At, 0, 1); PG8_STAGE(PG8_SB(0, 0), b2, voffB); PG8_STAGE(PG8_SB(0, 1), b2 + hstep, voffB); PG8_STAGE(PG8_SA(0, 0), a2, voffA);
;             PG8_WAIT_V(8); PG8_WAIT_L(0); PG8_BAR; PG8_MMA(1, 0, At, B0); PG8_MMA(1, 1, At, B1); PG8_BAR; PG8_SCHED;
.LBB0_300:
	v_add_u32_e32 v0, s28, v177
	ds_read_b128 v[130:133], v0
	ds_read_b128 v[134:137], v0 offset:1024
	ds_read_b128 v[138:141], v0 offset:2048
	ds_read_b128 v[142:145], v0 offset:3072
	v_add_u32_e32 v0, s33, v177
	ds_read_b128 v[158:161], v0
	ds_read_b128 v[162:165], v0 offset:1024
	ds_read_b128 v[166:169], v0 offset:2048
	ds_read_b128 v[170:173], v0 offset:3072
	s_add_u32 s14, s0, 0xfffc0080
	s_addc_u32 s15, s1, -1
	s_cmp_eq_u32 s57, 12
	s_cselect_b32 s19, s3, s15
	s_cselect_b32 s18, s24, s14
	s_cselect_b32 s15, s25, s45
	s_cselect_b32 s14, s41, s43
	v_lshl_add_u64 v[174:175], s[0:1], 0, v[154:155]
	s_add_i32 m0, s50, 0xc000
	ds_read_b128 v[182:185], v180
	ds_read_b128 v[186:189], v180 offset:1024
	ds_read_b128 v[190:193], v180 offset:2048
	ds_read_b128 v[194:197], v180 offset:3072
	ds_read_b128 v[198:201], v180 offset:4096
	ds_read_b128 v[202:205], v180 offset:5120
	ds_read_b128 v[206:209], v180 offset:6144
	ds_read_b128 v[210:213], v180 offset:7168
	global_load_lds_dwordx4 v[174:175], off
	v_lshl_add_u64 v[174:175], s[0:1], 0, v[156:157]
	s_add_i32 m0, s50, 0xe000
	s_nop 0
	global_load_lds_dwordx4 v[174:175], off
	s_waitcnt vmcnt(8)
	s_waitcnt lgkmcnt(0)
	s_barrier
	s_setprio 1
	s_waitcnt lgkmcnt(0)
	v_mfma_f32_16x16x32_bf16 v[126:129], v[130:133], v[182:185], v[126:129]
	v_mfma_f32_16x16x32_bf16 v[122:125], v[138:141], v[182:185], v[122:125]
	v_mfma_f32_16x16x32_bf16 v[110:113], v[130:133], v[190:193], v[110:113]
	v_mfma_f32_16x16x32_bf16 v[106:109], v[138:141], v[190:193], v[106:109]
	v_mfma_f32_16x16x32_bf16 v[94:97], v[130:133], v[198:201], v[94:97]
	v_mfma_f32_16x16x32_bf16 v[90:93], v[138:141], v[198:201], v[90:93]
	v_mfma_f32_16x16x32_bf16 v[78:81], v[130:133], v[206:209], v[78:81]
	v_mfma_f32_16x16x32_bf16 v[74:77], v[138:141], v[206:209], v[74:77]
	v_mfma_f32_16x16x32_bf16 v[126:129], v[134:137], v[186:189], v[126:129]
	v_mfma_f32_16x16x32_bf16 v[122:125], v[142:145], v[186:189], v[122:125]
	v_mfma_f32_16x16x32_bf16 v[110:113], v[134:137], v[194:197], v[110:113]
	v_mfma_f32_16x16x32_bf16 v[106:109], v[142:145], v[194:197], v[106:109]
	v_mfma_f32_16x16x32_bf16 v[94:97], v[134:137], v[202:205], v[94:97]
	v_mfma_f32_16x16x32_bf16 v[90:93], v[142:145], v[202:205], v[90:93]
	v_mfma_f32_16x16x32_bf16 v[78:81], v[134:137], v[210:213], v[78:81]
	v_mfma_f32_16x16x32_bf16 v[74:77], v[142:145], v[210:213], v[74:77]
	v_mfma_f32_16x16x32_bf16 v[118:121], v[158:161], v[182:185], v[118:121]
	v_mfma_f32_16x16x32_bf16 v[114:117], v[166:169], v[182:185], v[114:117]
	v_mfma_f32_16x16x32_bf16 v[102:105], v[158:161], v[190:193], v[102:105]
	v_mfma_f32_16x16x32_bf16 v[98:101], v[166:169], v[190:193], v[98:101]
	v_mfma_f32_16x16x32_bf16 v[86:89], v[158:161], v[198:201], v[86:89]
	v_mfma_f32_16x16x32_bf16 v[82:85], v[166:169], v[198:201], v[82:85]
	v_mfma_f32_16x16x32_bf16 v[70:73], v[158:161], v[206:209], v[70:73]
	v_mfma_f32_16x16x32_bf16 v[66:69], v[166:169], v[206:209], v[66:69]
	v_mfma_f32_16x16x32_bf16 v[118:121], v[162:165], v[186:189], v[118:121]
	v_mfma_f32_16x16x32_bf16 v[114:117], v[170:173], v[186:189], v[114:117]
	v_mfma_f32_16x16x32_bf16 v[102:105], v[162:165], v[194:197], v[102:105]
	v_mfma_f32_16x16x32_bf16 v[98:101], v[170:173], v[194:197], v[98:101]
	v_mfma_f32_16x16x32_bf16 v[86:89], v[162:165], v[202:205], v[86:89]
	v_mfma_f32_16x16x32_bf16 v[82:85], v[170:173], v[202:205], v[82:85]
	v_mfma_f32_16x16x32_bf16 v[70:73], v[162:165], v[210:213], v[70:73]
	v_mfma_f32_16x16x32_bf16 v[66:69], v[170:173], v[210:213], v[66:69]
	s_setprio 0
	s_barrier
	s_add_i32 s22, s28, s27
	v_lshl_add_u64 v[174:175], s[14:15], 0, v[148:149]
	s_mov_b32 m0, s22
	ds_read_b128 v[182:185], v180 offset:16384
	ds_read_b128 v[186:189], v180 offset:17408
	ds_read_b128 v[190:193], v180 offset:18432
	ds_read_b128 v[194:197], v180 offset:19456
	ds_read_b128 v[198:201], v180 offset:20480
	ds_read_b128 v[202:205], v180 offset:21504
	ds_read_b128 v[206:209], v180 offset:22528
	ds_read_b128 v[210:213], v180 offset:23552
	global_load_lds_dwordx4 v[174:175], off
	s_add_i32 m0, s22, 0x2000
	s_add_u32 s22, s14, 0x40000
	v_lshl_add_u64 v[214:215], s[14:15], 0, v[152:153]
	s_addc_u32 s23, s15, 0
	s_add_i32 s30, s33, s27
	global_load_lds_dwordx4 v[214:215], off
	v_lshl_add_u64 v[220:221], s[22:23], 0, v[148:149]
	s_mov_b32 m0, s30
	v_lshl_add_u64 v[222:223], s[18:19], 0, v[150:151]
	global_load_lds_dwordx4 v[220:221], off
	v_lshl_add_u64 v[220:221], s[22:23], 0, v[152:153]
	s_add_i32 m0, s30, 0x2000
	s_nop 0
	global_load_lds_dwordx4 v[220:221], off
	v_lshl_add_u64 v[220:221], s[18:19], 0, v[146:147]
	s_mov_b32 m0, s50
	s_nop 0
	global_load_lds_dwordx4 v[220:221], off
	s_mov_b32 m0, s51
	s_nop 0
	global_load_lds_dwordx4 v[222:223], off
	s_waitcnt vmcnt(8)
	s_waitcnt lgkmcnt(0)
	s_barrier
; #define PG8_STAGE(bufoff, gbase, voff) do { _Pragma("unroll") for (int _i = 0; _i < 2; ++_i) \
;         __builtin_amdgcn_global_load_lds((const unsigned*)((const char*)(gbase) + (voff)[_i]), (LAS unsigned*)(lds + (bufoff) + ldsw + _i * 8192), 16, 0, 0); } while (0)
; #define PG8_LDA(dst, b, h) do { _Pragma("unroll") for (int m = 0; m < 4; ++m) _Pragma("unroll") for (int k = 0; k < 2; ++k) dst[m][k] = *(const LAS bf16x8*)(lds + PG8_SA(b, h) + aoff + m * 2048 + k * 1024); } while (0)
; #define PG8_LDB(dst, b, h) do { _Pragma("unroll") for (int n = 0; n < 2; ++n) _Pragma("unroll") for (int k = 0; k < 2; ++k) dst[n][k] = *(const LAS bf16x8*)(lds + PG8_SB(b, h) + boff + n * 2048 + k * 1024); } while (0)
; #define PG8_MMA(ai, bj, At, Bt) do { __builtin_amdgcn_s_setprio(1); _Pragma("unroll") for (int m = 0; m < 4; ++m) _Pragma("unroll") for (int n = 0; n < 2; ++n) _Pragma("unroll") for (int k = 0; k < 2; ++k) \
;         acc[ai][bj][m][n] = __builtin_amdgcn_mfma_f32_16x16x32_bf16(Bt[n][k], At[m][k], acc[ai][bj][m][n], 0, 0, 0); __builtin_amdgcn_s_setprio(0); } while (0)
; #define PG8_WAIT_V(n) asm volatile("s_waitcnt vmcnt(" #n ")" ::: "memory")
; #define PG8_WAIT_L(n) asm volatile("s_waitcnt lgkmcnt(" #n ")" ::: "memory")
; #define PG8_BAR __builtin_amdgcn_s_barrier()
; #define PG8_SCHED __builtin_amdgcn_sched_barrier(0)
; template <class Epi, bool ALIGN_EPI, bool ASLOT = false>
; __device__ __forceinline__ void gemm_phase(LAS unsigned char* lds, const Gemm g, const Sched& S, const Epi& E) {
;     ...
;             PG8_WAIT_V(8); PG8_WAIT_L(0); PG8_BAR; PG8_MMA(1, 0, At, B0); PG8_MMA(1, 1, At, B1); PG8_BAR; PG8_SCHED;
;             PG8_LDB(B0, 1, 0); PG8_LDB(B1, 1, 1); PG8_SCHED; PG8_LDA(At, 1, 0); PG8_STAGE(PG8_SA(0, 1), a2 + hstep, voffA);
;             PG8_WAIT_V(8); PG8_WAIT_L(0); PG8_BAR; PG8_MMA(0, 0, At, B0); PG8_MMA(0, 1, At, B1); PG8_BAR; PG8_SCHED;
	s_setprio 1
	s_waitcnt lgkmcnt(0)
	v_mfma_f32_16x16x32_bf16 v[62:65], v[130:133], v[182:185], v[62:65]
	v_mfma_f32_16x16x32_bf16 v[58:61], v[138:141], v[182:185], v[58:61]
	v_mfma_f32_16x16x32_bf16 v[46:49], v[130:133], v[190:193], v[46:49]
	v_mfma_f32_16x16x32_bf16 v[42:45], v[138:141], v[190:193], v[42:45]
	v_mfma_f32_16x16x32_bf16 v[30:33], v[130:133], v[198:201], v[30:33]
	v_mfma_f32_16x16x32_bf16 v[26:29], v[138:141], v[198:201], v[26:29]
	v_mfma_f32_16x16x32_bf16 v[14:17], v[130:133], v[206:209], v[14:17]
	v_mfma_f32_16x16x32_bf16 v[10:13], v[138:141], v[206:209], v[10:13]
	v_mfma_f32_16x16x32_bf16 v[62:65], v[134:137], v[186:189], v[62:65]
	v_mfma_f32_16x16x32_bf16 v[58:61], v[142:145], v[186:189], v[58:61]
	v_mfma_f32_16x16x32_bf16 v[46:49], v[134:137], v[194:197], v[46:49]
	v_mfma_f32_16x16x32_bf16 v[42:45], v[142:145], v[194:197], v[42:45]
	v_mfma_f32_16x16x32_bf16 v[30:33], v[134:137], v[202:205], v[30:33]
	v_mfma_f32_16x16x32_bf16 v[26:29], v[142:145], v[202:205], v[26:29]
	v_mfma_f32_16x16x32_bf16 v[14:17], v[134:137], v[210:213], v[14:17]
	v_mfma_f32_16x16x32_bf16 v[10:13], v[142:145], v[210:213], v[10:13]
	v_mfma_f32_16x16x32_bf16 v[54:57], v[158:161], v[182:185], v[54:57]
	v_mfma_f32_16x16x32_bf16 v[50:53], v[166:169], v[182:185], v[50:53]
	v_mfma_f32_16x16x32_bf16 v[38:41], v[158:161], v[190:193], v[38:41]
	v_mfma_f32_16x16x32_bf16 v[34:37], v[166:169], v[190:193], v[34:37]
	v_mfma_f32_16x16x32_bf16 v[22:25], v[158:161], v[198:201], v[22:25]
	v_mfma_f32_16x16x32_bf16 v[18:21], v[166:169], v[198:201], v[18:21]
	v_mfma_f32_16x16x32_bf16 v[6:9], v[158:161], v[206:209], v[6:9]
	v_mfma_f32_16x16x32_bf16 v[2:5], v[166:169], v[206:209], v[2:5]
	v_mfma_f32_16x16x32_bf16 v[54:57], v[162:165], v[186:189], v[54:57]
	v_mfma_f32_16x16x32_bf16 v[50:53], v[170:173], v[186:189], v[50:53]
	v_mfma_f32_16x16x32_bf16 v[38:41], v[162:165], v[194:197], v[38:41]
	v_mfma_f32_16x16x32_bf16 v[34:37], v[170:173], v[194:197], v[34:37]
	v_mfma_f32_16x16x32_bf16 v[22:25], v[162:165], v[202:205], v[22:25]
	v_mfma_f32_16x16x32_bf16 v[18:21], v[170:173], v[202:205], v[18:21]
	v_mfma_f32_16x16x32_bf16 v[6:9], v[162:165], v[210:213], v[6:9]
	v_mfma_f32_16x16x32_bf16 v[2:5], v[170:173], v[210:213], v[2:5]
	s_setprio 0
	s_barrier
	v_add_u32_e32 v0, s29, v177
	ds_read_b128 v[130:133], v0
	ds_read_b128 v[134:137], v0 offset:1024
	ds_read_b128 v[138:141], v0 offset:2048
	ds_read_b128 v[142:145], v0 offset:3072
	v_add_u32_e32 v0, s26, v177
	ds_read_b128 v[158:161], v0
	ds_read_b128 v[162:165], v0 offset:1024
	ds_read_b128 v[166:169], v0 offset:2048
	ds_read_b128 v[170:173], v0 offset:3072
	s_add_u32 s18, s18, 0x40000
	s_addc_u32 s19, s19, 0
	s_mov_b32 m0, s52
	v_lshl_add_u64 v[232:233], s[18:19], 0, v[146:147]
	ds_read_b128 v[182:185], v180 offset:32768
	ds_read_b128 v[186:189], v180 offset:33792
	ds_read_b128 v[190:193], v180 offset:34816
	ds_read_b128 v[194:197], v180 offset:35840
	ds_read_b128 v[198:201], v180 offset:36864
	ds_read_b128 v[202:205], v180 offset:37888
	ds_read_b128 v[206:209], v180 offset:38912
	ds_read_b128 v[210:213], v180 offset:39936
	global_load_lds_dwordx4 v[232:233], off
	v_lshl_add_u64 v[232:233], s[18:19], 0, v[150:151]
	s_mov_b32 m0, s53
	s_nop 0
	global_load_lds_dwordx4 v[232:233], off
	s_waitcnt vmcnt(8)
	s_waitcnt lgkmcnt(0)
	s_barrier
	s_setprio 1
	s_waitcnt lgkmcnt(0)
	v_mfma_f32_16x16x32_bf16 v[126:129], v[130:133], v[182:185], v[126:129]
	v_mfma_f32_16x16x32_bf16 v[122:125], v[138:141], v[182:185], v[122:125]
	v_mfma_f32_16x16x32_bf16 v[110:113], v[130:133], v[190:193], v[110:113]
	v_mfma_f32_16x16x32_bf16 v[106:109], v[138:141], v[190:193], v[106:109]
	v_mfma_f32_16x16x32_bf16 v[94:97], v[130:133], v[198:201], v[94:97]
	v_mfma_f32_16x16x32_bf16 v[90:93], v[138:141], v[198:201], v[90:93]
	v_mfma_f32_16x16x32_bf16 v[78:81], v[130:133], v[206:209], v[78:81]
	v_mfma_f32_16x16x32_bf16 v[74:77], v[138:141], v[206:209], v[74:77]
	v_mfma_f32_16x16x32_bf16 v[126:129], v[134:137], v[186:189], v[126:129]
	v_mfma_f32_16x16x32_bf16 v[122:125], v[142:145], v[186:189], v[122:125]
	v_mfma_f32_16x16x32_bf16 v[110:113], v[134:137], v[194:197], v[110:113]
	v_mfma_f32_16x16x32_bf16 v[106:109], v[142:145], v[194:197], v[106:109]
	v_mfma_f32_16x16x32_bf16 v[94:97], v[134:137], v[202:205], v[94:97]
	v_mfma_f32_16x16x32_bf16 v[90:93], v[142:145], v[202:205], v[90:93]
	v_mfma_f32_16x16x32_bf16 v[78:81], v[134:137], v[210:213], v[78:81]
	v_mfma_f32_16x16x32_bf16 v[74:77], v[142:145], v[210:213], v[74:77]
	v_mfma_f32_16x16x32_bf16 v[118:121], v[158:161], v[182:185], v[118:121]
	v_mfma_f32_16x16x32_bf16 v[114:117], v[166:169], v[182:185], v[114:117]
	v_mfma_f32_16x16x32_bf16 v[102:105], v[158:161], v[190:193], v[102:105]
	v_mfma_f32_16x16x32_bf16 v[98:101], v[166:169], v[190:193], v[98:101]
	v_mfma_f32_16x16x32_bf16 v[86:89], v[158:161], v[198:201], v[86:89]
	v_mfma_f32_16x16x32_bf16 v[82:85], v[166:169], v[198:201], v[82:85]
	v_mfma_f32_16x16x32_bf16 v[70:73], v[158:161], v[206:209], v[70:73]
	v_mfma_f32_16x16x32_bf16 v[66:69], v[166:169], v[206:209], v[66:69]
	v_mfma_f32_16x16x32_bf16 v[118:121], v[162:165], v[186:189], v[118:121]
	v_mfma_f32_16x16x32_bf16 v[114:117], v[170:173], v[186:189], v[114:117]
	v_mfma_f32_16x16x32_bf16 v[102:105], v[162:165], v[194:197], v[102:105]
	v_mfma_f32_16x16x32_bf16 v[98:101], v[170:173], v[194:197], v[98:101]
	v_mfma_f32_16x16x32_bf16 v[86:89], v[162:165], v[202:205], v[86:89]
	v_mfma_f32_16x16x32_bf16 v[82:85], v[170:173], v[202:205], v[82:85]
	v_mfma_f32_16x16x32_bf16 v[70:73], v[162:165], v[210:213], v[70:73]
	v_mfma_f32_16x16x32_bf16 v[66:69], v[170:173], v[210:213], v[66:69]
	s_setprio 0
	s_barrier
; #define PG8_STAGE(bufoff, gbase, voff) do { _Pragma("unroll") for (int _i = 0; _i < 2; ++_i) \
;         __builtin_amdgcn_global_load_lds((const unsigned*)((const char*)(gbase) + (voff)[_i]), (LAS unsigned*)(lds + (bufoff) + ldsw + _i * 8192), 16, 0, 0); } while (0)
; #define PG8_LDA(dst, b, h) do { _Pragma("unroll") for (int m = 0; m < 4; ++m) _Pragma("unroll") for (int k = 0; k < 2; ++k) dst[m][k] = *(const LAS bf16x8*)(lds + PG8_SA(b, h) + aoff + m * 2048 + k * 1024); } while (0)
; #define PG8_MMA(ai, bj, At, Bt) do { __builtin_amdgcn_s_setprio(1); _Pragma("unroll") for (int m = 0; m < 4; ++m) _Pragma("unroll") for (int n = 0; n < 2; ++n) _Pragma("unroll") for (int k = 0; k < 2; ++k) \
;         acc[ai][bj][m][n] = __builtin_amdgcn_mfma_f32_16x16x32_bf16(Bt[n][k], At[m][k], acc[ai][bj][m][n], 0, 0, 0); __builtin_amdgcn_s_setprio(0); } while (0)
; #define PG8_WAIT_V(n) asm volatile("s_waitcnt vmcnt(" #n ")" ::: "memory")
; #define PG8_WAIT_L(n) asm volatile("s_waitcnt lgkmcnt(" #n ")" ::: "memory")
; #define PG8_BAR __builtin_amdgcn_s_barrier()
; #define PG8_SCHED __builtin_amdgcn_sched_barrier(0)
; template <class Epi, bool ALIGN_EPI, bool ASLOT = false>
; __device__ __forceinline__ void gemm_phase(LAS unsigned char* lds, const Gemm g, const Sched& S, const Epi& E) {
;     ...
;             PG8_LDA(At, 1, 1); PG8_STAGE(PG8_SB(1, 0), b3, voffB); PG8_STAGE(PG8_SB(1, 1), b3 + hstep, voffB); PG8_STAGE(PG8_SA(1, 0), a3, voffA);
;             PG8_WAIT_V(8); PG8_WAIT_L(0); PG8_BAR; PG8_MMA(1, 0, At, B0); PG8_MMA(1, 1, At, B1); PG8_BAR; PG8_SCHED;
;         }
	s_add_i32 s18, s29, s27
	v_lshl_add_u64 v[174:175], v[174:175], 0, s[16:17]
	s_mov_b32 m0, s18
	ds_read_b128 v[182:185], v180 offset:49152
	ds_read_b128 v[186:189], v180 offset:50176
	ds_read_b128 v[190:193], v180 offset:51200
	ds_read_b128 v[194:197], v180 offset:52224
	ds_read_b128 v[198:201], v180 offset:53248
	ds_read_b128 v[202:205], v180 offset:54272
	ds_read_b128 v[206:209], v180 offset:55296
	ds_read_b128 v[210:213], v180 offset:56320
	global_load_lds_dwordx4 v[174:175], off
	s_add_i32 m0, s18, 0x2000
	s_add_u32 s14, s14, 0x40080
	v_lshl_add_u64 v[174:175], v[214:215], 0, s[16:17]
	s_addc_u32 s15, s15, 0
	s_add_i32 s18, s26, s27
	global_load_lds_dwordx4 v[174:175], off
	v_lshl_add_u64 v[174:175], s[14:15], 0, v[148:149]
	s_mov_b32 m0, s18
	s_nop 0
	global_load_lds_dwordx4 v[174:175], off
	v_lshl_add_u64 v[174:175], s[14:15], 0, v[152:153]
	s_add_i32 m0, s18, 0x2000
	s_nop 0
	global_load_lds_dwordx4 v[174:175], off
	v_lshl_add_u64 v[174:175], v[220:221], 0, s[16:17]
	s_mov_b32 m0, s54
	s_nop 0
	global_load_lds_dwordx4 v[174:175], off
	v_lshl_add_u64 v[174:175], v[222:223], 0, s[16:17]
	s_mov_b32 m0, s55
	s_nop 0
	global_load_lds_dwordx4 v[174:175], off
	s_waitcnt vmcnt(8)
	s_waitcnt lgkmcnt(0)
	s_barrier
	s_setprio 1
	s_waitcnt lgkmcnt(0)
	v_mfma_f32_16x16x32_bf16 v[62:65], v[130:133], v[182:185], v[62:65]
	v_mfma_f32_16x16x32_bf16 v[58:61], v[138:141], v[182:185], v[58:61]
	v_mfma_f32_16x16x32_bf16 v[46:49], v[130:133], v[190:193], v[46:49]
	v_mfma_f32_16x16x32_bf16 v[42:45], v[138:141], v[190:193], v[42:45]
	v_mfma_f32_16x16x32_bf16 v[30:33], v[130:133], v[198:201], v[30:33]
	v_mfma_f32_16x16x32_bf16 v[26:29], v[138:141], v[198:201], v[26:29]
	v_mfma_f32_16x16x32_bf16 v[14:17], v[130:133], v[206:209], v[14:17]
	v_mfma_f32_16x16x32_bf16 v[10:13], v[138:141], v[206:209], v[10:13]
	v_mfma_f32_16x16x32_bf16 v[62:65], v[134:137], v[186:189], v[62:65]
	v_mfma_f32_16x16x32_bf16 v[58:61], v[142:145], v[186:189], v[58:61]
	v_mfma_f32_16x16x32_bf16 v[46:49], v[134:137], v[194:197], v[46:49]
	v_mfma_f32_16x16x32_bf16 v[42:45], v[142:145], v[194:197], v[42:45]
	v_mfma_f32_16x16x32_bf16 v[30:33], v[134:137], v[202:205], v[30:33]
	v_mfma_f32_16x16x32_bf16 v[26:29], v[142:145], v[202:205], v[26:29]
	v_mfma_f32_16x16x32_bf16 v[14:17], v[134:137], v[210:213], v[14:17]
	v_mfma_f32_16x16x32_bf16 v[10:13], v[142:145], v[210:213], v[10:13]
	v_mfma_f32_16x16x32_bf16 v[54:57], v[158:161], v[182:185], v[54:57]
	v_mfma_f32_16x16x32_bf16 v[50:53], v[166:169], v[182:185], v[50:53]
	v_mfma_f32_16x16x32_bf16 v[38:41], v[158:161], v[190:193], v[38:41]
	v_mfma_f32_16x16x32_bf16 v[34:37], v[166:169], v[190:193], v[34:37]
	v_mfma_f32_16x16x32_bf16 v[22:25], v[158:161], v[198:201], v[22:25]
	v_mfma_f32_16x16x32_bf16 v[18:21], v[166:169], v[198:201], v[18:21]
	v_mfma_f32_16x16x32_bf16 v[6:9], v[158:161], v[206:209], v[6:9]
	v_mfma_f32_16x16x32_bf16 v[2:5], v[166:169], v[206:209], v[2:5]
	v_mfma_f32_16x16x32_bf16 v[54:57], v[162:165], v[186:189], v[54:57]
	v_mfma_f32_16x16x32_bf16 v[50:53], v[170:173], v[186:189], v[50:53]
	v_mfma_f32_16x16x32_bf16 v[38:41], v[162:165], v[194:197], v[38:41]
	v_mfma_f32_16x16x32_bf16 v[34:37], v[170:173], v[194:197], v[34:37]
	v_mfma_f32_16x16x32_bf16 v[22:25], v[162:165], v[202:205], v[22:25]
	v_mfma_f32_16x16x32_bf16 v[18:21], v[170:173], v[202:205], v[18:21]
	v_mfma_f32_16x16x32_bf16 v[6:9], v[162:165], v[210:213], v[6:9]
	v_mfma_f32_16x16x32_bf16 v[2:5], v[170:173], v[210:213], v[2:5]
	s_setprio 0
	s_barrier
	s_add_i32 s57, s57, 2
	s_add_u32 s0, s0, 0x100
	s_addc_u32 s1, s1, 0
	s_add_u32 s43, s43, 0x100
	s_addc_u32 s45, s45, 0
	s_cmp_gt_u32 s57, 13
	s_cbranch_scc0 .LBB0_300
	s_and_b64 vcc, exec, s[12:13]
	s_cbranch_vccz .LBB0_303
	s_barrier

; #define PG8_STAGE(bufoff, gbase, voff) do { _Pragma("unroll") for (int _i = 0; _i < 2; ++_i) \
;         __builtin_amdgcn_global_load_lds((const unsigned*)((const char*)(gbase) + (voff)[_i]), (LAS unsigned*)(lds + (bufoff) + ldsw + _i * 8192), 16, 0, 0); } while (0)
; #define PG8_LDA(dst, b, h) do { _Pragma("unroll") for (int m = 0; m < 4; ++m) _Pragma("unroll") for (int k = 0; k < 2; ++k) dst[m][k] = *(const LAS bf16x8*)(lds + PG8_SA(b, h) + aoff + m * 2048 + k * 1024); } while (0)
; #define PG8_LDB(dst, b, h) do { _Pragma("unroll") for (int n = 0; n < 2; ++n) _Pragma("unroll") for (int k = 0; k < 2; ++k) dst[n][k] = *(const LAS bf16x8*)(lds + PG8_SB(b, h) + boff + n * 2048 + k * 1024); } while (0)
; #define PG8_MMA(ai, bj, At, Bt) do { __builtin_amdgcn_s_setprio(1); _Pragma("unroll") for (int m = 0; m < 4; ++m) _Pragma("unroll") for (int n = 0; n < 2; ++n) _Pragma("unroll") for (int k = 0; k < 2; ++k) \
;         acc[ai][bj][m][n] = __builtin_amdgcn_mfma_f32_16x16x32_bf16(Bt[n][k], At[m][k], acc[ai][bj][m][n], 0, 0, 0); __builtin_amdgcn_s_setprio(0); } while (0)
; #define PG8_WAIT_V(n) asm volatile("s_waitcnt vmcnt(" #n ")" ::: "memory")
; #define PG8_WAIT_L(n) asm volatile("s_waitcnt lgkmcnt(" #n ")" ::: "memory")
; #define PG8_BAR __builtin_amdgcn_s_barrier()
; #define PG8_SCHED __builtin_amdgcn_sched_barrier(0)
; template <class Epi, bool ALIGN_EPI, bool ASLOT = false>
; __device__ __forceinline__ void gemm_phase(LAS unsigned char* lds, const Gemm g, const Sched& S, const Epi& E) {
;     ...
;         for (int t = 0; t < nt; t += 2) {
;             const bool last = (t == nt - 2);
;             const char* a1 = cA + (size_t)(t + 1) * kstep;
;             const char* a2 = last ? nA : cA + (size_t)(t + 2) * kstep; const char* b2 = last ? nB : cB + (size_t)(t + 2) * kstep;
;             const char* a3 = a2 + kstep; const char* b3 = b2 + kstep;
;             PG8_LDB(B0, 0, 0); PG8_LDB(B1, 0, 1); PG8_SCHED; PG8_LDA(At, 0, 0); PG8_STAGE(PG8_SA(1, 1), a1 + hstep, voffA);
;             PG8_WAIT_V(8); PG8_WAIT_L(0); PG8_BAR; PG8_MMA(0, 0, At, B0); PG8_MMA(0, 1, At, B1); PG8_BAR; PG8_SCHED;
;             PG8_LDA(At, 0, 1); PG8_STAGE(PG8_SB(0, 0), b2, voffB); PG8_STAGE(PG8_SB(0, 1), b2 + hstep, voffB); PG8_STAGE(PG8_SA(0, 0), a2, voffA);
;             PG8_WAIT_V(8); PG8_WAIT_L(0); PG8_BAR; PG8_MMA(1, 0, At, B0); PG8_MMA(1, 1, At, B1); PG8_BAR; PG8_SCHED;
.Lbr_keep_acc:
.LBB0_664:
	v_add_u32_e32 v148, s28, v151
	ds_read_b128 v[140:143], v148
	ds_read_b128 v[144:147], v148 offset:1024
	ds_read_b128 v[154:157], v148 offset:2048
	ds_read_b128 v[158:161], v148 offset:3072
	v_add_u32_e32 v148, s33, v151
	ds_read_b128 v[162:165], v148
	ds_read_b128 v[166:169], v148 offset:1024
	ds_read_b128 v[170:173], v148 offset:2048
	ds_read_b128 v[174:177], v148 offset:3072
	s_add_u32 s18, s36, 0xfffe0080
	s_addc_u32 s19, s37, -1
	s_cmp_eq_u32 s40, 4
	s_cselect_b32 s21, s13, s19
	s_cselect_b32 s20, s15, s18
	s_cselect_b32 s19, s9, s25
	s_cselect_b32 s18, s11, s24
	v_lshl_add_u64 v[148:149], s[36:37], 0, v[136:137]
	s_add_i32 m0, s51, 0xc000
	ds_read_b128 v[178:181], v153
	ds_read_b128 v[182:185], v153 offset:1024
	ds_read_b128 v[186:189], v153 offset:2048
	ds_read_b128 v[190:193], v153 offset:3072
	ds_read_b128 v[194:197], v153 offset:4096
	ds_read_b128 v[198:201], v153 offset:5120
	ds_read_b128 v[202:205], v153 offset:6144
	ds_read_b128 v[206:209], v153 offset:7168
	global_load_lds_dwordx4 v[148:149], off
	v_lshl_add_u64 v[148:149], s[36:37], 0, v[138:139]
	s_add_i32 m0, s51, 0xe000
	s_nop 0
	global_load_lds_dwordx4 v[148:149], off
	s_waitcnt vmcnt(8)
	s_waitcnt lgkmcnt(0)
	s_barrier
	s_setprio 1
	s_waitcnt lgkmcnt(0)
	v_mfma_f32_16x16x32_bf16 v[126:129], v[140:143], v[178:181], v[126:129]
	v_mfma_f32_16x16x32_bf16 v[122:125], v[154:157], v[178:181], v[122:125]
	v_mfma_f32_16x16x32_bf16 v[110:113], v[140:143], v[186:189], v[110:113]
	v_mfma_f32_16x16x32_bf16 v[106:109], v[154:157], v[186:189], v[106:109]
	v_mfma_f32_16x16x32_bf16 v[94:97], v[140:143], v[194:197], v[94:97]
	v_mfma_f32_16x16x32_bf16 v[90:93], v[154:157], v[194:197], v[90:93]
	v_mfma_f32_16x16x32_bf16 v[78:81], v[140:143], v[202:205], v[78:81]
	v_mfma_f32_16x16x32_bf16 v[74:77], v[154:157], v[202:205], v[74:77]
	v_mfma_f32_16x16x32_bf16 v[126:129], v[144:147], v[182:185], v[126:129]
	v_mfma_f32_16x16x32_bf16 v[122:125], v[158:161], v[182:185], v[122:125]
	v_mfma_f32_16x16x32_bf16 v[110:113], v[144:147], v[190:193], v[110:113]
	v_mfma_f32_16x16x32_bf16 v[106:109], v[158:161], v[190:193], v[106:109]
	v_mfma_f32_16x16x32_bf16 v[94:97], v[144:147], v[198:201], v[94:97]
	v_mfma_f32_16x16x32_bf16 v[90:93], v[158:161], v[198:201], v[90:93]
	v_mfma_f32_16x16x32_bf16 v[78:81], v[144:147], v[206:209], v[78:81]
	v_mfma_f32_16x16x32_bf16 v[74:77], v[158:161], v[206:209], v[74:77]
	v_mfma_f32_16x16x32_bf16 v[118:121], v[162:165], v[178:181], v[118:121]
	v_mfma_f32_16x16x32_bf16 v[114:117], v[170:173], v[178:181], v[114:117]
	v_mfma_f32_16x16x32_bf16 v[102:105], v[162:165], v[186:189], v[102:105]
	v_mfma_f32_16x16x32_bf16 v[98:101], v[170:173], v[186:189], v[98:101]
	v_mfma_f32_16x16x32_bf16 v[86:89], v[162:165], v[194:197], v[86:89]
	v_mfma_f32_16x16x32_bf16 v[82:85], v[170:173], v[194:197], v[82:85]
	v_mfma_f32_16x16x32_bf16 v[70:73], v[162:165], v[202:205], v[70:73]
	v_mfma_f32_16x16x32_bf16 v[66:69], v[170:173], v[202:205], v[66:69]
	v_mfma_f32_16x16x32_bf16 v[118:121], v[166:169], v[182:185], v[118:121]
	v_mfma_f32_16x16x32_bf16 v[114:117], v[174:177], v[182:185], v[114:117]
	v_mfma_f32_16x16x32_bf16 v[102:105], v[166:169], v[190:193], v[102:105]
	v_mfma_f32_16x16x32_bf16 v[98:101], v[174:177], v[190:193], v[98:101]
	v_mfma_f32_16x16x32_bf16 v[86:89], v[166:169], v[198:201], v[86:89]
	v_mfma_f32_16x16x32_bf16 v[82:85], v[174:177], v[198:201], v[82:85]
	v_mfma_f32_16x16x32_bf16 v[70:73], v[166:169], v[206:209], v[70:73]
	v_mfma_f32_16x16x32_bf16 v[66:69], v[174:177], v[206:209], v[66:69]
	s_setprio 0
	s_barrier
	s_add_i32 s22, s28, s50
	v_lshl_add_u64 v[148:149], s[18:19], 0, v[0:1]
	s_mov_b32 m0, s22
	ds_read_b128 v[178:181], v153 offset:16384
	ds_read_b128 v[182:185], v153 offset:17408
	ds_read_b128 v[186:189], v153 offset:18432
	ds_read_b128 v[190:193], v153 offset:19456
	ds_read_b128 v[194:197], v153 offset:20480
	ds_read_b128 v[198:201], v153 offset:21504
	ds_read_b128 v[202:205], v153 offset:22528
	ds_read_b128 v[206:209], v153 offset:23552
	global_load_lds_dwordx4 v[148:149], off
	s_add_i32 m0, s22, 0x2000
	s_add_u32 s22, s18, 0x20000
	v_lshl_add_u64 v[210:211], s[18:19], 0, v[134:135]
	s_addc_u32 s23, s19, 0
	s_add_i32 s30, s33, s50
	global_load_lds_dwordx4 v[210:211], off
	v_lshl_add_u64 v[212:213], s[22:23], 0, v[0:1]
	s_mov_b32 m0, s30
	v_lshl_add_u64 v[214:215], s[20:21], 0, v[132:133]
	global_load_lds_dwordx4 v[212:213], off
	v_lshl_add_u64 v[212:213], s[22:23], 0, v[134:135]
	s_add_i32 m0, s30, 0x2000
	s_nop 0
	global_load_lds_dwordx4 v[212:213], off
	v_lshl_add_u64 v[212:213], s[20:21], 0, v[130:131]
	s_mov_b32 m0, s51
	s_nop 0
	global_load_lds_dwordx4 v[212:213], off
	s_mov_b32 m0, s52
	s_nop 0
	global_load_lds_dwordx4 v[214:215], off
	s_waitcnt vmcnt(8)
	s_waitcnt lgkmcnt(0)
	s_barrier
; #define PG8_STAGE(bufoff, gbase, voff) do { _Pragma("unroll") for (int _i = 0; _i < 2; ++_i) \
;         __builtin_amdgcn_global_load_lds((const unsigned*)((const char*)(gbase) + (voff)[_i]), (LAS unsigned*)(lds + (bufoff) + ldsw + _i * 8192), 16, 0, 0); } while (0)
; #define PG8_LDA(dst, b, h) do { _Pragma("unroll") for (int m = 0; m < 4; ++m) _Pragma("unroll") for (int k = 0; k < 2; ++k) dst[m][k] = *(const LAS bf16x8*)(lds + PG8_SA(b, h) + aoff + m * 2048 + k * 1024); } while (0)
; #define PG8_LDB(dst, b, h) do { _Pragma("unroll") for (int n = 0; n < 2; ++n) _Pragma("unroll") for (int k = 0; k < 2; ++k) dst[n][k] = *(const LAS bf16x8*)(lds + PG8_SB(b, h) + boff + n * 2048 + k * 1024); } while (0)
; #define PG8_MMA(ai, bj, At, Bt) do { __builtin_amdgcn_s_setprio(1); _Pragma("unroll") for (int m = 0; m < 4; ++m) _Pragma("unroll") for (int n = 0; n < 2; ++n) _Pragma("unroll") for (int k = 0; k < 2; ++k) \
;         acc[ai][bj][m][n] = __builtin_amdgcn_mfma_f32_16x16x32_bf16(Bt[n][k], At[m][k], acc[ai][bj][m][n], 0, 0, 0); __builtin_amdgcn_s_setprio(0); } while (0)
; #define PG8_WAIT_V(n) asm volatile("s_waitcnt vmcnt(" #n ")" ::: "memory")
; #define PG8_WAIT_L(n) asm volatile("s_waitcnt lgkmcnt(" #n ")" ::: "memory")
; #define PG8_BAR __builtin_amdgcn_s_barrier()
; #define PG8_SCHED __builtin_amdgcn_sched_barrier(0)
; template <class Epi, bool ALIGN_EPI, bool ASLOT = false>
; __device__ __forceinline__ void gemm_phase(LAS unsigned char* lds, const Gemm g, const Sched& S, const Epi& E) {
;     ...
;             PG8_WAIT_V(8); PG8_WAIT_L(0); PG8_BAR; PG8_MMA(1, 0, At, B0); PG8_MMA(1, 1, At, B1); PG8_BAR; PG8_SCHED;
;             PG8_LDB(B0, 1, 0); PG8_LDB(B1, 1, 1); PG8_SCHED; PG8_LDA(At, 1, 0); PG8_STAGE(PG8_SA(0, 1), a2 + hstep, voffA);
;             PG8_WAIT_V(8); PG8_WAIT_L(0); PG8_BAR; PG8_MMA(0, 0, At, B0); PG8_MMA(0, 1, At, B1); PG8_BAR; PG8_SCHED;
	s_setprio 1
	s_waitcnt lgkmcnt(0)
	v_mfma_f32_16x16x32_bf16 v[62:65], v[140:143], v[178:181], v[62:65]
	v_mfma_f32_16x16x32_bf16 v[58:61], v[154:157], v[178:181], v[58:61]
	v_mfma_f32_16x16x32_bf16 v[46:49], v[140:143], v[186:189], v[46:49]
	v_mfma_f32_16x16x32_bf16 v[42:45], v[154:157], v[186:189], v[42:45]
	v_mfma_f32_16x16x32_bf16 v[30:33], v[140:143], v[194:197], v[30:33]
	v_mfma_f32_16x16x32_bf16 v[26:29], v[154:157], v[194:197], v[26:29]
	v_mfma_f32_16x16x32_bf16 v[14:17], v[140:143], v[202:205], v[14:17]
	v_mfma_f32_16x16x32_bf16 v[10:13], v[154:157], v[202:205], v[10:13]
	v_mfma_f32_16x16x32_bf16 v[62:65], v[144:147], v[182:185], v[62:65]
	v_mfma_f32_16x16x32_bf16 v[58:61], v[158:161], v[182:185], v[58:61]
	v_mfma_f32_16x16x32_bf16 v[46:49], v[144:147], v[190:193], v[46:49]
	v_mfma_f32_16x16x32_bf16 v[42:45], v[158:161], v[190:193], v[42:45]
	v_mfma_f32_16x16x32_bf16 v[30:33], v[144:147], v[198:201], v[30:33]
	v_mfma_f32_16x16x32_bf16 v[26:29], v[158:161], v[198:201], v[26:29]
	v_mfma_f32_16x16x32_bf16 v[14:17], v[144:147], v[206:209], v[14:17]
	v_mfma_f32_16x16x32_bf16 v[10:13], v[158:161], v[206:209], v[10:13]
	v_mfma_f32_16x16x32_bf16 v[54:57], v[162:165], v[178:181], v[54:57]
	v_mfma_f32_16x16x32_bf16 v[50:53], v[170:173], v[178:181], v[50:53]
	v_mfma_f32_16x16x32_bf16 v[38:41], v[162:165], v[186:189], v[38:41]
	v_mfma_f32_16x16x32_bf16 v[34:37], v[170:173], v[186:189], v[34:37]
	v_mfma_f32_16x16x32_bf16 v[22:25], v[162:165], v[194:197], v[22:25]
	v_mfma_f32_16x16x32_bf16 v[18:21], v[170:173], v[194:197], v[18:21]
	v_mfma_f32_16x16x32_bf16 v[6:9], v[162:165], v[202:205], v[6:9]
	v_mfma_f32_16x16x32_bf16 v[2:5], v[170:173], v[202:205], v[2:5]
	v_mfma_f32_16x16x32_bf16 v[54:57], v[166:169], v[182:185], v[54:57]
	v_mfma_f32_16x16x32_bf16 v[50:53], v[174:177], v[182:185], v[50:53]
	v_mfma_f32_16x16x32_bf16 v[38:41], v[166:169], v[190:193], v[38:41]
	v_mfma_f32_16x16x32_bf16 v[34:37], v[174:177], v[190:193], v[34:37]
	v_mfma_f32_16x16x32_bf16 v[22:25], v[166:169], v[198:201], v[22:25]
	v_mfma_f32_16x16x32_bf16 v[18:21], v[174:177], v[198:201], v[18:21]
	v_mfma_f32_16x16x32_bf16 v[6:9], v[166:169], v[206:209], v[6:9]
	v_mfma_f32_16x16x32_bf16 v[2:5], v[174:177], v[206:209], v[2:5]
	s_setprio 0
	s_barrier
	v_add_u32_e32 v158, s29, v151
	v_add_u32_e32 v174, s26, v151
	ds_read_b128 v[140:143], v158
	ds_read_b128 v[144:147], v158 offset:1024
	ds_read_b128 v[154:157], v158 offset:2048
	ds_read_b128 v[158:161], v158 offset:3072
	ds_read_b128 v[162:165], v174
	ds_read_b128 v[166:169], v174 offset:1024
	ds_read_b128 v[170:173], v174 offset:2048
	ds_read_b128 v[174:177], v174 offset:3072
	s_add_u32 s20, s20, 0x20000
	s_addc_u32 s21, s21, 0
	s_mov_b32 m0, s53
	v_lshl_add_u64 v[220:221], s[20:21], 0, v[130:131]
	ds_read_b128 v[178:181], v153 offset:32768
	ds_read_b128 v[182:185], v153 offset:33792
	ds_read_b128 v[186:189], v153 offset:34816
	ds_read_b128 v[190:193], v153 offset:35840
	ds_read_b128 v[194:197], v153 offset:36864
	ds_read_b128 v[198:201], v153 offset:37888
	ds_read_b128 v[202:205], v153 offset:38912
	ds_read_b128 v[206:209], v153 offset:39936
	global_load_lds_dwordx4 v[220:221], off
	v_lshl_add_u64 v[220:221], s[20:21], 0, v[132:133]
	s_mov_b32 m0, s54
	s_nop 0
	global_load_lds_dwordx4 v[220:221], off
	s_waitcnt vmcnt(8)
	s_waitcnt lgkmcnt(0)
	s_barrier
	s_setprio 1
	s_waitcnt lgkmcnt(0)
	v_mfma_f32_16x16x32_bf16 v[126:129], v[140:143], v[178:181], v[126:129]
	v_mfma_f32_16x16x32_bf16 v[122:125], v[154:157], v[178:181], v[122:125]
	v_mfma_f32_16x16x32_bf16 v[110:113], v[140:143], v[186:189], v[110:113]
	v_mfma_f32_16x16x32_bf16 v[106:109], v[154:157], v[186:189], v[106:109]
	v_mfma_f32_16x16x32_bf16 v[94:97], v[140:143], v[194:197], v[94:97]
	v_mfma_f32_16x16x32_bf16 v[90:93], v[154:157], v[194:197], v[90:93]
	v_mfma_f32_16x16x32_bf16 v[78:81], v[140:143], v[202:205], v[78:81]
	v_mfma_f32_16x16x32_bf16 v[74:77], v[154:157], v[202:205], v[74:77]
	v_mfma_f32_16x16x32_bf16 v[126:129], v[144:147], v[182:185], v[126:129]
	v_mfma_f32_16x16x32_bf16 v[122:125], v[158:161], v[182:185], v[122:125]
	v_mfma_f32_16x16x32_bf16 v[110:113], v[144:147], v[190:193], v[110:113]
	v_mfma_f32_16x16x32_bf16 v[106:109], v[158:161], v[190:193], v[106:109]
	v_mfma_f32_16x16x32_bf16 v[94:97], v[144:147], v[198:201], v[94:97]
	v_mfma_f32_16x16x32_bf16 v[90:93], v[158:161], v[198:201], v[90:93]
	v_mfma_f32_16x16x32_bf16 v[78:81], v[144:147], v[206:209], v[78:81]
	v_mfma_f32_16x16x32_bf16 v[74:77], v[158:161], v[206:209], v[74:77]
	v_mfma_f32_16x16x32_bf16 v[118:121], v[162:165], v[178:181], v[118:121]
	v_mfma_f32_16x16x32_bf16 v[114:117], v[170:173], v[178:181], v[114:117]
	v_mfma_f32_16x16x32_bf16 v[102:105], v[162:165], v[186:189], v[102:105]
	v_mfma_f32_16x16x32_bf16 v[98:101], v[170:173], v[186:189], v[98:101]
	v_mfma_f32_16x16x32_bf16 v[86:89], v[162:165], v[194:197], v[86:89]
	v_mfma_f32_16x16x32_bf16 v[82:85], v[170:173], v[194:197], v[82:85]
	v_mfma_f32_16x16x32_bf16 v[70:73], v[162:165], v[202:205], v[70:73]
	v_mfma_f32_16x16x32_bf16 v[66:69], v[170:173], v[202:205], v[66:69]
	v_mfma_f32_16x16x32_bf16 v[118:121], v[166:169], v[182:185], v[118:121]
	v_mfma_f32_16x16x32_bf16 v[114:117], v[174:177], v[182:185], v[114:117]
	v_mfma_f32_16x16x32_bf16 v[102:105], v[166:169], v[190:193], v[102:105]
	v_mfma_f32_16x16x32_bf16 v[98:101], v[174:177], v[190:193], v[98:101]
	v_mfma_f32_16x16x32_bf16 v[86:89], v[166:169], v[198:201], v[86:89]
	v_mfma_f32_16x16x32_bf16 v[82:85], v[174:177], v[198:201], v[82:85]
	v_mfma_f32_16x16x32_bf16 v[70:73], v[166:169], v[206:209], v[70:73]
	v_mfma_f32_16x16x32_bf16 v[66:69], v[174:177], v[206:209], v[66:69]
	s_setprio 0
	s_barrier
; #define PG8_STAGE(bufoff, gbase, voff) do { _Pragma("unroll") for (int _i = 0; _i < 2; ++_i) \
;         __builtin_amdgcn_global_load_lds((const unsigned*)((const char*)(gbase) + (voff)[_i]), (LAS unsigned*)(lds + (bufoff) + ldsw + _i * 8192), 16, 0, 0); } while (0)
; #define PG8_LDA(dst, b, h) do { _Pragma("unroll") for (int m = 0; m < 4; ++m) _Pragma("unroll") for (int k = 0; k < 2; ++k) dst[m][k] = *(const LAS bf16x8*)(lds + PG8_SA(b, h) + aoff + m * 2048 + k * 1024); } while (0)
; #define PG8_MMA(ai, bj, At, Bt) do { __builtin_amdgcn_s_setprio(1); _Pragma("unroll") for (int m = 0; m < 4; ++m) _Pragma("unroll") for (int n = 0; n < 2; ++n) _Pragma("unroll") for (int k = 0; k < 2; ++k) \
;         acc[ai][bj][m][n] = __builtin_amdgcn_mfma_f32_16x16x32_bf16(Bt[n][k], At[m][k], acc[ai][bj][m][n], 0, 0, 0); __builtin_amdgcn_s_setprio(0); } while (0)
; #define PG8_WAIT_V(n) asm volatile("s_waitcnt vmcnt(" #n ")" ::: "memory")
; #define PG8_WAIT_L(n) asm volatile("s_waitcnt lgkmcnt(" #n ")" ::: "memory")
; #define PG8_BAR __builtin_amdgcn_s_barrier()
; #define PG8_SCHED __builtin_amdgcn_sched_barrier(0)
; template <class Epi, bool ALIGN_EPI, bool ASLOT = false>
; __device__ __forceinline__ void gemm_phase(LAS unsigned char* lds, const Gemm g, const Sched& S, const Epi& E) {
;     ...
;             PG8_LDA(At, 1, 1); PG8_STAGE(PG8_SB(1, 0), b3, voffB); PG8_STAGE(PG8_SB(1, 1), b3 + hstep, voffB); PG8_STAGE(PG8_SA(1, 0), a3, voffA);
;             PG8_WAIT_V(8); PG8_WAIT_L(0); PG8_BAR; PG8_MMA(1, 0, At, B0); PG8_MMA(1, 1, At, B1); PG8_BAR; PG8_SCHED;
;         }
	s_add_i32 s20, s29, s50
	v_lshl_add_u64 v[148:149], v[148:149], 0, s[16:17]
	s_mov_b32 m0, s20
	ds_read_b128 v[178:181], v153 offset:49152
	ds_read_b128 v[182:185], v153 offset:50176
	ds_read_b128 v[186:189], v153 offset:51200
	ds_read_b128 v[190:193], v153 offset:52224
	ds_read_b128 v[194:197], v153 offset:53248
	ds_read_b128 v[198:201], v153 offset:54272
	ds_read_b128 v[202:205], v153 offset:55296
	ds_read_b128 v[206:209], v153 offset:56320
	global_load_lds_dwordx4 v[148:149], off
	s_add_i32 m0, s20, 0x2000
	s_add_u32 s18, s18, 0x20080
	v_lshl_add_u64 v[148:149], v[210:211], 0, s[16:17]
	s_addc_u32 s19, s19, 0
	s_add_i32 s20, s26, s50
	global_load_lds_dwordx4 v[148:149], off
	v_lshl_add_u64 v[148:149], s[18:19], 0, v[0:1]
	s_mov_b32 m0, s20
	s_nop 0
	global_load_lds_dwordx4 v[148:149], off
	v_lshl_add_u64 v[148:149], s[18:19], 0, v[134:135]
	s_add_i32 m0, s20, 0x2000
	s_nop 0
	global_load_lds_dwordx4 v[148:149], off
	v_lshl_add_u64 v[148:149], v[212:213], 0, s[16:17]
	s_mov_b32 m0, s55
	s_nop 0
	global_load_lds_dwordx4 v[148:149], off
	v_lshl_add_u64 v[148:149], v[214:215], 0, s[16:17]
	s_mov_b32 m0, s56
	s_nop 0
	global_load_lds_dwordx4 v[148:149], off
	s_waitcnt vmcnt(8)
	s_waitcnt lgkmcnt(0)
	s_barrier
	s_setprio 1
	s_waitcnt lgkmcnt(0)
	v_mfma_f32_16x16x32_bf16 v[62:65], v[140:143], v[178:181], v[62:65]
	v_mfma_f32_16x16x32_bf16 v[58:61], v[154:157], v[178:181], v[58:61]
	v_mfma_f32_16x16x32_bf16 v[46:49], v[140:143], v[186:189], v[46:49]
	v_mfma_f32_16x16x32_bf16 v[42:45], v[154:157], v[186:189], v[42:45]
	v_mfma_f32_16x16x32_bf16 v[30:33], v[140:143], v[194:197], v[30:33]
	v_mfma_f32_16x16x32_bf16 v[26:29], v[154:157], v[194:197], v[26:29]
	v_mfma_f32_16x16x32_bf16 v[14:17], v[140:143], v[202:205], v[14:17]
	v_mfma_f32_16x16x32_bf16 v[10:13], v[154:157], v[202:205], v[10:13]
	v_mfma_f32_16x16x32_bf16 v[62:65], v[144:147], v[182:185], v[62:65]
	v_mfma_f32_16x16x32_bf16 v[58:61], v[158:161], v[182:185], v[58:61]
	v_mfma_f32_16x16x32_bf16 v[46:49], v[144:147], v[190:193], v[46:49]
	v_mfma_f32_16x16x32_bf16 v[42:45], v[158:161], v[190:193], v[42:45]
	v_mfma_f32_16x16x32_bf16 v[30:33], v[144:147], v[198:201], v[30:33]
	v_mfma_f32_16x16x32_bf16 v[26:29], v[158:161], v[198:201], v[26:29]
	v_mfma_f32_16x16x32_bf16 v[14:17], v[144:147], v[206:209], v[14:17]
	v_mfma_f32_16x16x32_bf16 v[10:13], v[158:161], v[206:209], v[10:13]
	v_mfma_f32_16x16x32_bf16 v[54:57], v[162:165], v[178:181], v[54:57]
	v_mfma_f32_16x16x32_bf16 v[50:53], v[170:173], v[178:181], v[50:53]
	v_mfma_f32_16x16x32_bf16 v[38:41], v[162:165], v[186:189], v[38:41]
	v_mfma_f32_16x16x32_bf16 v[34:37], v[170:173], v[186:189], v[34:37]
	v_mfma_f32_16x16x32_bf16 v[22:25], v[162:165], v[194:197], v[22:25]
	v_mfma_f32_16x16x32_bf16 v[18:21], v[170:173], v[194:197], v[18:21]
	v_mfma_f32_16x16x32_bf16 v[6:9], v[162:165], v[202:205], v[6:9]
	v_mfma_f32_16x16x32_bf16 v[2:5], v[170:173], v[202:205], v[2:5]
	v_mfma_f32_16x16x32_bf16 v[54:57], v[166:169], v[182:185], v[54:57]
	v_mfma_f32_16x16x32_bf16 v[50:53], v[174:177], v[182:185], v[50:53]
	v_mfma_f32_16x16x32_bf16 v[38:41], v[166:169], v[190:193], v[38:41]
	v_mfma_f32_16x16x32_bf16 v[34:37], v[174:177], v[190:193], v[34:37]
	v_mfma_f32_16x16x32_bf16 v[22:25], v[166:169], v[198:201], v[22:25]
	v_mfma_f32_16x16x32_bf16 v[18:21], v[174:177], v[198:201], v[18:21]
	v_mfma_f32_16x16x32_bf16 v[6:9], v[166:169], v[206:209], v[6:9]
	v_mfma_f32_16x16x32_bf16 v[2:5], v[174:177], v[206:209], v[2:5]
	s_setprio 0
	s_barrier
	s_add_i32 s40, s40, 2
	s_add_u32 s36, s36, 0x100
	s_addc_u32 s37, s37, 0
	s_add_u32 s24, s24, 0x100
	s_addc_u32 s25, s25, 0
	s_cmp_gt_u32 s40, 5
	s_cbranch_scc0 .LBB0_664
	s_and_b64 vcc, exec, s[6:7]
	s_cbranch_vccz .LBB0_667
	s_barrier

; #define PG8_STAGE(bufoff, gbase, voff) do { _Pragma("unroll") for (int _i = 0; _i < 2; ++_i) \
;         __builtin_amdgcn_global_load_lds((const unsigned*)((const char*)(gbase) + (voff)[_i]), (LAS unsigned*)(lds + (bufoff) + ldsw + _i * 8192), 16, 0, 0); } while (0)
; #define PG8_LDA(dst, b, h) do { _Pragma("unroll") for (int m = 0; m < 4; ++m) _Pragma("unroll") for (int k = 0; k < 2; ++k) dst[m][k] = *(const LAS bf16x8*)(lds + PG8_SA(b, h) + aoff + m * 2048 + k * 1024); } while (0)
; #define PG8_LDB(dst, b, h) do { _Pragma("unroll") for (int n = 0; n < 2; ++n) _Pragma("unroll") for (int k = 0; k < 2; ++k) dst[n][k] = *(const LAS bf16x8*)(lds + PG8_SB(b, h) + boff + n * 2048 + k * 1024); } while (0)
; #define PG8_MMA(ai, bj, At, Bt) do { __builtin_amdgcn_s_setprio(1); _Pragma("unroll") for (int m = 0; m < 4; ++m) _Pragma("unroll") for (int n = 0; n < 2; ++n) _Pragma("unroll") for (int k = 0; k < 2; ++k) \
;         acc[ai][bj][m][n] = __builtin_amdgcn_mfma_f32_16x16x32_bf16(Bt[n][k], At[m][k], acc[ai][bj][m][n], 0, 0, 0); __builtin_amdgcn_s_setprio(0); } while (0)
; #define PG8_WAIT_V(n) asm volatile("s_waitcnt vmcnt(" #n ")" ::: "memory")
; #define PG8_WAIT_L(n) asm volatile("s_waitcnt lgkmcnt(" #n ")" ::: "memory")
; #define PG8_BAR __builtin_amdgcn_s_barrier()
; #define PG8_SCHED __builtin_amdgcn_sched_barrier(0)
; template <class Epi, bool ALIGN_EPI, bool ASLOT = false>
; __device__ __forceinline__ void gemm_phase(LAS unsigned char* lds, const Gemm g, const Sched& S, const Epi& E) {
;     ...
;         for (int t = 0; t < nt; t += 2) {
;             const bool last = (t == nt - 2);
;             const char* a1 = cA + (size_t)(t + 1) * kstep;
;             const char* a2 = last ? nA : cA + (size_t)(t + 2) * kstep; const char* b2 = last ? nB : cB + (size_t)(t + 2) * kstep;
;             const char* a3 = a2 + kstep; const char* b3 = b2 + kstep;
;             PG8_LDB(B0, 0, 0); PG8_LDB(B1, 0, 1); PG8_SCHED; PG8_LDA(At, 0, 0); PG8_STAGE(PG8_SA(1, 1), a1 + hstep, voffA);
;             PG8_WAIT_V(8); PG8_WAIT_L(0); PG8_BAR; PG8_MMA(0, 0, At, B0); PG8_MMA(0, 1, At, B1); PG8_BAR; PG8_SCHED;
;             PG8_LDA(At, 0, 1); PG8_STAGE(PG8_SB(0, 0), b2, voffB); PG8_STAGE(PG8_SB(0, 1), b2 + hstep, voffB); PG8_STAGE(PG8_SA(0, 0), a2, voffA);
;             PG8_WAIT_V(8); PG8_WAIT_L(0); PG8_BAR; PG8_MMA(1, 0, At, B0); PG8_MMA(1, 1, At, B1); PG8_BAR; PG8_SCHED;
.LBB0_783:
	v_add_u32_e32 v156, s28, v142
	v_add_u32_e32 v172, s33, v142
	s_add_u32 s6, s30, s4
	ds_read_b128 v[144:147], v156
	ds_read_b128 v[148:151], v156 offset:1024
	ds_read_b128 v[152:155], v156 offset:2048
	ds_read_b128 v[156:159], v156 offset:3072
	ds_read_b128 v[160:163], v172
	ds_read_b128 v[164:167], v172 offset:1024
	ds_read_b128 v[168:171], v172 offset:2048
	ds_read_b128 v[172:175], v172 offset:3072
	s_addc_u32 s7, s38, s5
	s_add_u32 s6, s6, 0x4800100
	s_addc_u32 s7, s7, 0
	s_add_u32 s22, s19, s4
	s_addc_u32 s23, s20, s5
	s_cmpk_eq_i32 s4, 0x700
	s_cselect_b32 s9, s37, s7
	s_cselect_b32 s8, s36, s6
	s_cselect_b32 s7, s1, s23
	s_cselect_b32 s6, s0, s22
	v_lshl_add_u64 v[208:209], v[136:137], 0, s[4:5]
	s_add_i32 m0, s10, 0xc000
	ds_read_b128 v[176:179], v143
	ds_read_b128 v[180:183], v143 offset:1024
	ds_read_b128 v[184:187], v143 offset:2048
	ds_read_b128 v[188:191], v143 offset:3072
	ds_read_b128 v[192:195], v143 offset:4096
	ds_read_b128 v[196:199], v143 offset:5120
	ds_read_b128 v[200:203], v143 offset:6144
	ds_read_b128 v[204:207], v143 offset:7168
	global_load_lds_dwordx4 v[208:209], off
	v_lshl_add_u64 v[208:209], v[138:139], 0, s[4:5]
	s_add_i32 m0, s10, 0xe000
	s_nop 0
	global_load_lds_dwordx4 v[208:209], off
	s_waitcnt vmcnt(8)
	s_waitcnt lgkmcnt(0)
	s_barrier
	s_setprio 1
	s_waitcnt lgkmcnt(0)
	v_mfma_f32_16x16x32_bf16 v[126:129], v[144:147], v[176:179], v[126:129]
	v_mfma_f32_16x16x32_bf16 v[122:125], v[152:155], v[176:179], v[122:125]
	v_mfma_f32_16x16x32_bf16 v[118:121], v[144:147], v[184:187], v[118:121]
	v_mfma_f32_16x16x32_bf16 v[114:117], v[152:155], v[184:187], v[114:117]
	v_mfma_f32_16x16x32_bf16 v[102:105], v[144:147], v[192:195], v[102:105]
	v_mfma_f32_16x16x32_bf16 v[98:101], v[152:155], v[192:195], v[98:101]
	v_mfma_f32_16x16x32_bf16 v[86:89], v[144:147], v[200:203], v[86:89]
	v_mfma_f32_16x16x32_bf16 v[82:85], v[152:155], v[200:203], v[82:85]
	v_mfma_f32_16x16x32_bf16 v[126:129], v[148:151], v[180:183], v[126:129]
	v_mfma_f32_16x16x32_bf16 v[122:125], v[156:159], v[180:183], v[122:125]
	v_mfma_f32_16x16x32_bf16 v[118:121], v[148:151], v[188:191], v[118:121]
	v_mfma_f32_16x16x32_bf16 v[114:117], v[156:159], v[188:191], v[114:117]
	v_mfma_f32_16x16x32_bf16 v[102:105], v[148:151], v[196:199], v[102:105]
	v_mfma_f32_16x16x32_bf16 v[98:101], v[156:159], v[196:199], v[98:101]
	v_mfma_f32_16x16x32_bf16 v[86:89], v[148:151], v[204:207], v[86:89]
	v_mfma_f32_16x16x32_bf16 v[82:85], v[156:159], v[204:207], v[82:85]
	v_mfma_f32_16x16x32_bf16 v[110:113], v[160:163], v[176:179], v[110:113]
	v_mfma_f32_16x16x32_bf16 v[106:109], v[168:171], v[176:179], v[106:109]
	v_mfma_f32_16x16x32_bf16 v[94:97], v[160:163], v[184:187], v[94:97]
	v_mfma_f32_16x16x32_bf16 v[90:93], v[168:171], v[184:187], v[90:93]
	v_mfma_f32_16x16x32_bf16 v[78:81], v[160:163], v[192:195], v[78:81]
	v_mfma_f32_16x16x32_bf16 v[74:77], v[168:171], v[192:195], v[74:77]
	v_mfma_f32_16x16x32_bf16 v[70:73], v[160:163], v[200:203], v[70:73]
	v_mfma_f32_16x16x32_bf16 v[66:69], v[168:171], v[200:203], v[66:69]
	v_mfma_f32_16x16x32_bf16 v[110:113], v[164:167], v[180:183], v[110:113]
	v_mfma_f32_16x16x32_bf16 v[106:109], v[172:175], v[180:183], v[106:109]
	v_mfma_f32_16x16x32_bf16 v[94:97], v[164:167], v[188:191], v[94:97]
	v_mfma_f32_16x16x32_bf16 v[90:93], v[172:175], v[188:191], v[90:93]
	v_mfma_f32_16x16x32_bf16 v[78:81], v[164:167], v[196:199], v[78:81]
	v_mfma_f32_16x16x32_bf16 v[74:77], v[172:175], v[196:199], v[74:77]
	v_mfma_f32_16x16x32_bf16 v[70:73], v[164:167], v[204:207], v[70:73]
	v_mfma_f32_16x16x32_bf16 v[66:69], v[172:175], v[204:207], v[66:69]
	s_setprio 0
	s_barrier
	s_add_i32 s22, s28, s3
	v_lshl_add_u64 v[208:209], s[6:7], 0, v[0:1]
	s_mov_b32 m0, s22
	ds_read_b128 v[176:179], v143 offset:16384
	ds_read_b128 v[180:183], v143 offset:17408
	ds_read_b128 v[184:187], v143 offset:18432
	ds_read_b128 v[188:191], v143 offset:19456
	ds_read_b128 v[192:195], v143 offset:20480
	ds_read_b128 v[196:199], v143 offset:21504
	ds_read_b128 v[200:203], v143 offset:22528
	ds_read_b128 v[204:207], v143 offset:23552
	global_load_lds_dwordx4 v[208:209], off
	s_add_i32 m0, s22, 0x2000
	s_add_u32 s22, s6, 0x40000
	v_lshl_add_u64 v[210:211], s[6:7], 0, v[134:135]
	s_addc_u32 s23, s7, 0
	s_add_i32 s24, s33, s3
	global_load_lds_dwordx4 v[210:211], off
	v_lshl_add_u64 v[212:213], s[22:23], 0, v[0:1]
	s_mov_b32 m0, s24
	v_lshl_add_u64 v[214:215], s[8:9], 0, v[132:133]
	global_load_lds_dwordx4 v[212:213], off
	v_lshl_add_u64 v[212:213], s[22:23], 0, v[134:135]
	s_add_i32 m0, s24, 0x2000
	s_nop 0
	global_load_lds_dwordx4 v[212:213], off
	v_lshl_add_u64 v[212:213], s[8:9], 0, v[130:131]
	s_mov_b32 m0, s10
	s_nop 0
	global_load_lds_dwordx4 v[212:213], off
	s_mov_b32 m0, s11
	s_nop 0
	global_load_lds_dwordx4 v[214:215], off
	s_waitcnt vmcnt(8)
	s_waitcnt lgkmcnt(0)
	s_barrier
; #define PG8_STAGE(bufoff, gbase, voff) do { _Pragma("unroll") for (int _i = 0; _i < 2; ++_i) \
;         __builtin_amdgcn_global_load_lds((const unsigned*)((const char*)(gbase) + (voff)[_i]), (LAS unsigned*)(lds + (bufoff) + ldsw + _i * 8192), 16, 0, 0); } while (0)
; #define PG8_LDA(dst, b, h) do { _Pragma("unroll") for (int m = 0; m < 4; ++m) _Pragma("unroll") for (int k = 0; k < 2; ++k) dst[m][k] = *(const LAS bf16x8*)(lds + PG8_SA(b, h) + aoff + m * 2048 + k * 1024); } while (0)
; #define PG8_LDB(dst, b, h) do { _Pragma("unroll") for (int n = 0; n < 2; ++n) _Pragma("unroll") for (int k = 0; k < 2; ++k) dst[n][k] = *(const LAS bf16x8*)(lds + PG8_SB(b, h) + boff + n * 2048 + k * 1024); } while (0)
; #define PG8_MMA(ai, bj, At, Bt) do { __builtin_amdgcn_s_setprio(1); _Pragma("unroll") for (int m = 0; m < 4; ++m) _Pragma("unroll") for (int n = 0; n < 2; ++n) _Pragma("unroll") for (int k = 0; k < 2; ++k) \
;         acc[ai][bj][m][n] = __builtin_amdgcn_mfma_f32_16x16x32_bf16(Bt[n][k], At[m][k], acc[ai][bj][m][n], 0, 0, 0); __builtin_amdgcn_s_setprio(0); } while (0)
; #define PG8_WAIT_V(n) asm volatile("s_waitcnt vmcnt(" #n ")" ::: "memory")
; #define PG8_WAIT_L(n) asm volatile("s_waitcnt lgkmcnt(" #n ")" ::: "memory")
; #define PG8_BAR __builtin_amdgcn_s_barrier()
; #define PG8_SCHED __builtin_amdgcn_sched_barrier(0)
; template <class Epi, bool ALIGN_EPI, bool ASLOT = false>
; __device__ __forceinline__ void gemm_phase(LAS unsigned char* lds, const Gemm g, const Sched& S, const Epi& E) {
;     ...
;             PG8_WAIT_V(8); PG8_WAIT_L(0); PG8_BAR; PG8_MMA(1, 0, At, B0); PG8_MMA(1, 1, At, B1); PG8_BAR; PG8_SCHED;
;             PG8_LDB(B0, 1, 0); PG8_LDB(B1, 1, 1); PG8_SCHED; PG8_LDA(At, 1, 0); PG8_STAGE(PG8_SA(0, 1), a2 + hstep, voffA);
;             PG8_WAIT_V(8); PG8_WAIT_L(0); PG8_BAR; PG8_MMA(0, 0, At, B0); PG8_MMA(0, 1, At, B1); PG8_BAR; PG8_SCHED;
	s_setprio 1
	s_waitcnt lgkmcnt(0)
	v_mfma_f32_16x16x32_bf16 v[62:65], v[144:147], v[176:179], v[62:65]
	v_mfma_f32_16x16x32_bf16 v[58:61], v[152:155], v[176:179], v[58:61]
	v_mfma_f32_16x16x32_bf16 v[54:57], v[144:147], v[184:187], v[54:57]
	v_mfma_f32_16x16x32_bf16 v[50:53], v[152:155], v[184:187], v[50:53]
	v_mfma_f32_16x16x32_bf16 v[38:41], v[144:147], v[192:195], v[38:41]
	v_mfma_f32_16x16x32_bf16 v[34:37], v[152:155], v[192:195], v[34:37]
	v_mfma_f32_16x16x32_bf16 v[22:25], v[144:147], v[200:203], v[22:25]
	v_mfma_f32_16x16x32_bf16 v[18:21], v[152:155], v[200:203], v[18:21]
	v_mfma_f32_16x16x32_bf16 v[62:65], v[148:151], v[180:183], v[62:65]
	v_mfma_f32_16x16x32_bf16 v[58:61], v[156:159], v[180:183], v[58:61]
	v_mfma_f32_16x16x32_bf16 v[54:57], v[148:151], v[188:191], v[54:57]
	v_mfma_f32_16x16x32_bf16 v[50:53], v[156:159], v[188:191], v[50:53]
	v_mfma_f32_16x16x32_bf16 v[38:41], v[148:151], v[196:199], v[38:41]
	v_mfma_f32_16x16x32_bf16 v[34:37], v[156:159], v[196:199], v[34:37]
	v_mfma_f32_16x16x32_bf16 v[22:25], v[148:151], v[204:207], v[22:25]
	v_mfma_f32_16x16x32_bf16 v[18:21], v[156:159], v[204:207], v[18:21]
	v_mfma_f32_16x16x32_bf16 v[46:49], v[160:163], v[176:179], v[46:49]
	v_mfma_f32_16x16x32_bf16 v[42:45], v[168:171], v[176:179], v[42:45]
	v_mfma_f32_16x16x32_bf16 v[30:33], v[160:163], v[184:187], v[30:33]
	v_mfma_f32_16x16x32_bf16 v[26:29], v[168:171], v[184:187], v[26:29]
	v_mfma_f32_16x16x32_bf16 v[14:17], v[160:163], v[192:195], v[14:17]
	v_mfma_f32_16x16x32_bf16 v[10:13], v[168:171], v[192:195], v[10:13]
	v_mfma_f32_16x16x32_bf16 v[6:9], v[160:163], v[200:203], v[6:9]
	v_mfma_f32_16x16x32_bf16 v[2:5], v[168:171], v[200:203], v[2:5]
	v_mfma_f32_16x16x32_bf16 v[46:49], v[164:167], v[180:183], v[46:49]
	v_mfma_f32_16x16x32_bf16 v[42:45], v[172:175], v[180:183], v[42:45]
	v_mfma_f32_16x16x32_bf16 v[30:33], v[164:167], v[188:191], v[30:33]
	v_mfma_f32_16x16x32_bf16 v[26:29], v[172:175], v[188:191], v[26:29]
	v_mfma_f32_16x16x32_bf16 v[14:17], v[164:167], v[196:199], v[14:17]
	v_mfma_f32_16x16x32_bf16 v[10:13], v[172:175], v[196:199], v[10:13]
	v_mfma_f32_16x16x32_bf16 v[6:9], v[164:167], v[204:207], v[6:9]
	v_mfma_f32_16x16x32_bf16 v[2:5], v[172:175], v[204:207], v[2:5]
	s_setprio 0
	s_barrier
	v_add_u32_e32 v156, s29, v142
	v_add_u32_e32 v172, s26, v142
	ds_read_b128 v[144:147], v156
	ds_read_b128 v[148:151], v156 offset:1024
	ds_read_b128 v[152:155], v156 offset:2048
	ds_read_b128 v[156:159], v156 offset:3072
	ds_read_b128 v[160:163], v172
	ds_read_b128 v[164:167], v172 offset:1024
	ds_read_b128 v[168:171], v172 offset:2048
	ds_read_b128 v[172:175], v172 offset:3072
	s_add_u32 s8, s8, 0x40000
	s_addc_u32 s9, s9, 0
	s_mov_b32 m0, s12
	v_lshl_add_u64 v[220:221], s[8:9], 0, v[130:131]
	ds_read_b128 v[176:179], v143 offset:32768
	ds_read_b128 v[180:183], v143 offset:33792
	ds_read_b128 v[184:187], v143 offset:34816
	ds_read_b128 v[188:191], v143 offset:35840
	ds_read_b128 v[192:195], v143 offset:36864
	ds_read_b128 v[196:199], v143 offset:37888
	ds_read_b128 v[200:203], v143 offset:38912
	ds_read_b128 v[204:207], v143 offset:39936
	global_load_lds_dwordx4 v[220:221], off
	v_lshl_add_u64 v[220:221], s[8:9], 0, v[132:133]
	s_mov_b32 m0, s13
	s_nop 0
	global_load_lds_dwordx4 v[220:221], off
	s_waitcnt vmcnt(8)
	s_waitcnt lgkmcnt(0)
	s_barrier
	s_setprio 1
	s_waitcnt lgkmcnt(0)
	v_mfma_f32_16x16x32_bf16 v[126:129], v[144:147], v[176:179], v[126:129]
	v_mfma_f32_16x16x32_bf16 v[122:125], v[152:155], v[176:179], v[122:125]
	v_mfma_f32_16x16x32_bf16 v[118:121], v[144:147], v[184:187], v[118:121]
	v_mfma_f32_16x16x32_bf16 v[114:117], v[152:155], v[184:187], v[114:117]
	v_mfma_f32_16x16x32_bf16 v[102:105], v[144:147], v[192:195], v[102:105]
	v_mfma_f32_16x16x32_bf16 v[98:101], v[152:155], v[192:195], v[98:101]
	v_mfma_f32_16x16x32_bf16 v[86:89], v[144:147], v[200:203], v[86:89]
	v_mfma_f32_16x16x32_bf16 v[82:85], v[152:155], v[200:203], v[82:85]
	v_mfma_f32_16x16x32_bf16 v[126:129], v[148:151], v[180:183], v[126:129]
	v_mfma_f32_16x16x32_bf16 v[122:125], v[156:159], v[180:183], v[122:125]
	v_mfma_f32_16x16x32_bf16 v[118:121], v[148:151], v[188:191], v[118:121]
	v_mfma_f32_16x16x32_bf16 v[114:117], v[156:159], v[188:191], v[114:117]
	v_mfma_f32_16x16x32_bf16 v[102:105], v[148:151], v[196:199], v[102:105]
	v_mfma_f32_16x16x32_bf16 v[98:101], v[156:159], v[196:199], v[98:101]
	v_mfma_f32_16x16x32_bf16 v[86:89], v[148:151], v[204:207], v[86:89]
	v_mfma_f32_16x16x32_bf16 v[82:85], v[156:159], v[204:207], v[82:85]
	v_mfma_f32_16x16x32_bf16 v[110:113], v[160:163], v[176:179], v[110:113]
	v_mfma_f32_16x16x32_bf16 v[106:109], v[168:171], v[176:179], v[106:109]
	v_mfma_f32_16x16x32_bf16 v[94:97], v[160:163], v[184:187], v[94:97]
	v_mfma_f32_16x16x32_bf16 v[90:93], v[168:171], v[184:187], v[90:93]
	v_mfma_f32_16x16x32_bf16 v[78:81], v[160:163], v[192:195], v[78:81]
	v_mfma_f32_16x16x32_bf16 v[74:77], v[168:171], v[192:195], v[74:77]
	v_mfma_f32_16x16x32_bf16 v[70:73], v[160:163], v[200:203], v[70:73]
	v_mfma_f32_16x16x32_bf16 v[66:69], v[168:171], v[200:203], v[66:69]
	v_mfma_f32_16x16x32_bf16 v[110:113], v[164:167], v[180:183], v[110:113]
	v_mfma_f32_16x16x32_bf16 v[106:109], v[172:175], v[180:183], v[106:109]
	v_mfma_f32_16x16x32_bf16 v[94:97], v[164:167], v[188:191], v[94:97]
	v_mfma_f32_16x16x32_bf16 v[90:93], v[172:175], v[188:191], v[90:93]
	v_mfma_f32_16x16x32_bf16 v[78:81], v[164:167], v[196:199], v[78:81]
	v_mfma_f32_16x16x32_bf16 v[74:77], v[172:175], v[196:199], v[74:77]
	v_mfma_f32_16x16x32_bf16 v[70:73], v[164:167], v[204:207], v[70:73]
	v_mfma_f32_16x16x32_bf16 v[66:69], v[172:175], v[204:207], v[66:69]
	s_setprio 0
	s_barrier
; #define PG8_STAGE(bufoff, gbase, voff) do { _Pragma("unroll") for (int _i = 0; _i < 2; ++_i) \
;         __builtin_amdgcn_global_load_lds((const unsigned*)((const char*)(gbase) + (voff)[_i]), (LAS unsigned*)(lds + (bufoff) + ldsw + _i * 8192), 16, 0, 0); } while (0)
; #define PG8_LDA(dst, b, h) do { _Pragma("unroll") for (int m = 0; m < 4; ++m) _Pragma("unroll") for (int k = 0; k < 2; ++k) dst[m][k] = *(const LAS bf16x8*)(lds + PG8_SA(b, h) + aoff + m * 2048 + k * 1024); } while (0)
; #define PG8_MMA(ai, bj, At, Bt) do { __builtin_amdgcn_s_setprio(1); _Pragma("unroll") for (int m = 0; m < 4; ++m) _Pragma("unroll") for (int n = 0; n < 2; ++n) _Pragma("unroll") for (int k = 0; k < 2; ++k) \
;         acc[ai][bj][m][n] = __builtin_amdgcn_mfma_f32_16x16x32_bf16(Bt[n][k], At[m][k], acc[ai][bj][m][n], 0, 0, 0); __builtin_amdgcn_s_setprio(0); } while (0)
; #define PG8_WAIT_V(n) asm volatile("s_waitcnt vmcnt(" #n ")" ::: "memory")
; #define PG8_WAIT_L(n) asm volatile("s_waitcnt lgkmcnt(" #n ")" ::: "memory")
; #define PG8_BAR __builtin_amdgcn_s_barrier()
; #define PG8_SCHED __builtin_amdgcn_sched_barrier(0)
; template <class Epi, bool ALIGN_EPI, bool ASLOT = false>
; __device__ __forceinline__ void gemm_phase(LAS unsigned char* lds, const Gemm g, const Sched& S, const Epi& E) {
;     ...
;             PG8_LDA(At, 1, 1); PG8_STAGE(PG8_SB(1, 0), b3, voffB); PG8_STAGE(PG8_SB(1, 1), b3 + hstep, voffB); PG8_STAGE(PG8_SA(1, 0), a3, voffA);
;             PG8_WAIT_V(8); PG8_WAIT_L(0); PG8_BAR; PG8_MMA(1, 0, At, B0); PG8_MMA(1, 1, At, B1); PG8_BAR; PG8_SCHED;
;         }
	s_add_i32 s8, s29, s3
	v_lshl_add_u64 v[208:209], v[208:209], 0, s[16:17]
	s_mov_b32 m0, s8
	ds_read_b128 v[176:179], v143 offset:49152
	ds_read_b128 v[180:183], v143 offset:50176
	ds_read_b128 v[184:187], v143 offset:51200
	ds_read_b128 v[188:191], v143 offset:52224
	ds_read_b128 v[192:195], v143 offset:53248
	ds_read_b128 v[196:199], v143 offset:54272
	ds_read_b128 v[200:203], v143 offset:55296
	ds_read_b128 v[204:207], v143 offset:56320
	global_load_lds_dwordx4 v[208:209], off
	s_add_i32 m0, s8, 0x2000
	s_add_u32 s6, s6, 0x40080
	v_lshl_add_u64 v[208:209], v[210:211], 0, s[16:17]
	s_addc_u32 s7, s7, 0
	s_add_i32 s8, s26, s3
	global_load_lds_dwordx4 v[208:209], off
	v_lshl_add_u64 v[208:209], s[6:7], 0, v[0:1]
	s_mov_b32 m0, s8
	s_nop 0
	global_load_lds_dwordx4 v[208:209], off
	v_lshl_add_u64 v[208:209], s[6:7], 0, v[134:135]
	s_add_i32 m0, s8, 0x2000
	s_nop 0
	global_load_lds_dwordx4 v[208:209], off
	v_lshl_add_u64 v[208:209], v[212:213], 0, s[16:17]
	s_mov_b32 m0, s15
	s_nop 0
	global_load_lds_dwordx4 v[208:209], off
	v_lshl_add_u64 v[208:209], v[214:215], 0, s[16:17]
	s_mov_b32 m0, s18
	s_nop 0
	global_load_lds_dwordx4 v[208:209], off
	s_waitcnt vmcnt(8)
	s_waitcnt lgkmcnt(0)
	s_barrier
	s_setprio 1
	s_waitcnt lgkmcnt(0)
	v_mfma_f32_16x16x32_bf16 v[62:65], v[144:147], v[176:179], v[62:65]
	v_mfma_f32_16x16x32_bf16 v[58:61], v[152:155], v[176:179], v[58:61]
	v_mfma_f32_16x16x32_bf16 v[54:57], v[144:147], v[184:187], v[54:57]
	v_mfma_f32_16x16x32_bf16 v[50:53], v[152:155], v[184:187], v[50:53]
	v_mfma_f32_16x16x32_bf16 v[38:41], v[144:147], v[192:195], v[38:41]
	v_mfma_f32_16x16x32_bf16 v[34:37], v[152:155], v[192:195], v[34:37]
	v_mfma_f32_16x16x32_bf16 v[22:25], v[144:147], v[200:203], v[22:25]
	v_mfma_f32_16x16x32_bf16 v[18:21], v[152:155], v[200:203], v[18:21]
	v_mfma_f32_16x16x32_bf16 v[62:65], v[148:151], v[180:183], v[62:65]
	v_mfma_f32_16x16x32_bf16 v[58:61], v[156:159], v[180:183], v[58:61]
	v_mfma_f32_16x16x32_bf16 v[54:57], v[148:151], v[188:191], v[54:57]
	v_mfma_f32_16x16x32_bf16 v[50:53], v[156:159], v[188:191], v[50:53]
	v_mfma_f32_16x16x32_bf16 v[38:41], v[148:151], v[196:199], v[38:41]
	v_mfma_f32_16x16x32_bf16 v[34:37], v[156:159], v[196:199], v[34:37]
	v_mfma_f32_16x16x32_bf16 v[22:25], v[148:151], v[204:207], v[22:25]
	v_mfma_f32_16x16x32_bf16 v[18:21], v[156:159], v[204:207], v[18:21]
	v_mfma_f32_16x16x32_bf16 v[46:49], v[160:163], v[176:179], v[46:49]
	v_mfma_f32_16x16x32_bf16 v[42:45], v[168:171], v[176:179], v[42:45]
	v_mfma_f32_16x16x32_bf16 v[30:33], v[160:163], v[184:187], v[30:33]
	v_mfma_f32_16x16x32_bf16 v[26:29], v[168:171], v[184:187], v[26:29]
	v_mfma_f32_16x16x32_bf16 v[14:17], v[160:163], v[192:195], v[14:17]
	v_mfma_f32_16x16x32_bf16 v[10:13], v[168:171], v[192:195], v[10:13]
	v_mfma_f32_16x16x32_bf16 v[6:9], v[160:163], v[200:203], v[6:9]
	v_mfma_f32_16x16x32_bf16 v[2:5], v[168:171], v[200:203], v[2:5]
	v_mfma_f32_16x16x32_bf16 v[46:49], v[164:167], v[180:183], v[46:49]
	v_mfma_f32_16x16x32_bf16 v[42:45], v[172:175], v[180:183], v[42:45]
	v_mfma_f32_16x16x32_bf16 v[30:33], v[164:167], v[188:191], v[30:33]
	v_mfma_f32_16x16x32_bf16 v[26:29], v[172:175], v[188:191], v[26:29]
	v_mfma_f32_16x16x32_bf16 v[14:17], v[164:167], v[196:199], v[14:17]
	v_mfma_f32_16x16x32_bf16 v[10:13], v[172:175], v[196:199], v[10:13]
	v_mfma_f32_16x16x32_bf16 v[6:9], v[164:167], v[204:207], v[6:9]
	v_mfma_f32_16x16x32_bf16 v[2:5], v[172:175], v[204:207], v[2:5]
	s_setprio 0
	s_barrier
	s_add_i32 s21, s21, 2
	s_add_u32 s4, s4, 0x100
	s_addc_u32 s5, s5, 0
	s_cmp_gt_u32 s21, 13
	s_cbranch_scc0 .LBB0_783
	s_cmpk_lt_u32 s2, 0x100
	s_cbranch_scc0 .LBB0_786
	s_barrier

; #define PG8_STAGE(bufoff, gbase, voff) do { _Pragma("unroll") for (int _i = 0; _i < 2; ++_i) \
;         __builtin_amdgcn_global_load_lds((const unsigned*)((const char*)(gbase) + (voff)[_i]), (LAS unsigned*)(lds + (bufoff) + ldsw + _i * 8192), 16, 0, 0); } while (0)
; #define PG8_LDA(dst, b, h) do { _Pragma("unroll") for (int m = 0; m < 4; ++m) _Pragma("unroll") for (int k = 0; k < 2; ++k) dst[m][k] = *(const LAS bf16x8*)(lds + PG8_SA(b, h) + aoff + m * 2048 + k * 1024); } while (0)
; #define PG8_LDB(dst, b, h) do { _Pragma("unroll") for (int n = 0; n < 2; ++n) _Pragma("unroll") for (int k = 0; k < 2; ++k) dst[n][k] = *(const LAS bf16x8*)(lds + PG8_SB(b, h) + boff + n * 2048 + k * 1024); } while (0)
; #define PG8_MMA(ai, bj, At, Bt) do { __builtin_amdgcn_s_setprio(1); _Pragma("unroll") for (int m = 0; m < 4; ++m) _Pragma("unroll") for (int n = 0; n < 2; ++n) _Pragma("unroll") for (int k = 0; k < 2; ++k) \
;         acc[ai][bj][m][n] = __builtin_amdgcn_mfma_f32_16x16x32_bf16(Bt[n][k], At[m][k], acc[ai][bj][m][n], 0, 0, 0); __builtin_amdgcn_s_setprio(0); } while (0)
; #define PG8_WAIT_V(n) asm volatile("s_waitcnt vmcnt(" #n ")" ::: "memory")
; #define PG8_WAIT_L(n) asm volatile("s_waitcnt lgkmcnt(" #n ")" ::: "memory")
; #define PG8_BAR __builtin_amdgcn_s_barrier()
; #define PG8_SCHED __builtin_amdgcn_sched_barrier(0)
; template <class Epi, bool ALIGN_EPI, bool ASLOT = false>
; __device__ __forceinline__ void gemm_phase(LAS unsigned char* lds, const Gemm g, const Sched& S, const Epi& E) {
;     ...
;         for (int t = 0; t < nt; t += 2) {
;             const bool last = (t == nt - 2);
;             const char* a1 = cA + (size_t)(t + 1) * kstep;
;             const char* a2 = last ? nA : cA + (size_t)(t + 2) * kstep; const char* b2 = last ? nB : cB + (size_t)(t + 2) * kstep;
;             const char* a3 = a2 + kstep; const char* b3 = b2 + kstep;
;             PG8_LDB(B0, 0, 0); PG8_LDB(B1, 0, 1); PG8_SCHED; PG8_LDA(At, 0, 0); PG8_STAGE(PG8_SA(1, 1), a1 + hstep, voffA);
;             PG8_WAIT_V(8); PG8_WAIT_L(0); PG8_BAR; PG8_MMA(0, 0, At, B0); PG8_MMA(0, 1, At, B1); PG8_BAR; PG8_SCHED;
;             PG8_LDA(At, 0, 1); PG8_STAGE(PG8_SB(0, 0), b2, voffB); PG8_STAGE(PG8_SB(0, 1), b2 + hstep, voffB); PG8_STAGE(PG8_SA(0, 0), a2, voffA);
;             PG8_WAIT_V(8); PG8_WAIT_L(0); PG8_BAR; PG8_MMA(1, 0, At, B0); PG8_MMA(1, 1, At, B1); PG8_BAR; PG8_SCHED;
.LBB0_853:
	v_add_u32_e32 v156, s28, v158
	ds_read_b128 v[162:165], v156
	ds_read_b128 v[166:169], v156 offset:1024
	ds_read_b128 v[170:173], v156 offset:2048
	ds_read_b128 v[174:177], v156 offset:3072
	v_add_u32_e32 v156, s33, v158
	ds_read_b128 v[178:181], v156
	ds_read_b128 v[182:185], v156 offset:1024
	ds_read_b128 v[186:189], v156 offset:2048
	ds_read_b128 v[190:193], v156 offset:3072
	s_add_u32 s18, s36, 0xfffc0080
	s_addc_u32 s19, s37, -1
	s_cmp_eq_u32 s50, 12
	s_cselect_b32 s21, s9, s19
	s_cselect_b32 s20, s24, s18
	s_cselect_b32 s19, s11, s49
	s_cselect_b32 s18, s25, s48
	v_lshl_add_u64 v[156:157], s[36:37], 0, v[152:153]
	s_add_i32 m0, s42, 0xc000
	ds_read_b128 v[194:197], v160
	ds_read_b128 v[198:201], v160 offset:1024
	ds_read_b128 v[202:205], v160 offset:2048
	ds_read_b128 v[206:209], v160 offset:3072
	ds_read_b128 v[210:213], v160 offset:4096
	ds_read_b128 v[220:223], v160 offset:5120
	ds_read_b128 v[236:239], v160 offset:6144
	ds_read_b128 v[240:243], v160 offset:7168
	global_load_lds_dwordx4 v[156:157], off
	v_lshl_add_u64 v[156:157], s[36:37], 0, v[154:155]
	s_add_i32 m0, s42, 0xe000
	s_nop 0
	global_load_lds_dwordx4 v[156:157], off
	s_waitcnt vmcnt(8)
	s_waitcnt lgkmcnt(0)
	s_barrier
	s_setprio 1
	s_waitcnt lgkmcnt(0)
	v_mfma_f32_16x16x32_bf16 v[126:129], v[162:165], v[194:197], v[126:129]
	v_mfma_f32_16x16x32_bf16 v[122:125], v[170:173], v[194:197], v[122:125]
	v_mfma_f32_16x16x32_bf16 v[110:113], v[162:165], v[202:205], v[110:113]
	v_mfma_f32_16x16x32_bf16 v[106:109], v[170:173], v[202:205], v[106:109]
	v_mfma_f32_16x16x32_bf16 v[94:97], v[162:165], v[210:213], v[94:97]
	v_mfma_f32_16x16x32_bf16 v[90:93], v[170:173], v[210:213], v[90:93]
	v_mfma_f32_16x16x32_bf16 v[78:81], v[162:165], v[236:239], v[78:81]
	v_mfma_f32_16x16x32_bf16 v[74:77], v[170:173], v[236:239], v[74:77]
	v_mfma_f32_16x16x32_bf16 v[126:129], v[166:169], v[198:201], v[126:129]
	v_mfma_f32_16x16x32_bf16 v[122:125], v[174:177], v[198:201], v[122:125]
	v_mfma_f32_16x16x32_bf16 v[110:113], v[166:169], v[206:209], v[110:113]
	v_mfma_f32_16x16x32_bf16 v[106:109], v[174:177], v[206:209], v[106:109]
	v_mfma_f32_16x16x32_bf16 v[94:97], v[166:169], v[220:223], v[94:97]
	v_mfma_f32_16x16x32_bf16 v[90:93], v[174:177], v[220:223], v[90:93]
	v_mfma_f32_16x16x32_bf16 v[78:81], v[166:169], v[240:243], v[78:81]
	v_mfma_f32_16x16x32_bf16 v[74:77], v[174:177], v[240:243], v[74:77]
	v_mfma_f32_16x16x32_bf16 v[118:121], v[178:181], v[194:197], v[118:121]
	v_mfma_f32_16x16x32_bf16 v[114:117], v[186:189], v[194:197], v[114:117]
	v_mfma_f32_16x16x32_bf16 v[102:105], v[178:181], v[202:205], v[102:105]
	v_mfma_f32_16x16x32_bf16 v[98:101], v[186:189], v[202:205], v[98:101]
	v_mfma_f32_16x16x32_bf16 v[86:89], v[178:181], v[210:213], v[86:89]
	v_mfma_f32_16x16x32_bf16 v[82:85], v[186:189], v[210:213], v[82:85]
	v_mfma_f32_16x16x32_bf16 v[70:73], v[178:181], v[236:239], v[70:73]
	v_mfma_f32_16x16x32_bf16 v[66:69], v[186:189], v[236:239], v[66:69]
	v_mfma_f32_16x16x32_bf16 v[118:121], v[182:185], v[198:201], v[118:121]
	v_mfma_f32_16x16x32_bf16 v[114:117], v[190:193], v[198:201], v[114:117]
	v_mfma_f32_16x16x32_bf16 v[102:105], v[182:185], v[206:209], v[102:105]
	v_mfma_f32_16x16x32_bf16 v[98:101], v[190:193], v[206:209], v[98:101]
	v_mfma_f32_16x16x32_bf16 v[86:89], v[182:185], v[220:223], v[86:89]
	v_mfma_f32_16x16x32_bf16 v[82:85], v[190:193], v[220:223], v[82:85]
	v_mfma_f32_16x16x32_bf16 v[70:73], v[182:185], v[240:243], v[70:73]
	v_mfma_f32_16x16x32_bf16 v[66:69], v[190:193], v[240:243], v[66:69]
	s_setprio 0
	s_barrier
	s_add_i32 s22, s28, s39
	v_lshl_add_u64 v[156:157], s[18:19], 0, v[0:1]
	s_mov_b32 m0, s22
	ds_read_b128 v[194:197], v160 offset:16384
	ds_read_b128 v[198:201], v160 offset:17408
	ds_read_b128 v[202:205], v160 offset:18432
	ds_read_b128 v[206:209], v160 offset:19456
	ds_read_b128 v[210:213], v160 offset:20480
	ds_read_b128 v[220:223], v160 offset:21504
	ds_read_b128 v[236:239], v160 offset:22528
	ds_read_b128 v[240:243], v160 offset:23552
	global_load_lds_dwordx4 v[156:157], off
	s_add_i32 m0, s22, 0x2000
	s_add_u32 s22, s18, 0x40000
	v_lshl_add_u64 v[214:215], s[18:19], 0, v[134:135]
	s_addc_u32 s23, s19, 0
	s_add_i32 s30, s33, s39
	global_load_lds_dwordx4 v[214:215], off
	v_lshl_add_u64 v[232:233], s[22:23], 0, v[0:1]
	s_mov_b32 m0, s30
	v_lshl_add_u64 v[244:245], s[20:21], 0, v[132:133]
	global_load_lds_dwordx4 v[232:233], off
	v_lshl_add_u64 v[232:233], s[22:23], 0, v[134:135]
	s_add_i32 m0, s30, 0x2000
	s_nop 0
	global_load_lds_dwordx4 v[232:233], off
	v_lshl_add_u64 v[232:233], s[20:21], 0, v[130:131]
	s_mov_b32 m0, s42
	s_nop 0
	global_load_lds_dwordx4 v[232:233], off
	s_mov_b32 m0, s43
	s_nop 0
	global_load_lds_dwordx4 v[244:245], off
	s_waitcnt vmcnt(8)
	s_waitcnt lgkmcnt(0)
	s_barrier
; #define PG8_STAGE(bufoff, gbase, voff) do { _Pragma("unroll") for (int _i = 0; _i < 2; ++_i) \
;         __builtin_amdgcn_global_load_lds((const unsigned*)((const char*)(gbase) + (voff)[_i]), (LAS unsigned*)(lds + (bufoff) + ldsw + _i * 8192), 16, 0, 0); } while (0)
; #define PG8_LDA(dst, b, h) do { _Pragma("unroll") for (int m = 0; m < 4; ++m) _Pragma("unroll") for (int k = 0; k < 2; ++k) dst[m][k] = *(const LAS bf16x8*)(lds + PG8_SA(b, h) + aoff + m * 2048 + k * 1024); } while (0)
; #define PG8_LDB(dst, b, h) do { _Pragma("unroll") for (int n = 0; n < 2; ++n) _Pragma("unroll") for (int k = 0; k < 2; ++k) dst[n][k] = *(const LAS bf16x8*)(lds + PG8_SB(b, h) + boff + n * 2048 + k * 1024); } while (0)
; #define PG8_MMA(ai, bj, At, Bt) do { __builtin_amdgcn_s_setprio(1); _Pragma("unroll") for (int m = 0; m < 4; ++m) _Pragma("unroll") for (int n = 0; n < 2; ++n) _Pragma("unroll") for (int k = 0; k < 2; ++k) \
;         acc[ai][bj][m][n] = __builtin_amdgcn_mfma_f32_16x16x32_bf16(Bt[n][k], At[m][k], acc[ai][bj][m][n], 0, 0, 0); __builtin_amdgcn_s_setprio(0); } while (0)
; #define PG8_WAIT_V(n) asm volatile("s_waitcnt vmcnt(" #n ")" ::: "memory")
; #define PG8_WAIT_L(n) asm volatile("s_waitcnt lgkmcnt(" #n ")" ::: "memory")
; #define PG8_BAR __builtin_amdgcn_s_barrier()
; #define PG8_SCHED __builtin_amdgcn_sched_barrier(0)
; template <class Epi, bool ALIGN_EPI, bool ASLOT = false>
; __device__ __forceinline__ void gemm_phase(LAS unsigned char* lds, const Gemm g, const Sched& S, const Epi& E) {
;     ...
;             PG8_WAIT_V(8); PG8_WAIT_L(0); PG8_BAR; PG8_MMA(1, 0, At, B0); PG8_MMA(1, 1, At, B1); PG8_BAR; PG8_SCHED;
;             PG8_LDB(B0, 1, 0); PG8_LDB(B1, 1, 1); PG8_SCHED; PG8_LDA(At, 1, 0); PG8_STAGE(PG8_SA(0, 1), a2 + hstep, voffA);
;             PG8_WAIT_V(8); PG8_WAIT_L(0); PG8_BAR; PG8_MMA(0, 0, At, B0); PG8_MMA(0, 1, At, B1); PG8_BAR; PG8_SCHED;
	s_setprio 1
	s_waitcnt lgkmcnt(0)
	v_mfma_f32_16x16x32_bf16 v[62:65], v[162:165], v[194:197], v[62:65]
	v_mfma_f32_16x16x32_bf16 v[58:61], v[170:173], v[194:197], v[58:61]
	v_mfma_f32_16x16x32_bf16 v[46:49], v[162:165], v[202:205], v[46:49]
	v_mfma_f32_16x16x32_bf16 v[42:45], v[170:173], v[202:205], v[42:45]
	v_mfma_f32_16x16x32_bf16 v[30:33], v[162:165], v[210:213], v[30:33]
	v_mfma_f32_16x16x32_bf16 v[26:29], v[170:173], v[210:213], v[26:29]
	v_mfma_f32_16x16x32_bf16 v[14:17], v[162:165], v[236:239], v[14:17]
	v_mfma_f32_16x16x32_bf16 v[10:13], v[170:173], v[236:239], v[10:13]
	v_mfma_f32_16x16x32_bf16 v[62:65], v[166:169], v[198:201], v[62:65]
	v_mfma_f32_16x16x32_bf16 v[58:61], v[174:177], v[198:201], v[58:61]
	v_mfma_f32_16x16x32_bf16 v[46:49], v[166:169], v[206:209], v[46:49]
	v_mfma_f32_16x16x32_bf16 v[42:45], v[174:177], v[206:209], v[42:45]
	v_mfma_f32_16x16x32_bf16 v[30:33], v[166:169], v[220:223], v[30:33]
	v_mfma_f32_16x16x32_bf16 v[26:29], v[174:177], v[220:223], v[26:29]
	v_mfma_f32_16x16x32_bf16 v[14:17], v[166:169], v[240:243], v[14:17]
	v_mfma_f32_16x16x32_bf16 v[10:13], v[174:177], v[240:243], v[10:13]
	v_mfma_f32_16x16x32_bf16 v[54:57], v[178:181], v[194:197], v[54:57]
	v_mfma_f32_16x16x32_bf16 v[50:53], v[186:189], v[194:197], v[50:53]
	v_mfma_f32_16x16x32_bf16 v[38:41], v[178:181], v[202:205], v[38:41]
	v_mfma_f32_16x16x32_bf16 v[34:37], v[186:189], v[202:205], v[34:37]
	v_mfma_f32_16x16x32_bf16 v[22:25], v[178:181], v[210:213], v[22:25]
	v_mfma_f32_16x16x32_bf16 v[18:21], v[186:189], v[210:213], v[18:21]
	v_mfma_f32_16x16x32_bf16 v[6:9], v[178:181], v[236:239], v[6:9]
	v_mfma_f32_16x16x32_bf16 v[2:5], v[186:189], v[236:239], v[2:5]
	v_mfma_f32_16x16x32_bf16 v[54:57], v[182:185], v[198:201], v[54:57]
	v_mfma_f32_16x16x32_bf16 v[50:53], v[190:193], v[198:201], v[50:53]
	v_mfma_f32_16x16x32_bf16 v[38:41], v[182:185], v[206:209], v[38:41]
	v_mfma_f32_16x16x32_bf16 v[34:37], v[190:193], v[206:209], v[34:37]
	v_mfma_f32_16x16x32_bf16 v[22:25], v[182:185], v[220:223], v[22:25]
	v_mfma_f32_16x16x32_bf16 v[18:21], v[190:193], v[220:223], v[18:21]
	v_mfma_f32_16x16x32_bf16 v[6:9], v[182:185], v[240:243], v[6:9]
	v_mfma_f32_16x16x32_bf16 v[2:5], v[190:193], v[240:243], v[2:5]
	s_setprio 0
	s_barrier
	v_add_u32_e32 v161, s29, v158
	ds_read_b128 v[162:165], v161
	ds_read_b128 v[166:169], v161 offset:1024
	ds_read_b128 v[170:173], v161 offset:2048
	ds_read_b128 v[174:177], v161 offset:3072
	v_add_u32_e32 v161, s26, v158
	ds_read_b128 v[178:181], v161
	ds_read_b128 v[182:185], v161 offset:1024
	ds_read_b128 v[186:189], v161 offset:2048
	ds_read_b128 v[190:193], v161 offset:3072
	s_add_u32 s20, s20, 0x40000
	s_addc_u32 s21, s21, 0
	s_mov_b32 m0, s44
	v_lshl_add_u64 v[246:247], s[20:21], 0, v[130:131]
	ds_read_b128 v[194:197], v160 offset:32768
	ds_read_b128 v[198:201], v160 offset:33792
	ds_read_b128 v[202:205], v160 offset:34816
	ds_read_b128 v[206:209], v160 offset:35840
	ds_read_b128 v[210:213], v160 offset:36864
	ds_read_b128 v[220:223], v160 offset:37888
	ds_read_b128 v[236:239], v160 offset:38912
	ds_read_b128 v[240:243], v160 offset:39936
	global_load_lds_dwordx4 v[246:247], off
	v_lshl_add_u64 v[246:247], s[20:21], 0, v[132:133]
	s_mov_b32 m0, s45
	s_nop 0
	global_load_lds_dwordx4 v[246:247], off
	s_waitcnt vmcnt(8)
	s_waitcnt lgkmcnt(0)
	s_barrier
	s_setprio 1
	s_waitcnt lgkmcnt(0)
	v_mfma_f32_16x16x32_bf16 v[126:129], v[162:165], v[194:197], v[126:129]
	v_mfma_f32_16x16x32_bf16 v[122:125], v[170:173], v[194:197], v[122:125]
	v_mfma_f32_16x16x32_bf16 v[110:113], v[162:165], v[202:205], v[110:113]
	v_mfma_f32_16x16x32_bf16 v[106:109], v[170:173], v[202:205], v[106:109]
	v_mfma_f32_16x16x32_bf16 v[94:97], v[162:165], v[210:213], v[94:97]
	v_mfma_f32_16x16x32_bf16 v[90:93], v[170:173], v[210:213], v[90:93]
	v_mfma_f32_16x16x32_bf16 v[78:81], v[162:165], v[236:239], v[78:81]
	v_mfma_f32_16x16x32_bf16 v[74:77], v[170:173], v[236:239], v[74:77]
	v_mfma_f32_16x16x32_bf16 v[126:129], v[166:169], v[198:201], v[126:129]
	v_mfma_f32_16x16x32_bf16 v[122:125], v[174:177], v[198:201], v[122:125]
	v_mfma_f32_16x16x32_bf16 v[110:113], v[166:169], v[206:209], v[110:113]
	v_mfma_f32_16x16x32_bf16 v[106:109], v[174:177], v[206:209], v[106:109]
	v_mfma_f32_16x16x32_bf16 v[94:97], v[166:169], v[220:223], v[94:97]
	v_mfma_f32_16x16x32_bf16 v[90:93], v[174:177], v[220:223], v[90:93]
	v_mfma_f32_16x16x32_bf16 v[78:81], v[166:169], v[240:243], v[78:81]
	v_mfma_f32_16x16x32_bf16 v[74:77], v[174:177], v[240:243], v[74:77]
	v_mfma_f32_16x16x32_bf16 v[118:121], v[178:181], v[194:197], v[118:121]
	v_mfma_f32_16x16x32_bf16 v[114:117], v[186:189], v[194:197], v[114:117]
	v_mfma_f32_16x16x32_bf16 v[102:105], v[178:181], v[202:205], v[102:105]
	v_mfma_f32_16x16x32_bf16 v[98:101], v[186:189], v[202:205], v[98:101]
	v_mfma_f32_16x16x32_bf16 v[86:89], v[178:181], v[210:213], v[86:89]
	v_mfma_f32_16x16x32_bf16 v[82:85], v[186:189], v[210:213], v[82:85]
	v_mfma_f32_16x16x32_bf16 v[70:73], v[178:181], v[236:239], v[70:73]
	v_mfma_f32_16x16x32_bf16 v[66:69], v[186:189], v[236:239], v[66:69]
	v_mfma_f32_16x16x32_bf16 v[118:121], v[182:185], v[198:201], v[118:121]
	v_mfma_f32_16x16x32_bf16 v[114:117], v[190:193], v[198:201], v[114:117]
	v_mfma_f32_16x16x32_bf16 v[102:105], v[182:185], v[206:209], v[102:105]
	v_mfma_f32_16x16x32_bf16 v[98:101], v[190:193], v[206:209], v[98:101]
	v_mfma_f32_16x16x32_bf16 v[86:89], v[182:185], v[220:223], v[86:89]
	v_mfma_f32_16x16x32_bf16 v[82:85], v[190:193], v[220:223], v[82:85]
	v_mfma_f32_16x16x32_bf16 v[70:73], v[182:185], v[240:243], v[70:73]
	v_mfma_f32_16x16x32_bf16 v[66:69], v[190:193], v[240:243], v[66:69]
	s_setprio 0
	s_barrier
; #define PG8_STAGE(bufoff, gbase, voff) do { _Pragma("unroll") for (int _i = 0; _i < 2; ++_i) \
;         __builtin_amdgcn_global_load_lds((const unsigned*)((const char*)(gbase) + (voff)[_i]), (LAS unsigned*)(lds + (bufoff) + ldsw + _i * 8192), 16, 0, 0); } while (0)
; #define PG8_LDA(dst, b, h) do { _Pragma("unroll") for (int m = 0; m < 4; ++m) _Pragma("unroll") for (int k = 0; k < 2; ++k) dst[m][k] = *(const LAS bf16x8*)(lds + PG8_SA(b, h) + aoff + m * 2048 + k * 1024); } while (0)
; #define PG8_MMA(ai, bj, At, Bt) do { __builtin_amdgcn_s_setprio(1); _Pragma("unroll") for (int m = 0; m < 4; ++m) _Pragma("unroll") for (int n = 0; n < 2; ++n) _Pragma("unroll") for (int k = 0; k < 2; ++k) \
;         acc[ai][bj][m][n] = __builtin_amdgcn_mfma_f32_16x16x32_bf16(Bt[n][k], At[m][k], acc[ai][bj][m][n], 0, 0, 0); __builtin_amdgcn_s_setprio(0); } while (0)
; #define PG8_WAIT_V(n) asm volatile("s_waitcnt vmcnt(" #n ")" ::: "memory")
; #define PG8_WAIT_L(n) asm volatile("s_waitcnt lgkmcnt(" #n ")" ::: "memory")
; #define PG8_BAR __builtin_amdgcn_s_barrier()
; #define PG8_SCHED __builtin_amdgcn_sched_barrier(0)
; template <class Epi, bool ALIGN_EPI, bool ASLOT = false>
; __device__ __forceinline__ void gemm_phase(LAS unsigned char* lds, const Gemm g, const Sched& S, const Epi& E) {
;     ...
;             PG8_LDA(At, 1, 1); PG8_STAGE(PG8_SB(1, 0), b3, voffB); PG8_STAGE(PG8_SB(1, 1), b3 + hstep, voffB); PG8_STAGE(PG8_SA(1, 0), a3, voffA);
;             PG8_WAIT_V(8); PG8_WAIT_L(0); PG8_BAR; PG8_MMA(1, 0, At, B0); PG8_MMA(1, 1, At, B1); PG8_BAR; PG8_SCHED;
;         }
;         if constexpr (ALIGN_EPI) { if (wr == 0) PG8_BAR; }
	s_add_i32 s20, s29, s39
	v_lshl_add_u64 v[156:157], v[156:157], 0, s[16:17]
	s_mov_b32 m0, s20
	ds_read_b128 v[194:197], v160 offset:49152
	ds_read_b128 v[198:201], v160 offset:50176
	ds_read_b128 v[202:205], v160 offset:51200
	ds_read_b128 v[206:209], v160 offset:52224
	ds_read_b128 v[210:213], v160 offset:53248
	ds_read_b128 v[220:223], v160 offset:54272
	ds_read_b128 v[236:239], v160 offset:55296
	ds_read_b128 v[240:243], v160 offset:56320
	global_load_lds_dwordx4 v[156:157], off
	s_add_i32 m0, s20, 0x2000
	s_add_u32 s18, s18, 0x40080
	v_lshl_add_u64 v[156:157], v[214:215], 0, s[16:17]
	s_addc_u32 s19, s19, 0
	s_add_i32 s20, s26, s39
	global_load_lds_dwordx4 v[156:157], off
	v_lshl_add_u64 v[156:157], s[18:19], 0, v[0:1]
	s_mov_b32 m0, s20
	s_nop 0
	global_load_lds_dwordx4 v[156:157], off
	v_lshl_add_u64 v[156:157], s[18:19], 0, v[134:135]
	s_add_i32 m0, s20, 0x2000
	s_nop 0
	global_load_lds_dwordx4 v[156:157], off
	v_lshl_add_u64 v[156:157], v[232:233], 0, s[16:17]
	s_mov_b32 m0, s46
	s_nop 0
	global_load_lds_dwordx4 v[156:157], off
	v_lshl_add_u64 v[156:157], v[244:245], 0, s[16:17]
	s_mov_b32 m0, s47
	s_nop 0
	global_load_lds_dwordx4 v[156:157], off
	s_waitcnt vmcnt(8)
	s_waitcnt lgkmcnt(0)
	s_barrier
	s_setprio 1
	s_waitcnt lgkmcnt(0)
	v_mfma_f32_16x16x32_bf16 v[62:65], v[162:165], v[194:197], v[62:65]
	v_mfma_f32_16x16x32_bf16 v[58:61], v[170:173], v[194:197], v[58:61]
	v_mfma_f32_16x16x32_bf16 v[46:49], v[162:165], v[202:205], v[46:49]
	v_mfma_f32_16x16x32_bf16 v[42:45], v[170:173], v[202:205], v[42:45]
	v_mfma_f32_16x16x32_bf16 v[30:33], v[162:165], v[210:213], v[30:33]
	v_mfma_f32_16x16x32_bf16 v[26:29], v[170:173], v[210:213], v[26:29]
	v_mfma_f32_16x16x32_bf16 v[14:17], v[162:165], v[236:239], v[14:17]
	v_mfma_f32_16x16x32_bf16 v[10:13], v[170:173], v[236:239], v[10:13]
	v_mfma_f32_16x16x32_bf16 v[62:65], v[166:169], v[198:201], v[62:65]
	v_mfma_f32_16x16x32_bf16 v[58:61], v[174:177], v[198:201], v[58:61]
	v_mfma_f32_16x16x32_bf16 v[46:49], v[166:169], v[206:209], v[46:49]
	v_mfma_f32_16x16x32_bf16 v[42:45], v[174:177], v[206:209], v[42:45]
	v_mfma_f32_16x16x32_bf16 v[30:33], v[166:169], v[220:223], v[30:33]
	v_mfma_f32_16x16x32_bf16 v[26:29], v[174:177], v[220:223], v[26:29]
	v_mfma_f32_16x16x32_bf16 v[14:17], v[166:169], v[240:243], v[14:17]
	v_mfma_f32_16x16x32_bf16 v[10:13], v[174:177], v[240:243], v[10:13]
	v_mfma_f32_16x16x32_bf16 v[54:57], v[178:181], v[194:197], v[54:57]
	v_mfma_f32_16x16x32_bf16 v[50:53], v[186:189], v[194:197], v[50:53]
	v_mfma_f32_16x16x32_bf16 v[38:41], v[178:181], v[202:205], v[38:41]
	v_mfma_f32_16x16x32_bf16 v[34:37], v[186:189], v[202:205], v[34:37]
	v_mfma_f32_16x16x32_bf16 v[22:25], v[178:181], v[210:213], v[22:25]
	v_mfma_f32_16x16x32_bf16 v[18:21], v[186:189], v[210:213], v[18:21]
	v_mfma_f32_16x16x32_bf16 v[6:9], v[178:181], v[236:239], v[6:9]
	v_mfma_f32_16x16x32_bf16 v[2:5], v[186:189], v[236:239], v[2:5]
	v_mfma_f32_16x16x32_bf16 v[54:57], v[182:185], v[198:201], v[54:57]
	v_mfma_f32_16x16x32_bf16 v[50:53], v[190:193], v[198:201], v[50:53]
	v_mfma_f32_16x16x32_bf16 v[38:41], v[182:185], v[206:209], v[38:41]
	v_mfma_f32_16x16x32_bf16 v[34:37], v[190:193], v[206:209], v[34:37]
	v_mfma_f32_16x16x32_bf16 v[22:25], v[182:185], v[220:223], v[22:25]
	v_mfma_f32_16x16x32_bf16 v[18:21], v[190:193], v[220:223], v[18:21]
	v_mfma_f32_16x16x32_bf16 v[6:9], v[182:185], v[240:243], v[6:9]
	v_mfma_f32_16x16x32_bf16 v[2:5], v[190:193], v[240:243], v[2:5]
	s_setprio 0
	s_barrier
	s_add_i32 s50, s50, 2
	s_add_u32 s36, s36, 0x100
	s_addc_u32 s37, s37, 0
	s_add_u32 s48, s48, 0x100
	s_addc_u32 s49, s49, 0
	s_cmp_gt_u32 s50, 13
	s_cbranch_scc0 .LBB0_853
	s_and_b64 vcc, exec, s[6:7]
	s_cbranch_vccz .LBB0_856
	s_barrier

; #define PG8_STAGE(bufoff, gbase, voff) do { _Pragma("unroll") for (int _i = 0; _i < 2; ++_i) \
;         __builtin_amdgcn_global_load_lds((const unsigned*)((const char*)(gbase) + (voff)[_i]), (LAS unsigned*)(lds + (bufoff) + ldsw + _i * 8192), 16, 0, 0); } while (0)
; #define PG8_LDA(dst, b, h) do { _Pragma("unroll") for (int m = 0; m < 4; ++m) _Pragma("unroll") for (int k = 0; k < 2; ++k) dst[m][k] = *(const LAS bf16x8*)(lds + PG8_SA(b, h) + aoff + m * 2048 + k * 1024); } while (0)
; #define PG8_LDB(dst, b, h) do { _Pragma("unroll") for (int n = 0; n < 2; ++n) _Pragma("unroll") for (int k = 0; k < 2; ++k) dst[n][k] = *(const LAS bf16x8*)(lds + PG8_SB(b, h) + boff + n * 2048 + k * 1024); } while (0)
; #define PG8_MMA(ai, bj, At, Bt) do { __builtin_amdgcn_s_setprio(1); _Pragma("unroll") for (int m = 0; m < 4; ++m) _Pragma("unroll") for (int n = 0; n < 2; ++n) _Pragma("unroll") for (int k = 0; k < 2; ++k) \
;         acc[ai][bj][m][n] = __builtin_amdgcn_mfma_f32_16x16x32_bf16(Bt[n][k], At[m][k], acc[ai][bj][m][n], 0, 0, 0); __builtin_amdgcn_s_setprio(0); } while (0)
; #define PG8_WAIT_V(n) asm volatile("s_waitcnt vmcnt(" #n ")" ::: "memory")
; #define PG8_WAIT_L(n) asm volatile("s_waitcnt lgkmcnt(" #n ")" ::: "memory")
; #define PG8_BAR __builtin_amdgcn_s_barrier()
; #define PG8_SCHED __builtin_amdgcn_sched_barrier(0)
; template <class Epi, bool ALIGN_EPI, bool ASLOT = false>
; __device__ __forceinline__ void gemm_phase(LAS unsigned char* lds, const Gemm g, const Sched& S, const Epi& E) {
;     ...
;             const bool last = (t == nt - 2);
;             const char* a1 = cA + (size_t)(t + 1) * kstep;
;             const char* a2 = last ? nA : cA + (size_t)(t + 2) * kstep; const char* b2 = last ? nB : cB + (size_t)(t + 2) * kstep;
;             const char* a3 = a2 + kstep; const char* b3 = b2 + kstep;
;             PG8_LDB(B0, 0, 0); PG8_LDB(B1, 0, 1); PG8_SCHED; PG8_LDA(At, 0, 0); PG8_STAGE(PG8_SA(1, 1), a1 + hstep, voffA);
;             PG8_WAIT_V(8); PG8_WAIT_L(0); PG8_BAR; PG8_MMA(0, 0, At, B0); PG8_MMA(0, 1, At, B1); PG8_BAR; PG8_SCHED;
;             PG8_LDA(At, 0, 1); PG8_STAGE(PG8_SB(0, 0), b2, voffB); PG8_STAGE(PG8_SB(0, 1), b2 + hstep, voffB); PG8_STAGE(PG8_SA(0, 0), a2, voffA);
;             PG8_WAIT_V(8); PG8_WAIT_L(0); PG8_BAR; PG8_MMA(1, 0, At, B0); PG8_MMA(1, 1, At, B1); PG8_BAR; PG8_SCHED;
.LBB0_884:
	v_add_u32_e32 v156, s28, v142
	v_add_u32_e32 v172, s33, v142
	s_add_u32 s8, s30, s6
	ds_read_b128 v[144:147], v156
	ds_read_b128 v[148:151], v156 offset:1024
	ds_read_b128 v[152:155], v156 offset:2048
	ds_read_b128 v[156:159], v156 offset:3072
	ds_read_b128 v[160:163], v172
	ds_read_b128 v[164:167], v172 offset:1024
	ds_read_b128 v[168:171], v172 offset:2048
	ds_read_b128 v[172:175], v172 offset:3072
	s_addc_u32 s9, s38, s7
	s_add_u32 s8, s8, 0x8800100
	s_addc_u32 s9, s9, 0
	s_add_u32 s22, s21, s6
	s_addc_u32 s23, s24, s7
	s_cmpk_eq_i32 s6, 0x1500
	s_cselect_b32 s11, s37, s9
	s_cselect_b32 s10, s36, s8
	s_cselect_b32 s9, s1, s23
	s_cselect_b32 s8, s0, s22
	v_lshl_add_u64 v[208:209], v[136:137], 0, s[6:7]
	s_add_i32 m0, s12, 0xc000
	ds_read_b128 v[176:179], v143
	ds_read_b128 v[180:183], v143 offset:1024
	ds_read_b128 v[184:187], v143 offset:2048
	ds_read_b128 v[188:191], v143 offset:3072
	ds_read_b128 v[192:195], v143 offset:4096
	ds_read_b128 v[196:199], v143 offset:5120
	ds_read_b128 v[200:203], v143 offset:6144
	ds_read_b128 v[204:207], v143 offset:7168
	global_load_lds_dwordx4 v[208:209], off
	v_lshl_add_u64 v[208:209], v[138:139], 0, s[6:7]
	s_add_i32 m0, s12, 0xe000
	s_nop 0
	global_load_lds_dwordx4 v[208:209], off
	s_waitcnt vmcnt(8)
	s_waitcnt lgkmcnt(0)
	s_barrier
	s_setprio 1
	s_waitcnt lgkmcnt(0)
	v_mfma_f32_16x16x32_bf16 v[126:129], v[144:147], v[176:179], v[126:129]
	v_mfma_f32_16x16x32_bf16 v[122:125], v[152:155], v[176:179], v[122:125]
	v_mfma_f32_16x16x32_bf16 v[118:121], v[144:147], v[184:187], v[118:121]
	v_mfma_f32_16x16x32_bf16 v[114:117], v[152:155], v[184:187], v[114:117]
	v_mfma_f32_16x16x32_bf16 v[102:105], v[144:147], v[192:195], v[102:105]
	v_mfma_f32_16x16x32_bf16 v[98:101], v[152:155], v[192:195], v[98:101]
	v_mfma_f32_16x16x32_bf16 v[86:89], v[144:147], v[200:203], v[86:89]
	v_mfma_f32_16x16x32_bf16 v[82:85], v[152:155], v[200:203], v[82:85]
	v_mfma_f32_16x16x32_bf16 v[126:129], v[148:151], v[180:183], v[126:129]
	v_mfma_f32_16x16x32_bf16 v[122:125], v[156:159], v[180:183], v[122:125]
	v_mfma_f32_16x16x32_bf16 v[118:121], v[148:151], v[188:191], v[118:121]
	v_mfma_f32_16x16x32_bf16 v[114:117], v[156:159], v[188:191], v[114:117]
	v_mfma_f32_16x16x32_bf16 v[102:105], v[148:151], v[196:199], v[102:105]
	v_mfma_f32_16x16x32_bf16 v[98:101], v[156:159], v[196:199], v[98:101]
	v_mfma_f32_16x16x32_bf16 v[86:89], v[148:151], v[204:207], v[86:89]
	v_mfma_f32_16x16x32_bf16 v[82:85], v[156:159], v[204:207], v[82:85]
	v_mfma_f32_16x16x32_bf16 v[110:113], v[160:163], v[176:179], v[110:113]
	v_mfma_f32_16x16x32_bf16 v[106:109], v[168:171], v[176:179], v[106:109]
	v_mfma_f32_16x16x32_bf16 v[94:97], v[160:163], v[184:187], v[94:97]
	v_mfma_f32_16x16x32_bf16 v[90:93], v[168:171], v[184:187], v[90:93]
	v_mfma_f32_16x16x32_bf16 v[78:81], v[160:163], v[192:195], v[78:81]
	v_mfma_f32_16x16x32_bf16 v[74:77], v[168:171], v[192:195], v[74:77]
	v_mfma_f32_16x16x32_bf16 v[70:73], v[160:163], v[200:203], v[70:73]
	v_mfma_f32_16x16x32_bf16 v[66:69], v[168:171], v[200:203], v[66:69]
	v_mfma_f32_16x16x32_bf16 v[110:113], v[164:167], v[180:183], v[110:113]
	v_mfma_f32_16x16x32_bf16 v[106:109], v[172:175], v[180:183], v[106:109]
	v_mfma_f32_16x16x32_bf16 v[94:97], v[164:167], v[188:191], v[94:97]
	v_mfma_f32_16x16x32_bf16 v[90:93], v[172:175], v[188:191], v[90:93]
	v_mfma_f32_16x16x32_bf16 v[78:81], v[164:167], v[196:199], v[78:81]
	v_mfma_f32_16x16x32_bf16 v[74:77], v[172:175], v[196:199], v[74:77]
	v_mfma_f32_16x16x32_bf16 v[70:73], v[164:167], v[204:207], v[70:73]
	v_mfma_f32_16x16x32_bf16 v[66:69], v[172:175], v[204:207], v[66:69]
	s_setprio 0
	s_barrier
	s_add_i32 s22, s28, s3
	v_lshl_add_u64 v[208:209], s[8:9], 0, v[0:1]
	s_mov_b32 m0, s22
	ds_read_b128 v[176:179], v143 offset:16384
	ds_read_b128 v[180:183], v143 offset:17408
	ds_read_b128 v[184:187], v143 offset:18432
	ds_read_b128 v[188:191], v143 offset:19456
	ds_read_b128 v[192:195], v143 offset:20480
	ds_read_b128 v[196:199], v143 offset:21504
	ds_read_b128 v[200:203], v143 offset:22528
	ds_read_b128 v[204:207], v143 offset:23552
	global_load_lds_dwordx4 v[208:209], off
	s_add_i32 m0, s22, 0x2000
	s_add_u32 s22, s8, 0xb0000
	v_lshl_add_u64 v[210:211], s[8:9], 0, v[134:135]
	s_addc_u32 s23, s9, 0
	s_add_i32 s27, s33, s3
	global_load_lds_dwordx4 v[210:211], off
	v_lshl_add_u64 v[212:213], s[22:23], 0, v[0:1]
	s_mov_b32 m0, s27
	v_lshl_add_u64 v[214:215], s[10:11], 0, v[132:133]
	global_load_lds_dwordx4 v[212:213], off
	v_lshl_add_u64 v[212:213], s[22:23], 0, v[134:135]
	s_add_i32 m0, s27, 0x2000
	s_nop 0
	global_load_lds_dwordx4 v[212:213], off
	v_lshl_add_u64 v[212:213], s[10:11], 0, v[130:131]
	s_mov_b32 m0, s12
	s_nop 0
	global_load_lds_dwordx4 v[212:213], off
	s_mov_b32 m0, s13
	s_nop 0
	global_load_lds_dwordx4 v[214:215], off
	s_waitcnt vmcnt(8)
	s_waitcnt lgkmcnt(0)
	s_barrier
; #define PG8_STAGE(bufoff, gbase, voff) do { _Pragma("unroll") for (int _i = 0; _i < 2; ++_i) \
;         __builtin_amdgcn_global_load_lds((const unsigned*)((const char*)(gbase) + (voff)[_i]), (LAS unsigned*)(lds + (bufoff) + ldsw + _i * 8192), 16, 0, 0); } while (0)
; #define PG8_LDA(dst, b, h) do { _Pragma("unroll") for (int m = 0; m < 4; ++m) _Pragma("unroll") for (int k = 0; k < 2; ++k) dst[m][k] = *(const LAS bf16x8*)(lds + PG8_SA(b, h) + aoff + m * 2048 + k * 1024); } while (0)
; #define PG8_LDB(dst, b, h) do { _Pragma("unroll") for (int n = 0; n < 2; ++n) _Pragma("unroll") for (int k = 0; k < 2; ++k) dst[n][k] = *(const LAS bf16x8*)(lds + PG8_SB(b, h) + boff + n * 2048 + k * 1024); } while (0)
; #define PG8_MMA(ai, bj, At, Bt) do { __builtin_amdgcn_s_setprio(1); _Pragma("unroll") for (int m = 0; m < 4; ++m) _Pragma("unroll") for (int n = 0; n < 2; ++n) _Pragma("unroll") for (int k = 0; k < 2; ++k) \
;         acc[ai][bj][m][n] = __builtin_amdgcn_mfma_f32_16x16x32_bf16(Bt[n][k], At[m][k], acc[ai][bj][m][n], 0, 0, 0); __builtin_amdgcn_s_setprio(0); } while (0)
; #define PG8_WAIT_V(n) asm volatile("s_waitcnt vmcnt(" #n ")" ::: "memory")
; #define PG8_WAIT_L(n) asm volatile("s_waitcnt lgkmcnt(" #n ")" ::: "memory")
; #define PG8_BAR __builtin_amdgcn_s_barrier()
; #define PG8_SCHED __builtin_amdgcn_sched_barrier(0)
; template <class Epi, bool ALIGN_EPI, bool ASLOT = false>
; __device__ __forceinline__ void gemm_phase(LAS unsigned char* lds, const Gemm g, const Sched& S, const Epi& E) {
;     ...
;             PG8_WAIT_V(8); PG8_WAIT_L(0); PG8_BAR; PG8_MMA(1, 0, At, B0); PG8_MMA(1, 1, At, B1); PG8_BAR; PG8_SCHED;
;             PG8_LDB(B0, 1, 0); PG8_LDB(B1, 1, 1); PG8_SCHED; PG8_LDA(At, 1, 0); PG8_STAGE(PG8_SA(0, 1), a2 + hstep, voffA);
;             PG8_WAIT_V(8); PG8_WAIT_L(0); PG8_BAR; PG8_MMA(0, 0, At, B0); PG8_MMA(0, 1, At, B1); PG8_BAR; PG8_SCHED;
	s_setprio 1
	s_waitcnt lgkmcnt(0)
	v_mfma_f32_16x16x32_bf16 v[62:65], v[144:147], v[176:179], v[62:65]
	v_mfma_f32_16x16x32_bf16 v[58:61], v[152:155], v[176:179], v[58:61]
	v_mfma_f32_16x16x32_bf16 v[54:57], v[144:147], v[184:187], v[54:57]
	v_mfma_f32_16x16x32_bf16 v[50:53], v[152:155], v[184:187], v[50:53]
	v_mfma_f32_16x16x32_bf16 v[38:41], v[144:147], v[192:195], v[38:41]
	v_mfma_f32_16x16x32_bf16 v[34:37], v[152:155], v[192:195], v[34:37]
	v_mfma_f32_16x16x32_bf16 v[22:25], v[144:147], v[200:203], v[22:25]
	v_mfma_f32_16x16x32_bf16 v[18:21], v[152:155], v[200:203], v[18:21]
	v_mfma_f32_16x16x32_bf16 v[62:65], v[148:151], v[180:183], v[62:65]
	v_mfma_f32_16x16x32_bf16 v[58:61], v[156:159], v[180:183], v[58:61]
	v_mfma_f32_16x16x32_bf16 v[54:57], v[148:151], v[188:191], v[54:57]
	v_mfma_f32_16x16x32_bf16 v[50:53], v[156:159], v[188:191], v[50:53]
	v_mfma_f32_16x16x32_bf16 v[38:41], v[148:151], v[196:199], v[38:41]
	v_mfma_f32_16x16x32_bf16 v[34:37], v[156:159], v[196:199], v[34:37]
	v_mfma_f32_16x16x32_bf16 v[22:25], v[148:151], v[204:207], v[22:25]
	v_mfma_f32_16x16x32_bf16 v[18:21], v[156:159], v[204:207], v[18:21]
	v_mfma_f32_16x16x32_bf16 v[46:49], v[160:163], v[176:179], v[46:49]
	v_mfma_f32_16x16x32_bf16 v[42:45], v[168:171], v[176:179], v[42:45]
	v_mfma_f32_16x16x32_bf16 v[30:33], v[160:163], v[184:187], v[30:33]
	v_mfma_f32_16x16x32_bf16 v[26:29], v[168:171], v[184:187], v[26:29]
	v_mfma_f32_16x16x32_bf16 v[14:17], v[160:163], v[192:195], v[14:17]
	v_mfma_f32_16x16x32_bf16 v[10:13], v[168:171], v[192:195], v[10:13]
	v_mfma_f32_16x16x32_bf16 v[6:9], v[160:163], v[200:203], v[6:9]
	v_mfma_f32_16x16x32_bf16 v[2:5], v[168:171], v[200:203], v[2:5]
	v_mfma_f32_16x16x32_bf16 v[46:49], v[164:167], v[180:183], v[46:49]
	v_mfma_f32_16x16x32_bf16 v[42:45], v[172:175], v[180:183], v[42:45]
	v_mfma_f32_16x16x32_bf16 v[30:33], v[164:167], v[188:191], v[30:33]
	v_mfma_f32_16x16x32_bf16 v[26:29], v[172:175], v[188:191], v[26:29]
	v_mfma_f32_16x16x32_bf16 v[14:17], v[164:167], v[196:199], v[14:17]
	v_mfma_f32_16x16x32_bf16 v[10:13], v[172:175], v[196:199], v[10:13]
	v_mfma_f32_16x16x32_bf16 v[6:9], v[164:167], v[204:207], v[6:9]
	v_mfma_f32_16x16x32_bf16 v[2:5], v[172:175], v[204:207], v[2:5]
	s_setprio 0
	s_barrier
	v_add_u32_e32 v156, s29, v142
	v_add_u32_e32 v172, s26, v142
	ds_read_b128 v[144:147], v156
	ds_read_b128 v[148:151], v156 offset:1024
	ds_read_b128 v[152:155], v156 offset:2048
	ds_read_b128 v[156:159], v156 offset:3072
	ds_read_b128 v[160:163], v172
	ds_read_b128 v[164:167], v172 offset:1024
	ds_read_b128 v[168:171], v172 offset:2048
	ds_read_b128 v[172:175], v172 offset:3072
	s_add_u32 s10, s10, 0xb0000
	s_addc_u32 s11, s11, 0
	s_mov_b32 m0, s14
	v_lshl_add_u64 v[220:221], s[10:11], 0, v[130:131]
	ds_read_b128 v[176:179], v143 offset:32768
	ds_read_b128 v[180:183], v143 offset:33792
	ds_read_b128 v[184:187], v143 offset:34816
	ds_read_b128 v[188:191], v143 offset:35840
	ds_read_b128 v[192:195], v143 offset:36864
	ds_read_b128 v[196:199], v143 offset:37888
	ds_read_b128 v[200:203], v143 offset:38912
	ds_read_b128 v[204:207], v143 offset:39936
	global_load_lds_dwordx4 v[220:221], off
	v_lshl_add_u64 v[220:221], s[10:11], 0, v[132:133]
	s_mov_b32 m0, s15
	s_nop 0
	global_load_lds_dwordx4 v[220:221], off
	s_waitcnt vmcnt(8)
	s_waitcnt lgkmcnt(0)
	s_barrier
	s_setprio 1
	s_waitcnt lgkmcnt(0)
	v_mfma_f32_16x16x32_bf16 v[126:129], v[144:147], v[176:179], v[126:129]
	v_mfma_f32_16x16x32_bf16 v[122:125], v[152:155], v[176:179], v[122:125]
	v_mfma_f32_16x16x32_bf16 v[118:121], v[144:147], v[184:187], v[118:121]
	v_mfma_f32_16x16x32_bf16 v[114:117], v[152:155], v[184:187], v[114:117]
	v_mfma_f32_16x16x32_bf16 v[102:105], v[144:147], v[192:195], v[102:105]
	v_mfma_f32_16x16x32_bf16 v[98:101], v[152:155], v[192:195], v[98:101]
	v_mfma_f32_16x16x32_bf16 v[86:89], v[144:147], v[200:203], v[86:89]
	v_mfma_f32_16x16x32_bf16 v[82:85], v[152:155], v[200:203], v[82:85]
	v_mfma_f32_16x16x32_bf16 v[126:129], v[148:151], v[180:183], v[126:129]
	v_mfma_f32_16x16x32_bf16 v[122:125], v[156:159], v[180:183], v[122:125]
	v_mfma_f32_16x16x32_bf16 v[118:121], v[148:151], v[188:191], v[118:121]
	v_mfma_f32_16x16x32_bf16 v[114:117], v[156:159], v[188:191], v[114:117]
	v_mfma_f32_16x16x32_bf16 v[102:105], v[148:151], v[196:199], v[102:105]
	v_mfma_f32_16x16x32_bf16 v[98:101], v[156:159], v[196:199], v[98:101]
	v_mfma_f32_16x16x32_bf16 v[86:89], v[148:151], v[204:207], v[86:89]
	v_mfma_f32_16x16x32_bf16 v[82:85], v[156:159], v[204:207], v[82:85]
	v_mfma_f32_16x16x32_bf16 v[110:113], v[160:163], v[176:179], v[110:113]
	v_mfma_f32_16x16x32_bf16 v[106:109], v[168:171], v[176:179], v[106:109]
	v_mfma_f32_16x16x32_bf16 v[94:97], v[160:163], v[184:187], v[94:97]
	v_mfma_f32_16x16x32_bf16 v[90:93], v[168:171], v[184:187], v[90:93]
	v_mfma_f32_16x16x32_bf16 v[78:81], v[160:163], v[192:195], v[78:81]
	v_mfma_f32_16x16x32_bf16 v[74:77], v[168:171], v[192:195], v[74:77]
	v_mfma_f32_16x16x32_bf16 v[70:73], v[160:163], v[200:203], v[70:73]
	v_mfma_f32_16x16x32_bf16 v[66:69], v[168:171], v[200:203], v[66:69]
	v_mfma_f32_16x16x32_bf16 v[110:113], v[164:167], v[180:183], v[110:113]
	v_mfma_f32_16x16x32_bf16 v[106:109], v[172:175], v[180:183], v[106:109]
	v_mfma_f32_16x16x32_bf16 v[94:97], v[164:167], v[188:191], v[94:97]
	v_mfma_f32_16x16x32_bf16 v[90:93], v[172:175], v[188:191], v[90:93]
	v_mfma_f32_16x16x32_bf16 v[78:81], v[164:167], v[196:199], v[78:81]
	v_mfma_f32_16x16x32_bf16 v[74:77], v[172:175], v[196:199], v[74:77]
	v_mfma_f32_16x16x32_bf16 v[70:73], v[164:167], v[204:207], v[70:73]
	v_mfma_f32_16x16x32_bf16 v[66:69], v[172:175], v[204:207], v[66:69]
	s_setprio 0
	s_barrier
; #define PG8_STAGE(bufoff, gbase, voff) do { _Pragma("unroll") for (int _i = 0; _i < 2; ++_i) \
;         __builtin_amdgcn_global_load_lds((const unsigned*)((const char*)(gbase) + (voff)[_i]), (LAS unsigned*)(lds + (bufoff) + ldsw + _i * 8192), 16, 0, 0); } while (0)
; #define PG8_LDA(dst, b, h) do { _Pragma("unroll") for (int m = 0; m < 4; ++m) _Pragma("unroll") for (int k = 0; k < 2; ++k) dst[m][k] = *(const LAS bf16x8*)(lds + PG8_SA(b, h) + aoff + m * 2048 + k * 1024); } while (0)
; #define PG8_MMA(ai, bj, At, Bt) do { __builtin_amdgcn_s_setprio(1); _Pragma("unroll") for (int m = 0; m < 4; ++m) _Pragma("unroll") for (int n = 0; n < 2; ++n) _Pragma("unroll") for (int k = 0; k < 2; ++k) \
;         acc[ai][bj][m][n] = __builtin_amdgcn_mfma_f32_16x16x32_bf16(Bt[n][k], At[m][k], acc[ai][bj][m][n], 0, 0, 0); __builtin_amdgcn_s_setprio(0); } while (0)
; #define PG8_WAIT_V(n) asm volatile("s_waitcnt vmcnt(" #n ")" ::: "memory")
; #define PG8_WAIT_L(n) asm volatile("s_waitcnt lgkmcnt(" #n ")" ::: "memory")
; #define PG8_BAR __builtin_amdgcn_s_barrier()
; #define PG8_SCHED __builtin_amdgcn_sched_barrier(0)
; template <class Epi, bool ALIGN_EPI, bool ASLOT = false>
; __device__ __forceinline__ void gemm_phase(LAS unsigned char* lds, const Gemm g, const Sched& S, const Epi& E) {
;     ...
;             PG8_LDA(At, 1, 1); PG8_STAGE(PG8_SB(1, 0), b3, voffB); PG8_STAGE(PG8_SB(1, 1), b3 + hstep, voffB); PG8_STAGE(PG8_SA(1, 0), a3, voffA);
;             PG8_WAIT_V(8); PG8_WAIT_L(0); PG8_BAR; PG8_MMA(1, 0, At, B0); PG8_MMA(1, 1, At, B1); PG8_BAR; PG8_SCHED;
;         }
;         if constexpr (ALIGN_EPI) { if (wr == 0) PG8_BAR; }
	s_add_i32 s10, s29, s3
	v_lshl_add_u64 v[208:209], v[208:209], 0, s[16:17]
	s_mov_b32 m0, s10
	ds_read_b128 v[176:179], v143 offset:49152
	ds_read_b128 v[180:183], v143 offset:50176
	ds_read_b128 v[184:187], v143 offset:51200
	ds_read_b128 v[188:191], v143 offset:52224
	ds_read_b128 v[192:195], v143 offset:53248
	ds_read_b128 v[196:199], v143 offset:54272
	ds_read_b128 v[200:203], v143 offset:55296
	ds_read_b128 v[204:207], v143 offset:56320
	global_load_lds_dwordx4 v[208:209], off
	s_add_i32 m0, s10, 0x2000
	s_add_u32 s8, s8, 0xb0080
	v_lshl_add_u64 v[208:209], v[210:211], 0, s[16:17]
	s_addc_u32 s9, s9, 0
	s_add_i32 s10, s26, s3
	global_load_lds_dwordx4 v[208:209], off
	v_lshl_add_u64 v[208:209], s[8:9], 0, v[0:1]
	s_mov_b32 m0, s10
	s_nop 0
	global_load_lds_dwordx4 v[208:209], off
	v_lshl_add_u64 v[208:209], s[8:9], 0, v[134:135]
	s_add_i32 m0, s10, 0x2000
	s_nop 0
	global_load_lds_dwordx4 v[208:209], off
	v_lshl_add_u64 v[208:209], v[212:213], 0, s[16:17]
	s_mov_b32 m0, s19
	s_nop 0
	global_load_lds_dwordx4 v[208:209], off
	v_lshl_add_u64 v[208:209], v[214:215], 0, s[16:17]
	s_mov_b32 m0, s20
	s_nop 0
	global_load_lds_dwordx4 v[208:209], off
	s_waitcnt vmcnt(8)
	s_waitcnt lgkmcnt(0)
	s_barrier
	s_setprio 1
	s_waitcnt lgkmcnt(0)
	v_mfma_f32_16x16x32_bf16 v[62:65], v[144:147], v[176:179], v[62:65]
	v_mfma_f32_16x16x32_bf16 v[58:61], v[152:155], v[176:179], v[58:61]
	v_mfma_f32_16x16x32_bf16 v[54:57], v[144:147], v[184:187], v[54:57]
	v_mfma_f32_16x16x32_bf16 v[50:53], v[152:155], v[184:187], v[50:53]
	v_mfma_f32_16x16x32_bf16 v[38:41], v[144:147], v[192:195], v[38:41]
	v_mfma_f32_16x16x32_bf16 v[34:37], v[152:155], v[192:195], v[34:37]
	v_mfma_f32_16x16x32_bf16 v[22:25], v[144:147], v[200:203], v[22:25]
	v_mfma_f32_16x16x32_bf16 v[18:21], v[152:155], v[200:203], v[18:21]
	v_mfma_f32_16x16x32_bf16 v[62:65], v[148:151], v[180:183], v[62:65]
	v_mfma_f32_16x16x32_bf16 v[58:61], v[156:159], v[180:183], v[58:61]
	v_mfma_f32_16x16x32_bf16 v[54:57], v[148:151], v[188:191], v[54:57]
	v_mfma_f32_16x16x32_bf16 v[50:53], v[156:159], v[188:191], v[50:53]
	v_mfma_f32_16x16x32_bf16 v[38:41], v[148:151], v[196:199], v[38:41]
	v_mfma_f32_16x16x32_bf16 v[34:37], v[156:159], v[196:199], v[34:37]
	v_mfma_f32_16x16x32_bf16 v[22:25], v[148:151], v[204:207], v[22:25]
	v_mfma_f32_16x16x32_bf16 v[18:21], v[156:159], v[204:207], v[18:21]
	v_mfma_f32_16x16x32_bf16 v[46:49], v[160:163], v[176:179], v[46:49]
	v_mfma_f32_16x16x32_bf16 v[42:45], v[168:171], v[176:179], v[42:45]
	v_mfma_f32_16x16x32_bf16 v[30:33], v[160:163], v[184:187], v[30:33]
	v_mfma_f32_16x16x32_bf16 v[26:29], v[168:171], v[184:187], v[26:29]
	v_mfma_f32_16x16x32_bf16 v[14:17], v[160:163], v[192:195], v[14:17]
	v_mfma_f32_16x16x32_bf16 v[10:13], v[168:171], v[192:195], v[10:13]
	v_mfma_f32_16x16x32_bf16 v[6:9], v[160:163], v[200:203], v[6:9]
	v_mfma_f32_16x16x32_bf16 v[2:5], v[168:171], v[200:203], v[2:5]
	v_mfma_f32_16x16x32_bf16 v[46:49], v[164:167], v[180:183], v[46:49]
	v_mfma_f32_16x16x32_bf16 v[42:45], v[172:175], v[180:183], v[42:45]
	v_mfma_f32_16x16x32_bf16 v[30:33], v[164:167], v[188:191], v[30:33]
	v_mfma_f32_16x16x32_bf16 v[26:29], v[172:175], v[188:191], v[26:29]
	v_mfma_f32_16x16x32_bf16 v[14:17], v[164:167], v[196:199], v[14:17]
	v_mfma_f32_16x16x32_bf16 v[10:13], v[172:175], v[196:199], v[10:13]
	v_mfma_f32_16x16x32_bf16 v[6:9], v[164:167], v[204:207], v[6:9]
	v_mfma_f32_16x16x32_bf16 v[2:5], v[172:175], v[204:207], v[2:5]
	s_setprio 0
	s_barrier
	s_add_i32 s25, s25, 2
	s_add_u32 s6, s6, 0x100
	s_addc_u32 s7, s7, 0
	s_cmp_gt_u32 s25, 41
	s_cbranch_scc0 .LBB0_884
	s_cmpk_lt_u32 s2, 0x100
	s_cbranch_scc0 .LBB0_887
	s_barrier
